# nt policy also on P0 weight/adaLN f32 loads and P8 gate-epilogue loads
# baseline (speedup 1.0000x reference)
.LBB0_51:
	s_cmpk_gt_i32 s13, 0x8f
	s_mov_b64 s[0:1], -1
	s_cbranch_scc0 .LBB0_85
	v_mov_b32_e32 v3, v162
	s_lshl_b32 s0, s13, 1
	s_addk_i32 s0, 0xfee0
	v_ashrrev_i32_e32 v8, 8, v3
	v_add_u32_e32 v1, s0, v8
	v_ashrrev_i32_e32 v2, 31, v1
	v_lshrrev_b32_e32 v2, 28, v2
	v_add_u32_e32 v2, v1, v2
	v_ashrrev_i32_e32 v5, 4, v2
	v_and_b32_e32 v2, 0x3fffff0, v2
	v_and_b32_e32 v9, 63, v3
	v_sub_u32_e32 v2, v1, v2
	v_lshlrev_b32_e32 v1, 6, v5
	v_readlane_b32 s68, v247, 17
	v_readlane_b32 s16, v247, 1
	v_or_b32_e32 v4, v1, v9
	v_lshlrev_b32_e32 v6, 5, v5
	s_movk_i32 s4, 0x7f
	v_and_b32_e32 v5, 2, v5
	v_readlane_b32 s69, v247, 18
	v_readlane_b32 s31, v247, 16
	v_cmp_gt_i32_e64 s[0:1], s9, v4
	v_bfi_b32 v4, s4, v4, v6
	v_mov_b32_e32 v6, s69
	v_readlane_b32 s30, v247, 15
	v_mov_b32_e32 v7, s31
	v_cmp_eq_u32_e32 vcc, 0, v5
	v_mov_b32_e32 v5, s68
	v_lshlrev_b32_e32 v2, 6, v2
	v_cndmask_b32_e32 v7, v6, v7, vcc
	v_mov_b32_e32 v6, s30
	v_cndmask_b32_e32 v6, v5, v6, vcc
	v_lshrrev_b32_e32 v5, 2, v3
	v_and_b32_e32 v10, 48, v5
	v_or_b32_e32 v11, v2, v10
	v_ashrrev_i32_e32 v5, 31, v4
	s_movk_i32 s4, 0xb00
	v_lshl_add_u64 v[4:5], v[4:5], 2, v[6:7]
	v_mul_lo_u32 v6, v11, s4
	v_mov_b32_e32 v12, 0
	v_ashrrev_i32_e32 v7, 31, v6
	v_mov_b32_e32 v11, 0
	v_readlane_b32 s70, v247, 19
	v_readlane_b32 s71, v247, 20
	v_readlane_b32 s72, v247, 21
	v_readlane_b32 s73, v247, 22
	v_readlane_b32 s74, v247, 23
	v_readlane_b32 s75, v247, 24
	v_readlane_b32 s76, v247, 25
	v_readlane_b32 s77, v247, 26
	v_readlane_b32 s78, v247, 27
	v_readlane_b32 s79, v247, 28
	v_readlane_b32 s80, v247, 29
	v_readlane_b32 s81, v247, 30
	v_readlane_b32 s82, v247, 31
	v_readlane_b32 s83, v247, 32
	v_readlane_b32 s17, v247, 2
	v_readlane_b32 s18, v247, 3
	v_readlane_b32 s19, v247, 4
	v_readlane_b32 s20, v247, 5
	v_readlane_b32 s21, v247, 6
	v_readlane_b32 s22, v247, 7
	v_readlane_b32 s23, v247, 8
	v_readlane_b32 s24, v247, 9
	v_readlane_b32 s25, v247, 10
	v_readlane_b32 s26, v247, 11
	v_readlane_b32 s27, v247, 12
	v_readlane_b32 s28, v247, 13
	v_readlane_b32 s29, v247, 14
	s_and_saveexec_b64 s[4:5], s[0:1]
	s_cbranch_execz .LBB0_54
	v_lshl_add_u64 v[14:15], v[6:7], 2, v[4:5]
	global_load_dword v11, v[14:15], off nt
.LBB0_54:
	s_or_b64 exec, exec, s[4:5]
	s_and_saveexec_b64 s[4:5], s[0:1]
	s_cbranch_execz .LBB0_56
	v_lshl_add_u64 v[12:13], v[6:7], 2, v[4:5]
	v_add_co_u32_e32 v12, vcc, 0x2000, v12
	s_nop 1
	v_addc_co_u32_e32 v13, vcc, 0, v13, vcc
	global_load_dword v12, v[12:13], off offset:3072 nt
.LBB0_56:
	s_or_b64 exec, exec, s[4:5]
	v_mov_b32_e32 v13, 0
	v_mov_b32_e32 v14, 0
	s_and_saveexec_b64 s[4:5], s[0:1]
	s_cbranch_execz .LBB0_58
	v_lshl_add_u64 v[14:15], v[6:7], 2, v[4:5]
	v_add_co_u32_e32 v14, vcc, 0x5000, v14
	s_nop 1
	v_addc_co_u32_e32 v15, vcc, 0, v15, vcc
	global_load_dword v14, v[14:15], off offset:2048 nt
.LBB0_58:
	s_or_b64 exec, exec, s[4:5]
	s_and_saveexec_b64 s[4:5], s[0:1]
	s_cbranch_execz .LBB0_60
	v_lshl_add_u64 v[16:17], v[6:7], 2, v[4:5]
	v_add_co_u32_e32 v16, vcc, 0x8000, v16
	s_nop 1
	v_addc_co_u32_e32 v17, vcc, 0, v17, vcc
	global_load_dword v13, v[16:17], off offset:1024 nt
.LBB0_60:
	s_or_b64 exec, exec, s[4:5]
	v_mov_b32_e32 v15, 0
	v_mov_b32_e32 v16, 0
	s_and_saveexec_b64 s[4:5], s[0:1]
	s_cbranch_execz .LBB0_62
	v_lshl_add_u64 v[16:17], v[6:7], 2, v[4:5]
	v_add_co_u32_e32 v16, vcc, 0xb000, v16
	s_nop 1
	v_addc_co_u32_e32 v17, vcc, 0, v17, vcc
	global_load_dword v16, v[16:17], off nt
.LBB0_62:
	s_or_b64 exec, exec, s[4:5]
	s_and_saveexec_b64 s[4:5], s[0:1]
	s_cbranch_execz .LBB0_64
	v_lshl_add_u64 v[18:19], v[6:7], 2, v[4:5]
	v_add_co_u32_e32 v18, vcc, 0xd000, v18
	s_nop 1
	v_addc_co_u32_e32 v19, vcc, 0, v19, vcc
	global_load_dword v15, v[18:19], off offset:3072 nt
.LBB0_64:
	s_or_b64 exec, exec, s[4:5]
	v_mov_b32_e32 v17, 0
	v_mov_b32_e32 v18, 0
	s_and_saveexec_b64 s[4:5], s[0:1]
	s_cbranch_execz .LBB0_66
	v_lshl_add_u64 v[18:19], v[6:7], 2, v[4:5]
	v_add_co_u32_e32 v18, vcc, 0x10000, v18
	s_nop 1
	v_addc_co_u32_e32 v19, vcc, 0, v19, vcc
	global_load_dword v18, v[18:19], off offset:2048 nt
.LBB0_66:
	s_or_b64 exec, exec, s[4:5]
	s_and_saveexec_b64 s[4:5], s[0:1]
	s_cbranch_execz .LBB0_68
	v_lshl_add_u64 v[20:21], v[6:7], 2, v[4:5]
	v_add_co_u32_e32 v20, vcc, 0x13000, v20
	s_nop 1
	v_addc_co_u32_e32 v21, vcc, 0, v21, vcc
	global_load_dword v17, v[20:21], off offset:1024 nt
.LBB0_68:
	s_or_b64 exec, exec, s[4:5]
	v_mov_b32_e32 v19, 0
	v_mov_b32_e32 v20, 0
	s_and_saveexec_b64 s[4:5], s[0:1]
	s_cbranch_execz .LBB0_70
	v_lshl_add_u64 v[20:21], v[6:7], 2, v[4:5]
	v_add_co_u32_e32 v20, vcc, 0x16000, v20
	s_nop 1
	v_addc_co_u32_e32 v21, vcc, 0, v21, vcc
	global_load_dword v20, v[20:21], off nt
.LBB0_70:
	s_or_b64 exec, exec, s[4:5]
	s_and_saveexec_b64 s[4:5], s[0:1]
	s_cbranch_execz .LBB0_72
	v_lshl_add_u64 v[22:23], v[6:7], 2, v[4:5]
	v_add_co_u32_e32 v22, vcc, 0x18000, v22
	s_nop 1
	v_addc_co_u32_e32 v23, vcc, 0, v23, vcc
	global_load_dword v19, v[22:23], off offset:3072 nt
.LBB0_72:
	s_or_b64 exec, exec, s[4:5]
	v_mov_b32_e32 v21, 0
	v_mov_b32_e32 v22, 0
	s_and_saveexec_b64 s[4:5], s[0:1]
	s_cbranch_execz .LBB0_74
	v_lshl_add_u64 v[22:23], v[6:7], 2, v[4:5]
	v_add_co_u32_e32 v22, vcc, 0x1b000, v22
	s_nop 1
	v_addc_co_u32_e32 v23, vcc, 0, v23, vcc
	global_load_dword v22, v[22:23], off offset:2048 nt
.LBB0_74:
	s_or_b64 exec, exec, s[4:5]
	s_and_saveexec_b64 s[4:5], s[0:1]
	s_cbranch_execz .LBB0_76
	v_lshl_add_u64 v[24:25], v[6:7], 2, v[4:5]
	v_add_co_u32_e32 v24, vcc, 0x1e000, v24
	s_nop 1
	v_addc_co_u32_e32 v25, vcc, 0, v25, vcc
	global_load_dword v21, v[24:25], off offset:1024 nt
.LBB0_76:
	s_or_b64 exec, exec, s[4:5]
	v_mov_b32_e32 v23, 0
	v_mov_b32_e32 v24, 0
	s_and_saveexec_b64 s[4:5], s[0:1]
	s_cbranch_execz .LBB0_78
	v_lshl_add_u64 v[24:25], v[6:7], 2, v[4:5]
	v_add_co_u32_e32 v24, vcc, 0x21000, v24
	s_nop 1
	v_addc_co_u32_e32 v25, vcc, 0, v25, vcc
	global_load_dword v24, v[24:25], off nt
.LBB0_78:
	s_or_b64 exec, exec, s[4:5]
	s_and_saveexec_b64 s[4:5], s[0:1]
	s_cbranch_execz .LBB0_80
	v_lshl_add_u64 v[26:27], v[6:7], 2, v[4:5]
	v_add_co_u32_e32 v26, vcc, 0x23000, v26
	s_nop 1
	v_addc_co_u32_e32 v27, vcc, 0, v27, vcc
	global_load_dword v23, v[26:27], off offset:3072 nt
.LBB0_80:
	s_or_b64 exec, exec, s[4:5]
	v_mov_b32_e32 v25, 0
	v_mov_b32_e32 v26, 0
	s_and_saveexec_b64 s[4:5], s[0:1]
	s_cbranch_execz .LBB0_82
	v_lshl_add_u64 v[26:27], v[6:7], 2, v[4:5]
	v_add_co_u32_e32 v26, vcc, 0x26000, v26
	s_nop 1
	v_addc_co_u32_e32 v27, vcc, 0, v27, vcc
	global_load_dword v26, v[26:27], off offset:2048 nt
.LBB0_82:
	s_or_b64 exec, exec, s[4:5]
	s_and_saveexec_b64 s[4:5], s[0:1]
	s_cbranch_execz .LBB0_84
	v_lshl_add_u64 v[4:5], v[6:7], 2, v[4:5]
	v_add_co_u32_e32 v4, vcc, 0x29000, v4
	s_nop 1
	v_addc_co_u32_e32 v5, vcc, 0, v5, vcc
	global_load_dword v25, v[4:5], off offset:1024 nt

.LBB0_85:
	s_and_b64 vcc, exec, s[0:1]
	s_cbranch_vccz .LBB0_50
	v_mov_b32_e32 v78, v162
	v_readlane_b32 s16, v247, 1
	v_and_b32_e32 v4, 0x3ff, v78
	s_movk_i32 s0, 0x4000
	v_ashrrev_i32_e32 v79, 31, v78
	v_readlane_b32 s18, v247, 3
	v_readlane_b32 s19, v247, 4
	v_readlane_b32 s22, v247, 7
	v_readlane_b32 s23, v247, 8
	v_lshlrev_b32_e32 v76, 2, v4
	v_lshl_add_u64 v[2:3], v[78:79], 2, s[18:19]
	v_lshl_add_u64 v[4:5], s[22:23], 0, v[76:77]
	v_cmp_gt_i32_e32 vcc, s0, v78
	s_movk_i32 s4, 0x3e00
	s_mov_b64 s[0:1], 0x800
	v_cndmask_b32_e32 v7, v5, v3, vcc
	v_cndmask_b32_e32 v6, v4, v2, vcc
	global_load_dword v6, v[6:7], off nt
	v_add_u32_e32 v7, 0x200, v78
	v_and_b32_e32 v7, 0x3ff, v7
	v_lshlrev_b32_e32 v76, 2, v7
	v_lshl_add_u64 v[8:9], v[2:3], 0, s[0:1]
	v_lshl_add_u64 v[10:11], s[22:23], 0, v[76:77]
	v_cmp_gt_i32_e32 vcc, s4, v78
	s_movk_i32 s4, 0x3c00
	s_mov_b64 s[0:1], 0x1000
	v_cndmask_b32_e32 v9, v11, v9, vcc
	v_cndmask_b32_e32 v8, v10, v8, vcc
	global_load_dword v12, v[8:9], off nt
	v_lshl_add_u64 v[8:9], v[2:3], 0, s[0:1]
	v_cmp_gt_i32_e32 vcc, s4, v78
	v_add_u32_e32 v10, 0x600, v78
	v_and_b32_e32 v10, 0x3ff, v10
	v_cndmask_b32_e32 v9, v5, v9, vcc
	v_cndmask_b32_e32 v8, v4, v8, vcc
	global_load_dword v7, v[8:9], off nt
	s_movk_i32 s4, 0x3a00
	s_mov_b64 s[0:1], 0x1800
	v_lshlrev_b32_e32 v76, 2, v10
	v_lshl_add_u64 v[8:9], v[2:3], 0, s[0:1]
	v_lshl_add_u64 v[10:11], s[22:23], 0, v[76:77]
	v_cmp_gt_i32_e32 vcc, s4, v78
	s_movk_i32 s4, 0x3800
	s_mov_b64 s[0:1], 0x2000
	v_cndmask_b32_e32 v9, v11, v9, vcc
	v_cndmask_b32_e32 v8, v10, v8, vcc
	global_load_dword v14, v[8:9], off nt
	v_lshl_add_u64 v[8:9], v[2:3], 0, s[0:1]
	v_cmp_gt_i32_e32 vcc, s4, v78
	s_movk_i32 s4, 0x3600
	s_mov_b64 s[0:1], 0x2800
	v_cndmask_b32_e32 v9, v5, v9, vcc
	v_cndmask_b32_e32 v8, v4, v8, vcc
	global_load_dword v8, v[8:9], off nt
	v_add_u32_e32 v9, 0xa00, v78
	v_and_b32_e32 v9, 0x3ff, v9
	v_lshlrev_b32_e32 v76, 2, v9
	v_lshl_add_u64 v[10:11], v[2:3], 0, s[0:1]
	v_lshl_add_u64 v[16:17], s[22:23], 0, v[76:77]
	v_cmp_gt_i32_e32 vcc, s4, v78
	s_movk_i32 s4, 0x3400
	s_mov_b64 s[0:1], 0x3000
	v_cndmask_b32_e32 v11, v17, v11, vcc
	v_cndmask_b32_e32 v10, v16, v10, vcc
	v_add_u32_e32 v13, 0xe00, v78
	global_load_dword v16, v[10:11], off nt
	v_lshl_add_u64 v[10:11], v[2:3], 0, s[0:1]
	v_cmp_gt_i32_e32 vcc, s4, v78
	v_and_b32_e32 v13, 0x3ff, v13
	s_movk_i32 s4, 0x3200
	v_cndmask_b32_e32 v11, v5, v11, vcc
	v_cndmask_b32_e32 v10, v4, v10, vcc
	s_mov_b64 s[0:1], 0x3800
	v_lshlrev_b32_e32 v76, 2, v13
	global_load_dword v9, v[10:11], off nt
	v_lshl_add_u64 v[10:11], v[2:3], 0, s[0:1]
	v_lshl_add_u64 v[18:19], s[22:23], 0, v[76:77]
	v_cmp_gt_i32_e32 vcc, s4, v78
	s_movk_i32 s4, 0x3000
	s_mov_b64 s[0:1], 0x4000
	v_cndmask_b32_e32 v11, v19, v11, vcc
	v_cndmask_b32_e32 v10, v18, v10, vcc
	global_load_dword v18, v[10:11], off nt
	v_lshl_add_u64 v[10:11], v[2:3], 0, s[0:1]
	v_cmp_gt_i32_e32 vcc, s4, v78
	s_movk_i32 s4, 0x2e00
	s_mov_b64 s[0:1], 0x4800
	v_cndmask_b32_e32 v11, v5, v11, vcc
	v_cndmask_b32_e32 v10, v4, v10, vcc
	global_load_dword v10, v[10:11], off nt
	v_add_u32_e32 v11, 0x1200, v78
	v_and_b32_e32 v11, 0x3ff, v11
	v_lshlrev_b32_e32 v76, 2, v11
	v_lshl_add_u64 v[20:21], v[2:3], 0, s[0:1]
	v_lshl_add_u64 v[22:23], s[22:23], 0, v[76:77]
	v_cmp_gt_i32_e32 vcc, s4, v78
	s_movk_i32 s4, 0x2c00
	s_mov_b64 s[0:1], 0x5000
	v_add_u32_e32 v13, 0x1600, v78
	v_cndmask_b32_e32 v21, v23, v21, vcc
	v_cndmask_b32_e32 v20, v22, v20, vcc
	v_lshl_add_u64 v[22:23], v[2:3], 0, s[0:1]
	v_cmp_gt_i32_e32 vcc, s4, v78
	v_and_b32_e32 v13, 0x3ff, v13
	s_movk_i32 s4, 0x2a00
	v_cndmask_b32_e32 v23, v5, v23, vcc
	v_cndmask_b32_e32 v22, v4, v22, vcc
	s_mov_b64 s[0:1], 0x5800
	v_lshlrev_b32_e32 v76, 2, v13
	global_load_dword v11, v[22:23], off nt
	v_lshl_add_u64 v[22:23], v[2:3], 0, s[0:1]
	v_lshl_add_u64 v[24:25], s[22:23], 0, v[76:77]
	v_cmp_gt_i32_e32 vcc, s4, v78
	s_movk_i32 s4, 0x2800
	s_mov_b64 s[0:1], 0x6000
	v_add_u32_e32 v15, 0x1a00, v78
	v_cndmask_b32_e32 v23, v25, v23, vcc
	v_cndmask_b32_e32 v22, v24, v22, vcc
	v_lshl_add_u64 v[24:25], v[2:3], 0, s[0:1]
	v_cmp_gt_i32_e32 vcc, s4, v78
	v_and_b32_e32 v15, 0x3ff, v15
	s_movk_i32 s4, 0x2600
	v_cndmask_b32_e32 v25, v5, v25, vcc
	v_cndmask_b32_e32 v24, v4, v24, vcc
	s_mov_b64 s[0:1], 0x6800
	v_lshlrev_b32_e32 v76, 2, v15
	global_load_dword v13, v[24:25], off nt
	v_lshl_add_u64 v[24:25], v[2:3], 0, s[0:1]
	v_lshl_add_u64 v[26:27], s[22:23], 0, v[76:77]
	v_cmp_gt_i32_e32 vcc, s4, v78
	s_mov_b64 s[0:1], 0x7000
	v_add_u32_e32 v17, 0x1e00, v78
	v_cndmask_b32_e32 v25, v27, v25, vcc
	v_cndmask_b32_e32 v24, v26, v24, vcc
	v_lshl_add_u64 v[26:27], v[2:3], 0, s[0:1]
	v_cmp_gt_i32_e32 vcc, s11, v78
	v_and_b32_e32 v17, 0x3ff, v17
	s_movk_i32 s4, 0x2200
	v_cndmask_b32_e32 v27, v5, v27, vcc
	v_cndmask_b32_e32 v26, v4, v26, vcc
	s_mov_b64 s[0:1], 0x7800
	v_lshlrev_b32_e32 v76, 2, v17
	global_load_dword v15, v[26:27], off nt
	v_lshl_add_u64 v[26:27], v[2:3], 0, s[0:1]
	v_lshl_add_u64 v[28:29], s[22:23], 0, v[76:77]
	v_cmp_gt_i32_e32 vcc, s4, v78
	s_movk_i32 s4, 0x2000
	s_mov_b64 s[0:1], 0x8000
	v_add_u32_e32 v19, 0x2200, v78
	v_cndmask_b32_e32 v27, v29, v27, vcc
	v_cndmask_b32_e32 v26, v28, v26, vcc
	v_lshl_add_u64 v[28:29], v[2:3], 0, s[0:1]
	v_cmp_gt_i32_e32 vcc, s4, v78
	v_and_b32_e32 v19, 0x3ff, v19
	s_movk_i32 s4, 0x1e00
	v_cndmask_b32_e32 v29, v5, v29, vcc
	v_cndmask_b32_e32 v28, v4, v28, vcc
	s_mov_b64 s[0:1], 0x8800
	v_lshlrev_b32_e32 v76, 2, v19
	global_load_dword v20, v[20:21], off nt
	v_lshl_add_u64 v[30:31], s[22:23], 0, v[76:77]
	global_load_dword v17, v[28:29], off nt
	v_lshl_add_u64 v[28:29], v[2:3], 0, s[0:1]
	v_cmp_gt_i32_e32 vcc, s4, v78
	s_movk_i32 s4, 0x1c00
	s_mov_b64 s[0:1], 0x9000
	v_add_u32_e32 v21, 0x2600, v78
	v_cndmask_b32_e32 v29, v31, v29, vcc
	v_cndmask_b32_e32 v28, v30, v28, vcc
	v_lshl_add_u64 v[30:31], v[2:3], 0, s[0:1]
	v_cmp_gt_i32_e32 vcc, s4, v78
	v_and_b32_e32 v21, 0x3ff, v21
	s_movk_i32 s4, 0x1a00
	v_cndmask_b32_e32 v31, v5, v31, vcc
	v_cndmask_b32_e32 v30, v4, v30, vcc
	s_mov_b64 s[0:1], 0x9800
	v_lshlrev_b32_e32 v76, 2, v21
	global_load_dword v23, v[22:23], off nt
	v_lshl_add_u64 v[32:33], s[22:23], 0, v[76:77]
	global_load_dword v19, v[30:31], off nt
	v_lshl_add_u64 v[30:31], v[2:3], 0, s[0:1]
	v_cmp_gt_i32_e32 vcc, s4, v78
	s_movk_i32 s4, 0x1800
	s_mov_b64 s[0:1], 0xa000
	v_add_u32_e32 v22, 0x2a00, v78
	v_cndmask_b32_e32 v31, v33, v31, vcc
	v_cndmask_b32_e32 v30, v32, v30, vcc
	v_lshl_add_u64 v[32:33], v[2:3], 0, s[0:1]
	v_cmp_gt_i32_e32 vcc, s4, v78
	v_and_b32_e32 v22, 0x3ff, v22
	s_mov_b64 s[0:1], 0xa800
	v_cndmask_b32_e32 v33, v5, v33, vcc
	v_cndmask_b32_e32 v32, v4, v32, vcc
	v_lshlrev_b32_e32 v76, 2, v22
	global_load_dword v25, v[24:25], off nt
	v_lshl_add_u64 v[34:35], s[22:23], 0, v[76:77]
	global_load_dword v21, v[32:33], off nt
	v_lshl_add_u64 v[32:33], v[2:3], 0, s[0:1]
	v_cmp_gt_i32_e32 vcc, s9, v78
	s_movk_i32 s4, 0x1400
	s_mov_b64 s[0:1], 0xb000
	v_add_u32_e32 v24, 0x2e00, v78
	v_cndmask_b32_e32 v33, v35, v33, vcc
	v_cndmask_b32_e32 v32, v34, v32, vcc
	v_lshl_add_u64 v[34:35], v[2:3], 0, s[0:1]
	v_cmp_gt_i32_e32 vcc, s4, v78
	v_and_b32_e32 v24, 0x3ff, v24
	s_movk_i32 s4, 0x1200
	v_cndmask_b32_e32 v35, v5, v35, vcc
	v_cndmask_b32_e32 v34, v4, v34, vcc
	s_mov_b64 s[0:1], 0xb800
	v_lshlrev_b32_e32 v76, 2, v24
	global_load_dword v22, v[34:35], off nt
	v_lshl_add_u64 v[34:35], v[2:3], 0, s[0:1]
	v_lshl_add_u64 v[36:37], s[22:23], 0, v[76:77]
	v_cmp_gt_i32_e32 vcc, s4, v78
	global_load_dword v26, v[26:27], off nt
	s_movk_i32 s4, 0x1000
	v_cndmask_b32_e32 v35, v37, v35, vcc
	v_cndmask_b32_e32 v34, v36, v34, vcc
	s_mov_b64 s[0:1], 0xc000
	v_add_u32_e32 v27, 0x3200, v78
	global_load_dword v32, v[32:33], off nt
	v_cmp_gt_i32_e32 vcc, s4, v78
	global_load_dword v33, v[34:35], off nt
	v_lshl_add_u64 v[34:35], v[2:3], 0, s[0:1]
	v_and_b32_e32 v27, 0x3ff, v27
	v_cndmask_b32_e32 v35, v5, v35, vcc
	v_cndmask_b32_e32 v34, v4, v34, vcc
	s_movk_i32 s4, 0xe00
	s_mov_b64 s[0:1], 0xc800
	v_lshlrev_b32_e32 v76, 2, v27
	global_load_dword v28, v[28:29], off nt
	v_lshl_add_u64 v[36:37], s[22:23], 0, v[76:77]
	global_load_dword v24, v[34:35], off nt
	v_lshl_add_u64 v[34:35], v[2:3], 0, s[0:1]
	v_cmp_gt_i32_e32 vcc, s4, v78
	s_movk_i32 s4, 0xc00
	s_mov_b64 s[0:1], 0xd000
	v_add_u32_e32 v29, 0x3600, v78
	v_cndmask_b32_e32 v35, v37, v35, vcc
	v_cndmask_b32_e32 v34, v36, v34, vcc
	v_lshl_add_u64 v[36:37], v[2:3], 0, s[0:1]
	v_cmp_gt_i32_e32 vcc, s4, v78
	v_and_b32_e32 v29, 0x3ff, v29
	s_movk_i32 s4, 0xa00
	v_cndmask_b32_e32 v37, v5, v37, vcc
	v_cndmask_b32_e32 v36, v4, v36, vcc
	s_mov_b64 s[0:1], 0xd800
	v_lshlrev_b32_e32 v76, 2, v29
	global_load_dword v27, v[36:37], off nt
	v_lshl_add_u64 v[36:37], v[2:3], 0, s[0:1]
	v_lshl_add_u64 v[38:39], s[22:23], 0, v[76:77]
	v_cmp_gt_i32_e32 vcc, s4, v78
	global_load_dword v30, v[30:31], off nt
	s_movk_i32 s4, 0x800
	v_cndmask_b32_e32 v37, v39, v37, vcc
	v_cndmask_b32_e32 v36, v38, v36, vcc
	s_mov_b64 s[0:1], 0xe000
	v_add_u32_e32 v31, 0x3a00, v78
	global_load_dword v34, v[34:35], off nt
	v_cmp_gt_i32_e32 vcc, s4, v78
	global_load_dword v35, v[36:37], off nt
	v_lshl_add_u64 v[36:37], v[2:3], 0, s[0:1]
	v_and_b32_e32 v31, 0x3ff, v31
	v_cndmask_b32_e32 v37, v5, v37, vcc
	v_cndmask_b32_e32 v36, v4, v36, vcc
	s_movk_i32 s4, 0x600
	s_mov_b64 s[0:1], 0xe800
	v_lshlrev_b32_e32 v76, 2, v31
	global_load_dword v29, v[36:37], off nt
	v_lshl_add_u64 v[36:37], v[2:3], 0, s[0:1]
	v_lshl_add_u64 v[38:39], s[22:23], 0, v[76:77]
	v_cmp_gt_i32_e32 vcc, s4, v78
	s_movk_i32 s4, 0x400
	s_mov_b64 s[0:1], 0xf000
	v_cndmask_b32_e32 v37, v39, v37, vcc
	v_cndmask_b32_e32 v36, v38, v36, vcc
	global_load_dword v36, v[36:37], off nt
	v_add_u32_e32 v37, 0x3e00, v78
	v_lshl_add_u64 v[38:39], v[2:3], 0, s[0:1]
	v_cmp_gt_i32_e32 vcc, s4, v78
	v_and_b32_e32 v37, 0x3ff, v37
	s_movk_i32 s4, 0x200
	v_cndmask_b32_e32 v39, v5, v39, vcc
	v_cndmask_b32_e32 v38, v4, v38, vcc
	s_mov_b64 s[0:1], 0xf800
	v_lshlrev_b32_e32 v76, 2, v37
	global_load_dword v31, v[38:39], off nt
	v_lshl_add_u64 v[38:39], v[2:3], 0, s[0:1]
	v_lshl_add_u64 v[40:41], s[22:23], 0, v[76:77]
	v_cmp_gt_i32_e32 vcc, s4, v78
	s_mov_b64 s[0:1], 0x10000
	s_movk_i32 s4, 0xfe00
	v_cndmask_b32_e32 v39, v41, v39, vcc
	v_cndmask_b32_e32 v38, v40, v38, vcc
	global_load_dword v37, v[38:39], off nt
	v_lshl_add_u64 v[38:39], v[2:3], 0, s[0:1]
	v_cmp_gt_i32_e32 vcc, 0, v78
	s_mov_b64 s[0:1], 0x10800
	v_lshl_add_u64 v[2:3], v[2:3], 0, s[0:1]
	v_cndmask_b32_e32 v5, v5, v39, vcc
	v_cndmask_b32_e32 v4, v4, v38, vcc
	global_load_dword v4, v[4:5], off nt
	v_add_u32_e32 v5, 0x4200, v78
	v_and_b32_e32 v5, 0x3ff, v5
	v_lshlrev_b32_e32 v76, 2, v5
	s_waitcnt vmcnt(32)
	v_mul_f32_e32 v5, 0xbfb8aa3b, v6
	v_exp_f32_e32 v5, v5
	v_lshl_add_u64 v[38:39], s[22:23], 0, v[76:77]
	v_cmp_gt_i32_e32 vcc, s4, v78
	v_and_b32_e32 v1, 63, v78
	v_ashrrev_i32_e32 v79, 6, v78
	v_cndmask_b32_e32 v3, v39, v3, vcc
	v_cndmask_b32_e32 v2, v38, v2, vcc
	global_load_dword v2, v[2:3], off nt
	s_waitcnt vmcnt(32)
	v_mul_f32_e32 v3, 0xbfb8aa3b, v12
	v_exp_f32_e32 v38, v3
	v_add_f32_e32 v3, 1.0, v5
	v_rcp_f32_e32 v5, v3
	v_lshlrev_b32_e32 v3, 2, v78
	v_add_f32_e32 v38, 1.0, v38
	v_rcp_f32_e32 v38, v38
	v_mul_f32_e32 v5, v6, v5
	s_waitcnt vmcnt(31)
	v_mul_f32_e32 v6, 0xbfb8aa3b, v7
	v_exp_f32_e32 v6, v6
	v_mul_f32_e32 v12, v12, v38
	s_waitcnt vmcnt(30)
	v_mul_f32_e32 v38, 0xbfb8aa3b, v14
	v_exp_f32_e32 v38, v38
	v_add_f32_e32 v6, 1.0, v6
	v_rcp_f32_e32 v6, v6
	ds_write2st64_b32 v3, v5, v12 offset1:8
	v_add_f32_e32 v5, 1.0, v38
	v_rcp_f32_e32 v5, v5
	v_mul_f32_e32 v6, v7, v6
	s_waitcnt vmcnt(29)
	v_mul_f32_e32 v7, 0xbfb8aa3b, v8
	v_exp_f32_e32 v7, v7
	v_mul_f32_e32 v5, v14, v5
	s_waitcnt vmcnt(28)
	v_mul_f32_e32 v12, 0xbfb8aa3b, v16
	v_exp_f32_e32 v12, v12
	v_add_f32_e32 v7, 1.0, v7
	v_rcp_f32_e32 v7, v7
	ds_write2st64_b32 v3, v6, v5 offset0:16 offset1:24
	v_add_f32_e32 v5, 1.0, v12
	v_rcp_f32_e32 v5, v5
	v_mul_f32_e32 v6, v8, v7
	s_waitcnt vmcnt(27)
	v_mul_f32_e32 v7, 0xbfb8aa3b, v9
	v_exp_f32_e32 v7, v7
	v_mul_f32_e32 v5, v16, v5
	s_waitcnt vmcnt(26)
	v_mul_f32_e32 v8, 0xbfb8aa3b, v18
	v_exp_f32_e32 v8, v8
	v_add_f32_e32 v7, 1.0, v7
	v_rcp_f32_e32 v7, v7
	ds_write2st64_b32 v3, v6, v5 offset0:32 offset1:40
	v_add_f32_e32 v5, 1.0, v8
	v_rcp_f32_e32 v5, v5
	v_mul_f32_e32 v6, v9, v7
	s_waitcnt vmcnt(25)
	v_mul_f32_e32 v7, 0xbfb8aa3b, v10
	v_exp_f32_e32 v7, v7
	v_mul_f32_e32 v5, v18, v5
	s_waitcnt vmcnt(21)
	v_mul_f32_e32 v8, 0xbfb8aa3b, v20
	v_exp_f32_e32 v8, v8
	v_add_f32_e32 v7, 1.0, v7
	v_rcp_f32_e32 v7, v7
	ds_write2st64_b32 v3, v6, v5 offset0:48 offset1:56
	v_add_f32_e32 v5, 1.0, v8
	v_rcp_f32_e32 v5, v5
	v_mul_f32_e32 v6, v10, v7
	v_mul_f32_e32 v7, 0xbfb8aa3b, v11
	v_exp_f32_e32 v7, v7
	v_mul_f32_e32 v5, v20, v5
	s_waitcnt vmcnt(19)
	v_mul_f32_e32 v8, 0xbfb8aa3b, v23
	v_exp_f32_e32 v8, v8
	v_add_f32_e32 v7, 1.0, v7
	v_rcp_f32_e32 v7, v7
	ds_write2st64_b32 v3, v6, v5 offset0:64 offset1:72
	v_add_f32_e32 v5, 1.0, v8
	v_rcp_f32_e32 v5, v5
	v_mul_f32_e32 v6, v11, v7
	v_mul_f32_e32 v7, 0xbfb8aa3b, v13
	v_exp_f32_e32 v7, v7
	v_mul_f32_e32 v5, v23, v5
	s_waitcnt vmcnt(17)
	v_mul_f32_e32 v8, 0xbfb8aa3b, v25
	v_exp_f32_e32 v8, v8
	v_add_f32_e32 v7, 1.0, v7
	v_rcp_f32_e32 v7, v7
	ds_write2st64_b32 v3, v6, v5 offset0:80 offset1:88
	v_add_f32_e32 v5, 1.0, v8
	v_rcp_f32_e32 v5, v5
	v_mul_f32_e32 v6, v13, v7
	v_mul_f32_e32 v7, 0xbfb8aa3b, v15
	v_exp_f32_e32 v7, v7
	v_mul_f32_e32 v5, v25, v5
	s_waitcnt vmcnt(14)
	v_mul_f32_e32 v8, 0xbfb8aa3b, v26
	v_exp_f32_e32 v8, v8
	v_add_f32_e32 v7, 1.0, v7
	v_rcp_f32_e32 v7, v7
	ds_write2st64_b32 v3, v6, v5 offset0:96 offset1:104
	v_add_f32_e32 v5, 1.0, v8
	v_rcp_f32_e32 v5, v5
	v_mul_f32_e32 v6, v15, v7
	v_mul_f32_e32 v7, 0xbfb8aa3b, v17
	v_exp_f32_e32 v7, v7
	v_mul_f32_e32 v5, v26, v5
	s_waitcnt vmcnt(11)
	v_mul_f32_e32 v8, 0xbfb8aa3b, v28
	v_exp_f32_e32 v8, v8
	v_add_f32_e32 v7, 1.0, v7
	v_rcp_f32_e32 v7, v7
	ds_write2st64_b32 v3, v6, v5 offset0:112 offset1:120
	v_add_f32_e32 v5, 1.0, v8
	v_rcp_f32_e32 v5, v5
	v_mul_f32_e32 v6, v17, v7
	v_mul_f32_e32 v7, 0xbfb8aa3b, v19
	v_exp_f32_e32 v7, v7
	v_mul_f32_e32 v5, v28, v5
	s_waitcnt vmcnt(8)
	v_mul_f32_e32 v8, 0xbfb8aa3b, v30
	v_exp_f32_e32 v8, v8
	v_add_f32_e32 v7, 1.0, v7
	v_rcp_f32_e32 v7, v7
	ds_write2st64_b32 v3, v6, v5 offset0:128 offset1:136
	v_add_f32_e32 v5, 1.0, v8
	v_rcp_f32_e32 v5, v5
	v_mul_f32_e32 v6, v19, v7
	v_mul_f32_e32 v7, 0xbfb8aa3b, v21
	v_exp_f32_e32 v7, v7
	v_mul_f32_e32 v5, v30, v5
	v_mul_f32_e32 v8, 0xbfb8aa3b, v32
	v_exp_f32_e32 v8, v8
	v_add_f32_e32 v7, 1.0, v7
	v_rcp_f32_e32 v7, v7
	ds_write2st64_b32 v3, v6, v5 offset0:144 offset1:152
	v_add_f32_e32 v5, 1.0, v8
	v_rcp_f32_e32 v5, v5
	v_mul_f32_e32 v6, v21, v7
	v_mul_f32_e32 v7, 0xbfb8aa3b, v22
	v_exp_f32_e32 v7, v7
	v_mul_f32_e32 v5, v32, v5
	v_mul_f32_e32 v8, 0xbfb8aa3b, v33
	v_exp_f32_e32 v8, v8
	v_add_f32_e32 v7, 1.0, v7
	v_rcp_f32_e32 v7, v7
	ds_write2st64_b32 v3, v6, v5 offset0:160 offset1:168
	v_add_f32_e32 v5, 1.0, v8
	v_rcp_f32_e32 v5, v5
	v_mul_f32_e32 v6, v22, v7
	v_mul_f32_e32 v7, 0xbfb8aa3b, v24
	v_exp_f32_e32 v7, v7
	v_mul_f32_e32 v5, v33, v5
	s_waitcnt vmcnt(7)
	v_mul_f32_e32 v8, 0xbfb8aa3b, v34
	v_exp_f32_e32 v8, v8
	v_add_f32_e32 v7, 1.0, v7
	v_rcp_f32_e32 v7, v7
	ds_write2st64_b32 v3, v6, v5 offset0:176 offset1:184
	v_add_f32_e32 v5, 1.0, v8
	v_rcp_f32_e32 v5, v5
	v_mul_f32_e32 v6, v24, v7
	v_mul_f32_e32 v7, 0xbfb8aa3b, v27
	v_exp_f32_e32 v7, v7
	v_mul_f32_e32 v5, v34, v5
	s_waitcnt vmcnt(6)
	v_mul_f32_e32 v8, 0xbfb8aa3b, v35
	v_exp_f32_e32 v8, v8
	v_add_f32_e32 v7, 1.0, v7
	v_rcp_f32_e32 v7, v7
	ds_write2st64_b32 v3, v6, v5 offset0:192 offset1:200
	v_add_f32_e32 v5, 1.0, v8
	v_rcp_f32_e32 v5, v5
	v_mul_f32_e32 v6, v27, v7
	s_waitcnt vmcnt(5)
	v_mul_f32_e32 v7, 0xbfb8aa3b, v29
	v_exp_f32_e32 v7, v7
	s_waitcnt vmcnt(4)
	v_mul_f32_e32 v8, 0xbfb8aa3b, v36
	v_exp_f32_e32 v8, v8
	v_mul_f32_e32 v5, v35, v5
	v_add_f32_e32 v7, 1.0, v7
	v_rcp_f32_e32 v7, v7
	ds_write2st64_b32 v3, v6, v5 offset0:208 offset1:216
	v_add_f32_e32 v5, 1.0, v8
	v_rcp_f32_e32 v5, v5
	v_mul_f32_e32 v6, v29, v7
	s_waitcnt vmcnt(3)
	v_mul_f32_e32 v7, 0xbfb8aa3b, v31
	v_exp_f32_e32 v7, v7
	s_waitcnt vmcnt(2)
	v_mul_f32_e32 v8, 0xbfb8aa3b, v37
	v_exp_f32_e32 v8, v8
	v_mul_f32_e32 v5, v36, v5
	v_add_f32_e32 v7, 1.0, v7
	v_rcp_f32_e32 v7, v7
	ds_write2st64_b32 v3, v6, v5 offset0:224 offset1:232
	v_add_f32_e32 v5, 1.0, v8
	v_rcp_f32_e32 v5, v5
	s_waitcnt vmcnt(0)
	v_mul_f32_e32 v8, 0xbfb8aa3b, v2
	v_exp_f32_e32 v8, v8
	v_mul_f32_e32 v6, v31, v7
	v_mul_f32_e32 v7, 0xbfb8aa3b, v4
	v_exp_f32_e32 v7, v7
	v_mul_f32_e32 v5, v37, v5
	ds_write2st64_b32 v3, v6, v5 offset0:240 offset1:248
	v_add_f32_e32 v5, 1.0, v8
	v_rcp_f32_e32 v5, v5
	v_add_f32_e32 v7, 1.0, v7
	v_rcp_f32_e32 v7, v7
	v_add_u32_e32 v6, 0x10000, v3
	v_mul_f32_e32 v2, v2, v5
	v_add_u32_e32 v3, 0x10800, v3
	ds_write_b32 v3, v2
	v_add_u32_e32 v2, s3, v1
	v_mul_f32_e32 v4, v4, v7
	v_ashrrev_i32_e32 v3, 31, v2
	ds_write_b32 v6, v4
	v_lshlrev_b32_e32 v4, 7, v79
	v_lshlrev_b64 v[2:3], 2, v[2:3]
	v_readlane_b32 s24, v247, 9
	v_readlane_b32 s25, v247, 10
	v_mad_i64_i32 v[2:3], s[0:1], v4, s12, v[2:3]
	s_nop 0
	v_lshl_add_u64 v[80:81], s[24:25], 0, v[2:3]
	v_mov_b32_e32 v2, 0
	v_lshlrev_b32_e32 v93, 9, v79
	s_mov_b32 s0, -16
	v_mov_b32_e32 v3, v2
	v_mov_b32_e32 v20, v2
	v_mov_b32_e32 v21, v2
	v_mov_b32_e32 v28, v2
	v_mov_b32_e32 v29, v2
	v_mov_b32_e32 v94, v2
	v_mov_b32_e32 v95, v2
	v_mov_b32_e32 v96, v2
	v_mov_b32_e32 v97, v2
	v_mov_b32_e32 v98, v2
	v_mov_b32_e32 v99, v2
	v_mov_b32_e32 v100, v2
	v_mov_b32_e32 v101, v2
	v_mov_b32_e32 v102, v2
	v_mov_b32_e32 v103, v2
	v_mov_b32_e32 v83, v2
	v_readlane_b32 s17, v247, 2
	v_readlane_b32 s20, v247, 5
	v_readlane_b32 s21, v247, 6
	v_readlane_b32 s26, v247, 11
	v_readlane_b32 s27, v247, 12
	v_readlane_b32 s28, v247, 13
	v_readlane_b32 s29, v247, 14
	v_readlane_b32 s30, v247, 15
	v_readlane_b32 s31, v247, 16
	s_waitcnt lgkmcnt(0)
	s_barrier
.LBB0_87:
	v_add_co_u32_e32 v4, vcc, s12, v80
	s_mov_b32 s1, 0x12000
	s_nop 0
	v_addc_co_u32_e32 v5, vcc, 0, v81, vcc
	global_load_dword v106, v[80:81], off nt
	global_load_dword v108, v[4:5], off nt
	v_add_co_u32_e32 v4, vcc, s1, v80
	s_mov_b32 s1, 0x1b000
	s_nop 0
	v_addc_co_u32_e32 v5, vcc, 0, v81, vcc
	global_load_dword v110, v[4:5], off nt
	v_add_co_u32_e32 v4, vcc, s1, v80
	s_mov_b32 s1, 0x24000
	s_nop 0
	v_addc_co_u32_e32 v5, vcc, 0, v81, vcc
	global_load_dword v112, v[4:5], off nt
	v_add_co_u32_e32 v4, vcc, s1, v80
	s_mov_b32 s1, 0x2d000
	s_nop 0
	v_addc_co_u32_e32 v5, vcc, 0, v81, vcc
	global_load_dword v104, v[4:5], off nt
	v_add_co_u32_e32 v4, vcc, s1, v80
	s_mov_b32 s1, 0x36000
	s_nop 0
	v_addc_co_u32_e32 v5, vcc, 0, v81, vcc
	global_load_dword v92, v[4:5], off nt
	v_add_co_u32_e32 v4, vcc, s1, v80
	s_mov_b32 s1, 0x3f000
	s_nop 0
	v_addc_co_u32_e32 v5, vcc, 0, v81, vcc
	global_load_dword v90, v[4:5], off nt
	v_add_co_u32_e32 v4, vcc, s1, v80
	s_mov_b32 s1, 0x48000
	s_nop 0
	v_addc_co_u32_e32 v5, vcc, 0, v81, vcc
	global_load_dword v91, v[4:5], off nt
	v_add_co_u32_e32 v4, vcc, s1, v80
	s_mov_b32 s1, 0x51000
	s_nop 0
	v_addc_co_u32_e32 v5, vcc, 0, v81, vcc
	global_load_dword v86, v[4:5], off nt
	v_add_co_u32_e32 v4, vcc, s1, v80
	s_mov_b32 s1, 0x5a000
	s_nop 0
	v_addc_co_u32_e32 v5, vcc, 0, v81, vcc
	global_load_dword v87, v[4:5], off nt
	v_add_co_u32_e32 v4, vcc, s1, v80
	s_mov_b32 s1, 0x63000
	s_nop 0
	v_addc_co_u32_e32 v5, vcc, 0, v81, vcc
	global_load_dword v88, v[4:5], off nt
	v_add_co_u32_e32 v4, vcc, s1, v80
	s_mov_b32 s1, 0x6c000
	s_nop 0
	v_addc_co_u32_e32 v5, vcc, 0, v81, vcc
	global_load_dword v89, v[4:5], off nt
	v_add_co_u32_e32 v4, vcc, s1, v80
	s_mov_b32 s1, 0x75000
	s_nop 0
	v_addc_co_u32_e32 v5, vcc, 0, v81, vcc
	global_load_dword v84, v[4:5], off nt
	v_add_co_u32_e32 v4, vcc, s1, v80
	s_mov_b32 s1, 0x7e000
	s_nop 0
	v_addc_co_u32_e32 v5, vcc, 0, v81, vcc
	global_load_dword v85, v[4:5], off nt
	v_add_co_u32_e32 v4, vcc, s1, v80
	s_mov_b32 s1, 0x87000
	s_nop 0
	v_addc_co_u32_e32 v5, vcc, 0, v81, vcc
	global_load_dword v82, v[4:5], off nt
	v_add_co_u32_e32 v4, vcc, s1, v80
	s_add_i32 s0, s0, 16
	s_nop 0
	v_addc_co_u32_e32 v5, vcc, 0, v81, vcc
	global_load_dword v76, v[4:5], off nt
	v_add_u32_e32 v4, 0x10000, v93
	ds_read_b128 v[4:7], v4
	s_mov_b64 s[4:5], 0x90000
	v_lshl_add_u64 v[80:81], v[80:81], 0, s[4:5]
	s_cmpk_gt_u32 s0, 0x6f
	s_waitcnt vmcnt(15) lgkmcnt(0)
	v_fmac_f32_e32 v83, v106, v4
	s_waitcnt vmcnt(14)
	v_fmac_f32_e32 v83, v108, v5
	s_waitcnt vmcnt(13)
	v_fmac_f32_e32 v83, v110, v6
	s_waitcnt vmcnt(12)
	v_fmac_f32_e32 v83, v112, v7
	ds_read_b128 v[4:7], v93
	ds_read_b128 v[68:71], v93 offset:16
	ds_read_b128 v[56:59], v93 offset:32
	ds_read_b128 v[44:47], v93 offset:48
	ds_read_b128 v[72:75], v93 offset:4112
	ds_read_b128 v[8:11], v93 offset:4096
	s_waitcnt lgkmcnt(5)
	v_mov_b32_e32 v12, v4
	v_mov_b32_e32 v4, v6
	s_waitcnt lgkmcnt(0)
	v_mov_b32_e32 v13, v8
	v_pk_fma_f32 v[2:3], v[106:107], v[12:13], v[2:3] op_sel_hi:[0,1,1]
	v_mov_b32_e32 v8, v5
	v_pk_fma_f32 v[2:3], v[108:109], v[8:9], v[2:3] op_sel_hi:[0,1,1]
	v_mov_b32_e32 v5, v10
	v_pk_fma_f32 v[2:3], v[110:111], v[4:5], v[2:3] op_sel_hi:[0,1,1]
	v_mov_b32_e32 v10, v7
	v_pk_fma_f32 v[2:3], v[112:113], v[10:11], v[2:3] op_sel_hi:[0,1,1]
	v_mov_b32_e32 v4, v68
	v_mov_b32_e32 v5, v72
	s_waitcnt vmcnt(11)
	v_pk_fma_f32 v[118:119], v[104:105], v[4:5], v[2:3] op_sel_hi:[0,1,1]
	ds_read_b128 v[60:63], v93 offset:8208
	ds_read_b128 v[64:67], v93 offset:12304
	ds_read_b128 v[2:5], v93 offset:8192
	ds_read_b128 v[6:9], v93 offset:12288
	v_mov_b32_e32 v72, v69
	s_waitcnt lgkmcnt(1)
	v_mov_b32_e32 v10, v2
	s_waitcnt lgkmcnt(0)
	v_mov_b32_e32 v11, v6
	v_pk_fma_f32 v[10:11], v[106:107], v[10:11], v[20:21] op_sel_hi:[0,1,1]
	v_mov_b32_e32 v6, v3
	v_pk_fma_f32 v[2:3], v[108:109], v[6:7], v[10:11] op_sel_hi:[0,1,1]
	v_mov_b32_e32 v6, v4
	v_mov_b32_e32 v7, v8
	v_pk_fma_f32 v[2:3], v[110:111], v[6:7], v[2:3] op_sel_hi:[0,1,1]
	v_mov_b32_e32 v8, v5
	v_pk_fma_f32 v[2:3], v[112:113], v[8:9], v[2:3] op_sel_hi:[0,1,1]
	v_mov_b32_e32 v4, v60
	v_mov_b32_e32 v5, v64
	v_pk_fma_f32 v[116:117], v[104:105], v[4:5], v[2:3] op_sel_hi:[0,1,1]
	ds_read_b128 v[48:51], v93 offset:16400
	ds_read_b128 v[52:55], v93 offset:20496
	ds_read_b128 v[2:5], v93 offset:16384
	ds_read_b128 v[6:9], v93 offset:20480
	v_mov_b32_e32 v64, v61
	s_waitcnt lgkmcnt(1)
	v_mov_b32_e32 v10, v2
	s_waitcnt lgkmcnt(0)
	v_mov_b32_e32 v11, v6
	v_pk_fma_f32 v[10:11], v[106:107], v[10:11], v[28:29] op_sel_hi:[0,1,1]
	v_mov_b32_e32 v6, v3
	v_pk_fma_f32 v[2:3], v[108:109], v[6:7], v[10:11] op_sel_hi:[0,1,1]
	v_mov_b32_e32 v6, v4
	v_mov_b32_e32 v7, v8
	v_pk_fma_f32 v[2:3], v[110:111], v[6:7], v[2:3] op_sel_hi:[0,1,1]
	v_mov_b32_e32 v8, v5
	v_pk_fma_f32 v[2:3], v[112:113], v[8:9], v[2:3] op_sel_hi:[0,1,1]
	v_mov_b32_e32 v4, v48
	v_mov_b32_e32 v5, v52
	v_pk_fma_f32 v[114:115], v[104:105], v[4:5], v[2:3] op_sel_hi:[0,1,1]
	ds_read_b128 v[36:39], v93 offset:24592
	ds_read_b128 v[40:43], v93 offset:28688
	ds_read_b128 v[2:5], v93 offset:24576
	ds_read_b128 v[6:9], v93 offset:28672
	s_waitcnt vmcnt(6)
	v_mov_b32_e32 v48, v87
	v_mov_b32_e32 v52, v49
	s_waitcnt lgkmcnt(1)
	v_mov_b32_e32 v10, v2
	s_waitcnt lgkmcnt(0)
	v_mov_b32_e32 v11, v6
	v_pk_fma_f32 v[10:11], v[106:107], v[10:11], v[94:95] op_sel_hi:[0,1,1]
	v_mov_b32_e32 v6, v3
	v_pk_fma_f32 v[2:3], v[108:109], v[6:7], v[10:11] op_sel_hi:[0,1,1]
	v_mov_b32_e32 v6, v4
	v_mov_b32_e32 v7, v8
	v_pk_fma_f32 v[2:3], v[110:111], v[6:7], v[2:3] op_sel_hi:[0,1,1]
	v_mov_b32_e32 v8, v5
	v_pk_fma_f32 v[2:3], v[112:113], v[8:9], v[2:3] op_sel_hi:[0,1,1]
	v_mov_b32_e32 v4, v36
	v_mov_b32_e32 v5, v40
	v_pk_fma_f32 v[94:95], v[104:105], v[4:5], v[2:3] op_sel_hi:[0,1,1]
	ds_read_b128 v[28:31], v93 offset:32784
	ds_read_b128 v[32:35], v93 offset:36880
	ds_read_b128 v[2:5], v93 offset:32768
	ds_read_b128 v[6:9], v93 offset:36864
	v_mov_b32_e32 v40, v37
	v_mov_b32_e32 v36, v91
	s_waitcnt lgkmcnt(1)
	v_mov_b32_e32 v10, v2
	s_waitcnt lgkmcnt(0)
	v_mov_b32_e32 v11, v6
	v_pk_fma_f32 v[10:11], v[106:107], v[10:11], v[96:97] op_sel_hi:[0,1,1]
	v_mov_b32_e32 v6, v3
	v_pk_fma_f32 v[2:3], v[108:109], v[6:7], v[10:11] op_sel_hi:[0,1,1]
	v_mov_b32_e32 v6, v4
	v_mov_b32_e32 v7, v8
	v_pk_fma_f32 v[2:3], v[110:111], v[6:7], v[2:3] op_sel_hi:[0,1,1]
	v_mov_b32_e32 v8, v5
	v_pk_fma_f32 v[2:3], v[112:113], v[8:9], v[2:3] op_sel_hi:[0,1,1]
	v_mov_b32_e32 v4, v28
	v_mov_b32_e32 v5, v32
	v_pk_fma_f32 v[96:97], v[104:105], v[4:5], v[2:3] op_sel_hi:[0,1,1]
	ds_read_b128 v[20:23], v93 offset:40976
	ds_read_b128 v[24:27], v93 offset:45072
	ds_read_b128 v[2:5], v93 offset:40960
	ds_read_b128 v[6:9], v93 offset:45056
	v_mov_b32_e32 v32, v29
	v_mov_b32_e32 v28, v50
	v_mov_b32_e32 v29, v54
	s_waitcnt lgkmcnt(1)
	v_mov_b32_e32 v10, v2
	s_waitcnt lgkmcnt(0)
	v_mov_b32_e32 v11, v6
	v_pk_fma_f32 v[10:11], v[106:107], v[10:11], v[98:99] op_sel_hi:[0,1,1]
	v_mov_b32_e32 v6, v3
	v_pk_fma_f32 v[2:3], v[108:109], v[6:7], v[10:11] op_sel_hi:[0,1,1]
	v_mov_b32_e32 v6, v4
	v_mov_b32_e32 v7, v8
	v_pk_fma_f32 v[2:3], v[110:111], v[6:7], v[2:3] op_sel_hi:[0,1,1]
	v_mov_b32_e32 v8, v5
	v_pk_fma_f32 v[2:3], v[112:113], v[8:9], v[2:3] op_sel_hi:[0,1,1]
	v_mov_b32_e32 v4, v20
	v_mov_b32_e32 v5, v24
	v_pk_fma_f32 v[98:99], v[104:105], v[4:5], v[2:3] op_sel_hi:[0,1,1]
	ds_read_b128 v[12:15], v93 offset:49168
	ds_read_b128 v[16:19], v93 offset:53264
	ds_read_b128 v[2:5], v93 offset:49152
	ds_read_b128 v[6:9], v93 offset:53248
	v_mov_b32_e32 v24, v21
	v_mov_b32_e32 v20, v62
	v_mov_b32_e32 v21, v66
	s_waitcnt lgkmcnt(1)
	v_mov_b32_e32 v10, v2
	s_waitcnt lgkmcnt(0)
	v_mov_b32_e32 v11, v6
	v_pk_fma_f32 v[10:11], v[106:107], v[10:11], v[100:101] op_sel_hi:[0,1,1]
	v_mov_b32_e32 v6, v3
	v_pk_fma_f32 v[2:3], v[108:109], v[6:7], v[10:11] op_sel_hi:[0,1,1]
	v_mov_b32_e32 v6, v4
	v_mov_b32_e32 v7, v8
	v_pk_fma_f32 v[2:3], v[110:111], v[6:7], v[2:3] op_sel_hi:[0,1,1]
	v_mov_b32_e32 v8, v5
	v_pk_fma_f32 v[2:3], v[112:113], v[8:9], v[2:3] op_sel_hi:[0,1,1]
	v_mov_b32_e32 v4, v12
	v_mov_b32_e32 v5, v16
	v_pk_fma_f32 v[100:101], v[104:105], v[4:5], v[2:3] op_sel_hi:[0,1,1]
	ds_read_b128 v[4:7], v93 offset:57360
	ds_read_b128 v[8:11], v93 offset:61456
	ds_read_b128 v[120:123], v93 offset:57344
	ds_read_b128 v[124:127], v93 offset:61440
	v_mov_b32_e32 v16, v13
	v_mov_b32_e32 v13, v74
	v_mov_b32_e32 v74, v71
	s_waitcnt lgkmcnt(1)
	v_mov_b32_e32 v2, v120
	s_waitcnt lgkmcnt(0)
	v_mov_b32_e32 v3, v124
	v_pk_fma_f32 v[2:3], v[106:107], v[2:3], v[102:103] op_sel_hi:[0,1,1]
	v_mov_b32_e32 v124, v121
	v_pk_fma_f32 v[2:3], v[108:109], v[124:125], v[2:3] op_sel_hi:[0,1,1]
	v_mov_b32_e32 v102, v122
	v_mov_b32_e32 v103, v126
	v_pk_fma_f32 v[2:3], v[110:111], v[102:103], v[2:3] op_sel_hi:[0,1,1]
	v_mov_b32_e32 v126, v123
	v_pk_fma_f32 v[2:3], v[112:113], v[126:127], v[2:3] op_sel_hi:[0,1,1]
	v_mov_b32_e32 v102, v4
	v_mov_b32_e32 v103, v8
	v_pk_fma_f32 v[102:103], v[104:105], v[102:103], v[2:3] op_sel_hi:[0,1,1]
	v_add_u32_e32 v2, 0x10010, v93
	v_mov_b32_e32 v8, v5
	ds_read_b128 v[2:5], v2
	v_mov_b32_e32 v105, v92
	v_mov_b32_e32 v66, v63
	v_mov_b32_e32 v54, v51
	v_pk_fma_f32 v[8:9], v[92:93], v[8:9], v[102:103] op_sel_hi:[0,1,1]
	s_waitcnt lgkmcnt(0)
	v_pk_mul_f32 v[2:3], v[104:105], v[2:3]
	s_nop 0
	v_add_f32_e32 v2, v83, v2
	v_add_f32_e32 v12, v2, v3
	v_pk_mul_f32 v[2:3], v[90:91], v[4:5]
	s_nop 0
	v_add_f32_e32 v2, v12, v2
	v_add_f32_e32 v12, v2, v3
	v_add_u32_e32 v2, 0x10020, v93
	ds_read_b128 v[2:5], v2
	s_waitcnt lgkmcnt(0)
	v_pk_mul_f32 v[2:3], v[86:87], v[2:3]
	s_nop 0
	v_add_f32_e32 v2, v12, v2
	v_add_f32_e32 v12, v2, v3
	s_waitcnt vmcnt(4)
	v_pk_mul_f32 v[2:3], v[88:89], v[4:5]
	s_nop 0
	v_add_f32_e32 v2, v12, v2
	v_add_f32_e32 v12, v2, v3
	v_add_u32_e32 v2, 0x10030, v93
	ds_read_b128 v[2:5], v2
	s_waitcnt vmcnt(2) lgkmcnt(0)
	v_pk_mul_f32 v[2:3], v[84:85], v[2:3]
	s_nop 0
	v_add_f32_e32 v2, v12, v2
	v_mov_b32_e32 v12, v70
	ds_read_b128 v[68:71], v93 offset:4128
	v_add_f32_e32 v37, v2, v3
	v_pk_fma_f32 v[2:3], v[92:93], v[72:73], v[118:119] op_sel_hi:[0,1,1]
	v_pk_fma_f32 v[2:3], v[90:91], v[12:13], v[2:3] op_sel_hi:[0,1,1]
	v_pk_fma_f32 v[2:3], v[36:37], v[74:75], v[2:3] op_sel_hi:[0,1,1]
	v_mov_b32_e32 v12, v56
	s_waitcnt lgkmcnt(0)
	v_mov_b32_e32 v13, v68
	v_pk_fma_f32 v[2:3], v[86:87], v[12:13], v[2:3] op_sel_hi:[0,1,1]
	v_mov_b32_e32 v12, v58
	v_mov_b32_e32 v13, v70
	v_mov_b32_e32 v70, v59
	ds_read_b128 v[58:61], v93 offset:4144
	v_mov_b32_e32 v68, v57
	v_pk_fma_f32 v[2:3], v[48:49], v[68:69], v[2:3] op_sel_hi:[0,1,1]
	v_pk_fma_f32 v[2:3], v[88:89], v[12:13], v[2:3] op_sel_hi:[0,1,1]
	v_mov_b32_e32 v56, v89
	v_pk_fma_f32 v[2:3], v[56:57], v[70:71], v[2:3] op_sel_hi:[0,1,1]
	v_mov_b32_e32 v12, v44
	s_waitcnt lgkmcnt(0)
	v_mov_b32_e32 v13, v58
	v_pk_fma_f32 v[2:3], v[84:85], v[12:13], v[2:3] op_sel_hi:[0,1,1]
	v_mov_b32_e32 v44, v85
	v_mov_b32_e32 v58, v45
	v_pk_fma_f32 v[2:3], v[44:45], v[58:59], v[2:3] op_sel_hi:[0,1,1]
	v_mov_b32_e32 v12, v46
	v_mov_b32_e32 v13, v60
	s_waitcnt vmcnt(1)
	v_pk_fma_f32 v[2:3], v[82:83], v[12:13], v[2:3] op_sel_hi:[0,1,1]
	v_mov_b32_e32 v60, v47
	s_waitcnt vmcnt(0)
	v_pk_fma_f32 v[2:3], v[76:77], v[60:61], v[2:3] op_sel_hi:[0,1,1]
	v_pk_fma_f32 v[12:13], v[92:93], v[64:65], v[116:117] op_sel_hi:[0,1,1]
	ds_read_b128 v[58:61], v93 offset:8224
	ds_read_b128 v[62:65], v93 offset:12320
	v_pk_fma_f32 v[12:13], v[90:91], v[20:21], v[12:13] op_sel_hi:[0,1,1]
	v_pk_fma_f32 v[12:13], v[36:37], v[66:67], v[12:13] op_sel_hi:[0,1,1]
	s_waitcnt lgkmcnt(1)
	v_mov_b32_e32 v20, v58
	s_waitcnt lgkmcnt(0)
	v_mov_b32_e32 v21, v62
	v_pk_fma_f32 v[12:13], v[86:87], v[20:21], v[12:13] op_sel_hi:[0,1,1]
	v_mov_b32_e32 v62, v59
	v_pk_fma_f32 v[12:13], v[48:49], v[62:63], v[12:13] op_sel_hi:[0,1,1]
	v_mov_b32_e32 v20, v60
	v_mov_b32_e32 v21, v64
	v_pk_fma_f32 v[12:13], v[88:89], v[20:21], v[12:13] op_sel_hi:[0,1,1]
	v_mov_b32_e32 v64, v61
	v_pk_fma_f32 v[12:13], v[56:57], v[64:65], v[12:13] op_sel_hi:[0,1,1]
	ds_read_b128 v[58:61], v93 offset:8240
	ds_read_b128 v[62:65], v93 offset:12336
	s_waitcnt lgkmcnt(1)
	v_mov_b32_e32 v20, v58
	s_waitcnt lgkmcnt(0)
	v_mov_b32_e32 v21, v62
	v_pk_fma_f32 v[12:13], v[84:85], v[20:21], v[12:13] op_sel_hi:[0,1,1]
	v_mov_b32_e32 v62, v59
	v_pk_fma_f32 v[12:13], v[44:45], v[62:63], v[12:13] op_sel_hi:[0,1,1]
	v_mov_b32_e32 v20, v60
	v_mov_b32_e32 v21, v64
	v_pk_fma_f32 v[12:13], v[82:83], v[20:21], v[12:13] op_sel_hi:[0,1,1]
	v_mov_b32_e32 v64, v61
	v_pk_fma_f32 v[20:21], v[76:77], v[64:65], v[12:13] op_sel_hi:[0,1,1]
	v_pk_fma_f32 v[12:13], v[92:93], v[52:53], v[114:115] op_sel_hi:[0,1,1]
	ds_read_b128 v[50:53], v93 offset:16416
	ds_read_b128 v[58:61], v93 offset:20512
	v_pk_fma_f32 v[12:13], v[90:91], v[28:29], v[12:13] op_sel_hi:[0,1,1]
	v_pk_fma_f32 v[12:13], v[36:37], v[54:55], v[12:13] op_sel_hi:[0,1,1]
	s_waitcnt lgkmcnt(1)
	v_mov_b32_e32 v28, v50
	s_waitcnt lgkmcnt(0)
	v_mov_b32_e32 v29, v58
	v_pk_fma_f32 v[12:13], v[86:87], v[28:29], v[12:13] op_sel_hi:[0,1,1]
	v_mov_b32_e32 v58, v51
	v_pk_fma_f32 v[12:13], v[48:49], v[58:59], v[12:13] op_sel_hi:[0,1,1]
	v_mov_b32_e32 v28, v52
	v_mov_b32_e32 v29, v60
	v_pk_fma_f32 v[12:13], v[88:89], v[28:29], v[12:13] op_sel_hi:[0,1,1]
	v_mov_b32_e32 v60, v53
	v_pk_fma_f32 v[12:13], v[56:57], v[60:61], v[12:13] op_sel_hi:[0,1,1]
	ds_read_b128 v[50:53], v93 offset:16432
	ds_read_b128 v[58:61], v93 offset:20528
	s_waitcnt lgkmcnt(1)
	v_mov_b32_e32 v28, v50
	s_waitcnt lgkmcnt(0)
	v_mov_b32_e32 v29, v58
	v_pk_fma_f32 v[12:13], v[84:85], v[28:29], v[12:13] op_sel_hi:[0,1,1]
	v_mov_b32_e32 v58, v51
	v_pk_fma_f32 v[12:13], v[44:45], v[58:59], v[12:13] op_sel_hi:[0,1,1]
	v_mov_b32_e32 v28, v52
	v_mov_b32_e32 v29, v60
	v_pk_fma_f32 v[12:13], v[82:83], v[28:29], v[12:13] op_sel_hi:[0,1,1]
	v_mov_b32_e32 v60, v53
	v_pk_fma_f32 v[28:29], v[76:77], v[60:61], v[12:13] op_sel_hi:[0,1,1]
	v_pk_fma_f32 v[12:13], v[92:93], v[40:41], v[94:95] op_sel_hi:[0,1,1]
	v_mov_b32_e32 v40, v38
	v_mov_b32_e32 v41, v42
	v_pk_fma_f32 v[12:13], v[90:91], v[40:41], v[12:13] op_sel_hi:[0,1,1]
	v_mov_b32_e32 v42, v39
	ds_read_b128 v[38:41], v93 offset:24608
	ds_read_b128 v[50:53], v93 offset:28704
	v_pk_fma_f32 v[12:13], v[36:37], v[42:43], v[12:13] op_sel_hi:[0,1,1]
	s_waitcnt lgkmcnt(1)
	v_mov_b32_e32 v42, v38
	s_waitcnt lgkmcnt(0)
	v_mov_b32_e32 v43, v50
	v_pk_fma_f32 v[12:13], v[86:87], v[42:43], v[12:13] op_sel_hi:[0,1,1]
	v_mov_b32_e32 v50, v39
	v_pk_fma_f32 v[12:13], v[48:49], v[50:51], v[12:13] op_sel_hi:[0,1,1]
	v_mov_b32_e32 v38, v40
	v_mov_b32_e32 v39, v52
	v_pk_fma_f32 v[12:13], v[88:89], v[38:39], v[12:13] op_sel_hi:[0,1,1]
	v_mov_b32_e32 v52, v41
	v_pk_fma_f32 v[12:13], v[56:57], v[52:53], v[12:13] op_sel_hi:[0,1,1]
	ds_read_b128 v[38:41], v93 offset:24624
	ds_read_b128 v[50:53], v93 offset:28720
	s_waitcnt lgkmcnt(1)
	v_mov_b32_e32 v42, v38
	s_waitcnt lgkmcnt(0)
	v_mov_b32_e32 v43, v50
	v_pk_fma_f32 v[12:13], v[84:85], v[42:43], v[12:13] op_sel_hi:[0,1,1]
	v_mov_b32_e32 v50, v39
	v_pk_fma_f32 v[12:13], v[44:45], v[50:51], v[12:13] op_sel_hi:[0,1,1]
	v_mov_b32_e32 v38, v40
	v_mov_b32_e32 v39, v52
	v_pk_fma_f32 v[12:13], v[82:83], v[38:39], v[12:13] op_sel_hi:[0,1,1]
	v_mov_b32_e32 v52, v41
	v_pk_fma_f32 v[94:95], v[76:77], v[52:53], v[12:13] op_sel_hi:[0,1,1]
	v_pk_fma_f32 v[12:13], v[92:93], v[32:33], v[96:97] op_sel_hi:[0,1,1]
	v_mov_b32_e32 v32, v30
	v_mov_b32_e32 v33, v34
	v_pk_fma_f32 v[12:13], v[90:91], v[32:33], v[12:13] op_sel_hi:[0,1,1]
	v_mov_b32_e32 v34, v31
	ds_read_b128 v[30:33], v93 offset:32800
	ds_read_b128 v[38:41], v93 offset:36896
	v_pk_fma_f32 v[12:13], v[36:37], v[34:35], v[12:13] op_sel_hi:[0,1,1]
	s_waitcnt lgkmcnt(1)
	v_mov_b32_e32 v34, v30
	s_waitcnt lgkmcnt(0)
	v_mov_b32_e32 v35, v38
	v_pk_fma_f32 v[12:13], v[86:87], v[34:35], v[12:13] op_sel_hi:[0,1,1]
	v_mov_b32_e32 v38, v31
	v_pk_fma_f32 v[12:13], v[48:49], v[38:39], v[12:13] op_sel_hi:[0,1,1]
	v_mov_b32_e32 v30, v32
	v_mov_b32_e32 v31, v40
	v_pk_fma_f32 v[12:13], v[88:89], v[30:31], v[12:13] op_sel_hi:[0,1,1]
	v_mov_b32_e32 v40, v33
	v_pk_fma_f32 v[12:13], v[56:57], v[40:41], v[12:13] op_sel_hi:[0,1,1]
	ds_read_b128 v[30:33], v93 offset:32816
	ds_read_b128 v[38:41], v93 offset:36912
	s_waitcnt lgkmcnt(1)
	v_mov_b32_e32 v34, v30
	s_waitcnt lgkmcnt(0)
	v_mov_b32_e32 v35, v38
	v_pk_fma_f32 v[12:13], v[84:85], v[34:35], v[12:13] op_sel_hi:[0,1,1]
	v_mov_b32_e32 v38, v31
	v_pk_fma_f32 v[12:13], v[44:45], v[38:39], v[12:13] op_sel_hi:[0,1,1]
	v_mov_b32_e32 v30, v32
	v_mov_b32_e32 v31, v40
	v_pk_fma_f32 v[12:13], v[82:83], v[30:31], v[12:13] op_sel_hi:[0,1,1]
	v_mov_b32_e32 v40, v33
	v_pk_fma_f32 v[96:97], v[76:77], v[40:41], v[12:13] op_sel_hi:[0,1,1]
	v_pk_fma_f32 v[12:13], v[92:93], v[24:25], v[98:99] op_sel_hi:[0,1,1]
	v_mov_b32_e32 v24, v22
	v_mov_b32_e32 v25, v26
	v_pk_fma_f32 v[12:13], v[90:91], v[24:25], v[12:13] op_sel_hi:[0,1,1]
	v_mov_b32_e32 v26, v23
	ds_read_b128 v[22:25], v93 offset:40992
	ds_read_b128 v[30:33], v93 offset:45088
	v_pk_fma_f32 v[12:13], v[36:37], v[26:27], v[12:13] op_sel_hi:[0,1,1]
	s_waitcnt lgkmcnt(1)
	v_mov_b32_e32 v26, v22
	s_waitcnt lgkmcnt(0)
	v_mov_b32_e32 v27, v30
	v_pk_fma_f32 v[12:13], v[86:87], v[26:27], v[12:13] op_sel_hi:[0,1,1]
	v_mov_b32_e32 v30, v23
	v_pk_fma_f32 v[12:13], v[48:49], v[30:31], v[12:13] op_sel_hi:[0,1,1]
	v_mov_b32_e32 v22, v24
	v_mov_b32_e32 v23, v32
	v_pk_fma_f32 v[12:13], v[88:89], v[22:23], v[12:13] op_sel_hi:[0,1,1]
	v_mov_b32_e32 v32, v25
	v_pk_fma_f32 v[12:13], v[56:57], v[32:33], v[12:13] op_sel_hi:[0,1,1]
	ds_read_b128 v[22:25], v93 offset:41008
	ds_read_b128 v[30:33], v93 offset:45104
	s_waitcnt lgkmcnt(1)
	v_mov_b32_e32 v26, v22
	s_waitcnt lgkmcnt(0)
	v_mov_b32_e32 v27, v30
	v_pk_fma_f32 v[12:13], v[84:85], v[26:27], v[12:13] op_sel_hi:[0,1,1]
	v_mov_b32_e32 v30, v23
	v_pk_fma_f32 v[12:13], v[44:45], v[30:31], v[12:13] op_sel_hi:[0,1,1]
	v_mov_b32_e32 v22, v24
	v_mov_b32_e32 v23, v32
	v_pk_fma_f32 v[12:13], v[82:83], v[22:23], v[12:13] op_sel_hi:[0,1,1]
	v_mov_b32_e32 v32, v25
	v_pk_fma_f32 v[98:99], v[76:77], v[32:33], v[12:13] op_sel_hi:[0,1,1]
	v_pk_fma_f32 v[12:13], v[92:93], v[16:17], v[100:101] op_sel_hi:[0,1,1]
	v_mov_b32_e32 v16, v14
	v_mov_b32_e32 v17, v18
	v_pk_fma_f32 v[12:13], v[90:91], v[16:17], v[12:13] op_sel_hi:[0,1,1]
	v_mov_b32_e32 v18, v15
	v_pk_fma_f32 v[22:23], v[36:37], v[18:19], v[12:13] op_sel_hi:[0,1,1]
	ds_read_b128 v[12:15], v93 offset:49184
	ds_read_b128 v[16:19], v93 offset:53280
	s_waitcnt lgkmcnt(1)
	v_mov_b32_e32 v24, v12
	s_waitcnt lgkmcnt(0)
	v_mov_b32_e32 v25, v16
	v_pk_fma_f32 v[22:23], v[86:87], v[24:25], v[22:23] op_sel_hi:[0,1,1]
	v_mov_b32_e32 v16, v13
	v_pk_fma_f32 v[12:13], v[48:49], v[16:17], v[22:23] op_sel_hi:[0,1,1]
	v_mov_b32_e32 v16, v14
	v_mov_b32_e32 v17, v18
	v_pk_fma_f32 v[12:13], v[88:89], v[16:17], v[12:13] op_sel_hi:[0,1,1]
	v_mov_b32_e32 v18, v15
	v_pk_fma_f32 v[16:17], v[56:57], v[18:19], v[12:13] op_sel_hi:[0,1,1]
	ds_read_b128 v[12:15], v93 offset:49200
	ds_read_b128 v[22:25], v93 offset:53296
	s_waitcnt lgkmcnt(1)
	v_mov_b32_e32 v18, v12
	s_waitcnt lgkmcnt(0)
	v_mov_b32_e32 v19, v22
	v_pk_fma_f32 v[16:17], v[84:85], v[18:19], v[16:17] op_sel_hi:[0,1,1]
	v_mov_b32_e32 v22, v13
	v_pk_fma_f32 v[12:13], v[44:45], v[22:23], v[16:17] op_sel_hi:[0,1,1]
	v_mov_b32_e32 v16, v14
	v_mov_b32_e32 v17, v24
	v_pk_fma_f32 v[12:13], v[82:83], v[16:17], v[12:13] op_sel_hi:[0,1,1]
	v_mov_b32_e32 v24, v15
	v_pk_fma_f32 v[100:101], v[76:77], v[24:25], v[12:13] op_sel_hi:[0,1,1]
	v_mov_b32_e32 v12, v6
	v_mov_b32_e32 v13, v10
	v_pk_fma_f32 v[8:9], v[90:91], v[12:13], v[8:9] op_sel_hi:[0,1,1]
	v_mov_b32_e32 v10, v7
	v_pk_fma_f32 v[14:15], v[36:37], v[10:11], v[8:9] op_sel_hi:[0,1,1]
	ds_read_b128 v[6:9], v93 offset:57376
	ds_read_b128 v[10:13], v93 offset:61472
	s_waitcnt lgkmcnt(1)
	v_mov_b32_e32 v16, v6
	s_waitcnt lgkmcnt(0)
	v_mov_b32_e32 v17, v10
	v_pk_fma_f32 v[14:15], v[86:87], v[16:17], v[14:15] op_sel_hi:[0,1,1]
	v_mov_b32_e32 v10, v7
	v_pk_fma_f32 v[6:7], v[48:49], v[10:11], v[14:15] op_sel_hi:[0,1,1]
	v_mov_b32_e32 v10, v8
	v_mov_b32_e32 v11, v12
	v_pk_fma_f32 v[6:7], v[88:89], v[10:11], v[6:7] op_sel_hi:[0,1,1]
	v_mov_b32_e32 v12, v9
	v_pk_fma_f32 v[14:15], v[56:57], v[12:13], v[6:7] op_sel_hi:[0,1,1]
	ds_read_b128 v[6:9], v93 offset:57392
	ds_read_b128 v[10:13], v93 offset:61488
	v_add_u32_e32 v93, 64, v93
	s_waitcnt lgkmcnt(1)
	v_mov_b32_e32 v16, v6
	s_waitcnt lgkmcnt(0)
	v_mov_b32_e32 v17, v10
	v_pk_fma_f32 v[14:15], v[84:85], v[16:17], v[14:15] op_sel_hi:[0,1,1]
	v_mov_b32_e32 v10, v7
	v_pk_fma_f32 v[6:7], v[44:45], v[10:11], v[14:15] op_sel_hi:[0,1,1]
	v_mov_b32_e32 v10, v8
	v_mov_b32_e32 v11, v12
	v_pk_fma_f32 v[6:7], v[82:83], v[10:11], v[6:7] op_sel_hi:[0,1,1]
	v_mov_b32_e32 v83, v76
	v_pk_mul_f32 v[4:5], v[82:83], v[4:5]
	v_mov_b32_e32 v12, v9
	v_add_f32_e32 v4, v37, v4
	v_pk_fma_f32 v[102:103], v[76:77], v[12:13], v[6:7] op_sel_hi:[0,1,1]
	v_add_f32_e32 v83, v4, v5
	s_cbranch_scc0 .LBB0_87
	s_movk_i32 s0, 0x1100
	v_lshlrev_b32_e32 v6, 2, v1
	v_mul_lo_u32 v4, v79, s0
	s_movk_i32 s0, 0x440
	v_or_b32_e32 v4, v6, v4
	v_cmp_gt_i32_e32 vcc, s0, v78
	s_barrier
	ds_write2st64_b32 v4, v2, v3 offset1:1
	ds_write2st64_b32 v4, v20, v21 offset0:2 offset1:3
	ds_write2st64_b32 v4, v28, v29 offset0:4 offset1:5
	ds_write2st64_b32 v4, v94, v95 offset0:6 offset1:7
	ds_write2st64_b32 v4, v96, v97 offset0:8 offset1:9
	ds_write2st64_b32 v4, v98, v99 offset0:10 offset1:11
	ds_write2st64_b32 v4, v100, v101 offset0:12 offset1:13
	ds_write2st64_b32 v4, v102, v103 offset0:14 offset1:15
	ds_write_b32 v4, v83 offset:4096
	s_waitcnt lgkmcnt(0)
	s_barrier
	s_and_saveexec_b64 s[0:1], vcc
	s_cbranch_execz .LBB0_49
	v_lshl_or_b32 v2, s13, 6, v1
	v_readlane_b32 s16, v247, 1
	v_ashrrev_i32_e32 v3, 31, v2
	v_readlane_b32 s26, v247, 11
	v_readlane_b32 s27, v247, 12
	s_mov_b64 s[4:5], 0
	v_readlane_b32 s17, v247, 2
	v_lshl_add_u64 v[4:5], v[2:3], 2, s[26:27]
	v_readlane_b32 s18, v247, 3
	v_readlane_b32 s19, v247, 4
	v_readlane_b32 s20, v247, 5
	v_readlane_b32 s21, v247, 6
	v_readlane_b32 s22, v247, 7
	v_readlane_b32 s23, v247, 8
	v_readlane_b32 s24, v247, 9
	v_readlane_b32 s25, v247, 10
	v_readlane_b32 s28, v247, 13
	v_readlane_b32 s29, v247, 14
	v_readlane_b32 s30, v247, 15
	v_readlane_b32 s31, v247, 16
.LBB0_90:
	v_ashrrev_i32_e32 v1, 6, v78
	v_lshl_or_b32 v3, v1, 8, v6
	ds_read2st64_b32 v[8:9], v3 offset1:17
	s_waitcnt lgkmcnt(0)
	v_add_f32_e32 v7, 0, v8
	v_add_f32_e32 v7, v7, v9
	ds_read2st64_b32 v[8:9], v3 offset0:34 offset1:51
	s_waitcnt lgkmcnt(0)
	v_add_f32_e32 v7, v7, v8
	v_add_f32_e32 v7, v7, v9
	ds_read2st64_b32 v[8:9], v3 offset0:68 offset1:85
	s_waitcnt lgkmcnt(0)
	v_add_f32_e32 v7, v7, v8
	v_add_f32_e32 v7, v7, v9
	ds_read2st64_b32 v[8:9], v3 offset0:102 offset1:119
	s_waitcnt lgkmcnt(0)
	v_add_f32_e32 v3, v7, v8
	global_load_dword v7, v[4:5], off nt
	v_add_f32_e32 v3, v3, v9
	s_waitcnt vmcnt(0)
	v_add_f32_e32 v3, v3, v7
	v_mad_u64_u32 v[8:9], s[14:15], v1, s11, v[2:3]
	s_movk_i32 s14, 0x23f
	v_ashrrev_i32_e32 v9, 31, v8
	v_add_u32_e32 v1, 0x200, v78
	v_cmp_lt_i32_e32 vcc, s14, v78
	v_lshl_add_u64 v[8:9], v[8:9], 2, s[40:41]
	s_or_b64 s[4:5], vcc, s[4:5]
	v_mov_b32_e32 v78, v1
	global_store_dword v[8:9], v3, off
	s_andn2_b64 exec, exec, s[4:5]
	s_cbranch_execnz .LBB0_90
	s_branch .LBB0_49

.LBB0_92:
	s_cmpk_lt_i32 s2, 0x90
	s_mov_b64 s[0:1], -1
	s_cbranch_scc1 .LBB0_254
	v_mov_b32_e32 v3, v162
	s_mul_i32 s3, s2, 10
	s_add_i32 s0, s3, 0xfffffb80
	v_ashrrev_i32_e32 v6, 8, v3
	v_add_u32_e32 v1, s0, v6
	v_ashrrev_i32_e32 v2, 31, v1
	v_lshrrev_b32_e32 v2, 28, v2
	v_add_u32_e32 v2, v1, v2
	v_ashrrev_i32_e32 v5, 4, v2
	v_and_b32_e32 v2, 0x3fffff0, v2
	v_and_b32_e32 v7, 63, v3
	v_sub_u32_e32 v2, v1, v2
	v_lshlrev_b32_e32 v1, 6, v5
	v_readlane_b32 s68, v247, 17
	v_readlane_b32 s8, v247, 1
	v_or_b32_e32 v4, v1, v7
	s_movk_i32 s0, 0x1600
	v_lshlrev_b32_e32 v8, 5, v5
	s_movk_i32 s4, 0x7f
	v_and_b32_e32 v5, 2, v5
	v_readlane_b32 s69, v247, 18
	v_readlane_b32 s23, v247, 16
	v_cmp_gt_i32_e64 s[0:1], s0, v4
	v_bfi_b32 v4, s4, v4, v8
	v_mov_b32_e32 v8, s69
	v_readlane_b32 s22, v247, 15
	v_mov_b32_e32 v9, s23
	v_cmp_eq_u32_e32 vcc, 0, v5
	v_mov_b32_e32 v5, s68
	v_lshlrev_b32_e32 v2, 6, v2
	v_cndmask_b32_e32 v13, v8, v9, vcc
	v_mov_b32_e32 v8, s22
	v_cndmask_b32_e32 v12, v5, v8, vcc
	v_lshrrev_b32_e32 v5, 2, v3
	v_and_b32_e32 v8, 48, v5
	v_ashrrev_i32_e32 v5, 31, v4
	v_or_b32_e32 v11, v2, v8
	v_lshl_add_u64 v[4:5], v[4:5], 2, v[12:13]
	v_mov_b32_e32 v10, 0
	v_mov_b32_e32 v9, 0
	v_readlane_b32 s70, v247, 19
	v_readlane_b32 s71, v247, 20
	v_readlane_b32 s72, v247, 21
	v_readlane_b32 s73, v247, 22
	v_readlane_b32 s74, v247, 23
	v_readlane_b32 s75, v247, 24
	v_readlane_b32 s76, v247, 25
	v_readlane_b32 s77, v247, 26
	v_readlane_b32 s78, v247, 27
	v_readlane_b32 s79, v247, 28
	v_readlane_b32 s80, v247, 29
	v_readlane_b32 s81, v247, 30
	v_readlane_b32 s82, v247, 31
	v_readlane_b32 s83, v247, 32
	v_readlane_b32 s9, v247, 2
	v_readlane_b32 s10, v247, 3
	v_readlane_b32 s11, v247, 4
	v_readlane_b32 s12, v247, 5
	v_readlane_b32 s13, v247, 6
	v_readlane_b32 s14, v247, 7
	v_readlane_b32 s15, v247, 8
	v_readlane_b32 s16, v247, 9
	v_readlane_b32 s17, v247, 10
	v_readlane_b32 s18, v247, 11
	v_readlane_b32 s19, v247, 12
	v_readlane_b32 s20, v247, 13
	v_readlane_b32 s21, v247, 14
	s_and_saveexec_b64 s[4:5], s[0:1]
	s_cbranch_execz .LBB0_95
	s_movk_i32 s8, 0xb00
	v_mul_lo_u32 v12, v11, s8
	v_ashrrev_i32_e32 v13, 31, v12
	v_lshl_add_u64 v[12:13], v[12:13], 2, v[4:5]
	global_load_dword v9, v[12:13], off nt
.LBB0_95:
	s_or_b64 exec, exec, s[4:5]
	s_and_saveexec_b64 s[4:5], s[0:1]
	s_cbranch_execz .LBB0_97
	s_movk_i32 s8, 0xb00
	v_mul_lo_u32 v12, v11, s8
	v_ashrrev_i32_e32 v13, 31, v12
	v_lshl_add_u64 v[12:13], v[12:13], 2, v[4:5]
	v_add_co_u32_e32 v12, vcc, 0x2000, v12
	s_nop 1
	v_addc_co_u32_e32 v13, vcc, 0, v13, vcc
	global_load_dword v10, v[12:13], off offset:3072 nt
.LBB0_97:
	s_or_b64 exec, exec, s[4:5]
	v_mov_b32_e32 v12, 0
	v_mov_b32_e32 v13, 0
	s_and_saveexec_b64 s[4:5], s[0:1]
	s_cbranch_execz .LBB0_99
	s_movk_i32 s8, 0xb00
	v_mul_lo_u32 v14, v11, s8
	v_ashrrev_i32_e32 v15, 31, v14
	v_lshl_add_u64 v[14:15], v[14:15], 2, v[4:5]
	v_add_co_u32_e32 v14, vcc, 0x5000, v14
	s_nop 1
	v_addc_co_u32_e32 v15, vcc, 0, v15, vcc
	global_load_dword v13, v[14:15], off offset:2048 nt
.LBB0_99:
	s_or_b64 exec, exec, s[4:5]
	s_and_saveexec_b64 s[4:5], s[0:1]
	s_cbranch_execz .LBB0_101
	s_movk_i32 s8, 0xb00
	v_mul_lo_u32 v14, v11, s8
	v_ashrrev_i32_e32 v15, 31, v14
	v_lshl_add_u64 v[14:15], v[14:15], 2, v[4:5]
	v_add_co_u32_e32 v14, vcc, 0x8000, v14
	s_nop 1
	v_addc_co_u32_e32 v15, vcc, 0, v15, vcc
	global_load_dword v12, v[14:15], off offset:1024 nt
.LBB0_101:
	s_or_b64 exec, exec, s[4:5]
	v_mov_b32_e32 v14, 0
	v_mov_b32_e32 v15, 0
	s_and_saveexec_b64 s[4:5], s[0:1]
	s_cbranch_execz .LBB0_103
	s_movk_i32 s8, 0xb00
	v_mul_lo_u32 v16, v11, s8
	v_ashrrev_i32_e32 v17, 31, v16
	v_lshl_add_u64 v[16:17], v[16:17], 2, v[4:5]
	v_add_co_u32_e32 v16, vcc, 0xb000, v16
	s_nop 1
	v_addc_co_u32_e32 v17, vcc, 0, v17, vcc
	global_load_dword v15, v[16:17], off nt
.LBB0_103:
	s_or_b64 exec, exec, s[4:5]
	s_and_saveexec_b64 s[4:5], s[0:1]
	s_cbranch_execz .LBB0_105
	s_movk_i32 s8, 0xb00
	v_mul_lo_u32 v16, v11, s8
	v_ashrrev_i32_e32 v17, 31, v16
	v_lshl_add_u64 v[16:17], v[16:17], 2, v[4:5]
	v_add_co_u32_e32 v16, vcc, 0xd000, v16
	s_nop 1
	v_addc_co_u32_e32 v17, vcc, 0, v17, vcc
	global_load_dword v14, v[16:17], off offset:3072 nt
.LBB0_105:
	s_or_b64 exec, exec, s[4:5]
	v_mov_b32_e32 v16, 0
	v_mov_b32_e32 v17, 0
	s_and_saveexec_b64 s[4:5], s[0:1]
	s_cbranch_execz .LBB0_107
	s_movk_i32 s8, 0xb00
	v_mul_lo_u32 v18, v11, s8
	v_ashrrev_i32_e32 v19, 31, v18
	v_lshl_add_u64 v[18:19], v[18:19], 2, v[4:5]
	v_add_co_u32_e32 v18, vcc, 0x10000, v18
	s_nop 1
	v_addc_co_u32_e32 v19, vcc, 0, v19, vcc
	global_load_dword v17, v[18:19], off offset:2048 nt
.LBB0_107:
	s_or_b64 exec, exec, s[4:5]
	s_and_saveexec_b64 s[4:5], s[0:1]
	s_cbranch_execz .LBB0_109
	s_movk_i32 s8, 0xb00
	v_mul_lo_u32 v18, v11, s8
	v_ashrrev_i32_e32 v19, 31, v18
	v_lshl_add_u64 v[18:19], v[18:19], 2, v[4:5]
	v_add_co_u32_e32 v18, vcc, 0x13000, v18
	s_nop 1
	v_addc_co_u32_e32 v19, vcc, 0, v19, vcc
	global_load_dword v16, v[18:19], off offset:1024 nt
.LBB0_109:
	s_or_b64 exec, exec, s[4:5]
	v_mov_b32_e32 v18, 0
	v_mov_b32_e32 v19, 0
	s_and_saveexec_b64 s[4:5], s[0:1]
	s_cbranch_execz .LBB0_111
	s_movk_i32 s8, 0xb00
	v_mul_lo_u32 v20, v11, s8
	v_ashrrev_i32_e32 v21, 31, v20
	v_lshl_add_u64 v[20:21], v[20:21], 2, v[4:5]
	v_add_co_u32_e32 v20, vcc, 0x16000, v20
	s_nop 1
	v_addc_co_u32_e32 v21, vcc, 0, v21, vcc
	global_load_dword v19, v[20:21], off nt
.LBB0_111:
	s_or_b64 exec, exec, s[4:5]
	s_and_saveexec_b64 s[4:5], s[0:1]
	s_cbranch_execz .LBB0_113
	s_movk_i32 s8, 0xb00
	v_mul_lo_u32 v20, v11, s8
	v_ashrrev_i32_e32 v21, 31, v20
	v_lshl_add_u64 v[20:21], v[20:21], 2, v[4:5]
	v_add_co_u32_e32 v20, vcc, 0x18000, v20
	s_nop 1
	v_addc_co_u32_e32 v21, vcc, 0, v21, vcc
	global_load_dword v18, v[20:21], off offset:3072 nt
.LBB0_113:
	s_or_b64 exec, exec, s[4:5]
	v_mov_b32_e32 v20, 0
	v_mov_b32_e32 v21, 0
	s_and_saveexec_b64 s[4:5], s[0:1]
	s_cbranch_execz .LBB0_115
	s_movk_i32 s8, 0xb00
	v_mul_lo_u32 v22, v11, s8
	v_ashrrev_i32_e32 v23, 31, v22
	v_lshl_add_u64 v[22:23], v[22:23], 2, v[4:5]
	v_add_co_u32_e32 v22, vcc, 0x1b000, v22
	s_nop 1
	v_addc_co_u32_e32 v23, vcc, 0, v23, vcc
	global_load_dword v21, v[22:23], off offset:2048 nt
.LBB0_115:
	s_or_b64 exec, exec, s[4:5]
	s_and_saveexec_b64 s[4:5], s[0:1]
	s_cbranch_execz .LBB0_117
	s_movk_i32 s8, 0xb00
	v_mul_lo_u32 v22, v11, s8
	v_ashrrev_i32_e32 v23, 31, v22
	v_lshl_add_u64 v[22:23], v[22:23], 2, v[4:5]
	v_add_co_u32_e32 v22, vcc, 0x1e000, v22
	s_nop 1
	v_addc_co_u32_e32 v23, vcc, 0, v23, vcc
	global_load_dword v20, v[22:23], off offset:1024 nt
.LBB0_117:
	s_or_b64 exec, exec, s[4:5]
	v_mov_b32_e32 v22, 0
	v_mov_b32_e32 v23, 0
	s_and_saveexec_b64 s[4:5], s[0:1]
	s_cbranch_execz .LBB0_119
	s_movk_i32 s8, 0xb00
	v_mul_lo_u32 v24, v11, s8
	v_ashrrev_i32_e32 v25, 31, v24
	v_lshl_add_u64 v[24:25], v[24:25], 2, v[4:5]
	v_add_co_u32_e32 v24, vcc, 0x21000, v24
	s_nop 1
	v_addc_co_u32_e32 v25, vcc, 0, v25, vcc
	global_load_dword v23, v[24:25], off nt
.LBB0_119:
	s_or_b64 exec, exec, s[4:5]
	s_and_saveexec_b64 s[4:5], s[0:1]
	s_cbranch_execz .LBB0_121
	s_movk_i32 s8, 0xb00
	v_mul_lo_u32 v24, v11, s8
	v_ashrrev_i32_e32 v25, 31, v24
	v_lshl_add_u64 v[24:25], v[24:25], 2, v[4:5]
	v_add_co_u32_e32 v24, vcc, 0x23000, v24
	s_nop 1
	v_addc_co_u32_e32 v25, vcc, 0, v25, vcc
	global_load_dword v22, v[24:25], off offset:3072 nt
.LBB0_121:
	s_or_b64 exec, exec, s[4:5]
	v_mov_b32_e32 v24, 0
	v_mov_b32_e32 v25, 0
	s_and_saveexec_b64 s[4:5], s[0:1]
	s_cbranch_execz .LBB0_123
	s_movk_i32 s8, 0xb00
	v_mul_lo_u32 v26, v11, s8
	v_ashrrev_i32_e32 v27, 31, v26
	v_lshl_add_u64 v[26:27], v[26:27], 2, v[4:5]
	v_add_co_u32_e32 v26, vcc, 0x26000, v26
	s_nop 1
	v_addc_co_u32_e32 v27, vcc, 0, v27, vcc
	global_load_dword v25, v[26:27], off offset:2048 nt
.LBB0_123:
	s_or_b64 exec, exec, s[4:5]
	s_and_saveexec_b64 s[4:5], s[0:1]
	s_cbranch_execz .LBB0_125
	s_movk_i32 s0, 0xb00
	v_mul_lo_u32 v26, v11, s0
	v_ashrrev_i32_e32 v27, 31, v26
	v_lshl_add_u64 v[4:5], v[26:27], 2, v[4:5]
	v_add_co_u32_e32 v4, vcc, 0x29000, v4
	s_nop 1
	v_addc_co_u32_e32 v5, vcc, 0, v5, vcc
	global_load_dword v24, v[4:5], off offset:1024 nt
.LBB0_125:
	s_or_b64 exec, exec, s[4:5]
	v_mul_i32_i24_e32 v4, 0x4100, v6
	v_lshl_or_b32 v5, v7, 2, v4
	s_movk_i32 s0, 0x104
	v_mad_u32_u24 v5, v8, s0, v5
	v_add_u32_e32 v6, 0x400, v5
	s_waitcnt vmcnt(0)
	ds_write2_b32 v5, v9, v10 offset1:65
	ds_write2_b32 v5, v13, v12 offset0:130 offset1:195
	ds_write2_b32 v6, v15, v14 offset0:4 offset1:69
	ds_write2_b32 v6, v17, v16 offset0:134 offset1:199
	v_add_u32_e32 v6, 0x800, v5
	ds_write2_b32 v6, v19, v18 offset0:8 offset1:73
	ds_write2_b32 v6, v21, v20 offset0:138 offset1:203
	v_bfe_u32 v20, v3, 2, 6
	v_lshlrev_b32_e32 v3, 4, v3
	v_and_b32_e32 v21, 48, v3
	v_lshl_or_b32 v3, v20, 2, v4
	v_add_u32_e32 v5, 0xc00, v5
	v_mad_u32_u24 v3, v21, s0, v3
	ds_write2_b32 v5, v23, v22 offset0:12 offset1:77
	ds_write2_b32 v5, v25, v24 offset0:142 offset1:207
	s_waitcnt lgkmcnt(0)
	s_barrier
	ds_read2_b32 v[4:5], v3 offset1:65
	ds_read2_b32 v[6:7], v3 offset0:130 offset1:195
	v_add_u32_e32 v10, 0x400, v3
	v_add_u32_e32 v14, 0x800, v3
	ds_read2_b32 v[8:9], v10 offset0:4 offset1:69
	ds_read2_b32 v[10:11], v10 offset0:134 offset1:199
	ds_read2_b32 v[12:13], v14 offset0:8 offset1:73
	ds_read2_b32 v[14:15], v14 offset0:138 offset1:203
	v_add_u32_e32 v3, 0xc00, v3
	s_waitcnt lgkmcnt(5)
	v_cvt_pk_bf16_f32 v4, v4, v5
	s_waitcnt lgkmcnt(4)
	v_cvt_pk_bf16_f32 v5, v6, v7
	s_waitcnt lgkmcnt(3)
	v_cvt_pk_bf16_f32 v6, v8, v9
	s_waitcnt lgkmcnt(1)
	v_cvt_pk_bf16_f32 v8, v12, v13
	v_or_b32_e32 v12, v1, v20
	ds_read2_b32 v[16:17], v3 offset0:12 offset1:77
	ds_read2_b32 v[18:19], v3 offset0:142 offset1:207
	v_ashrrev_i32_e32 v13, 31, v12
	v_lshlrev_b64 v[12:13], 11, v[12:13]
	v_lshl_add_u64 v[12:13], s[46:47], 0, v[12:13]
	v_ashrrev_i32_e32 v3, 31, v2
	v_lshl_add_u64 v[12:13], v[2:3], 1, v[12:13]
	v_lshlrev_b32_e32 v2, 1, v21
	v_mov_b32_e32 v3, 0
	v_cvt_pk_bf16_f32 v7, v10, v11
	v_lshl_add_u64 v[12:13], v[12:13], 0, v[2:3]
	s_waitcnt lgkmcnt(2)
	v_cvt_pk_bf16_f32 v9, v14, v15
	s_waitcnt lgkmcnt(1)
	v_cvt_pk_bf16_f32 v10, v16, v17
	s_waitcnt lgkmcnt(0)
	v_cvt_pk_bf16_f32 v11, v18, v19
	global_store_dwordx4 v[12:13], v[4:7], off
	global_store_dwordx4 v[12:13], v[8:11], off offset:16
	s_nop 0
	v_mov_b32_e32 v6, v162
	s_barrier
	s_add_i32 s0, s3, 0xfffffb82
	v_ashrrev_i32_e32 v7, 8, v6
	v_add_u32_e32 v1, s0, v7
	v_ashrrev_i32_e32 v2, 31, v1
	v_lshrrev_b32_e32 v2, 28, v2
	v_add_u32_e32 v2, v1, v2
	v_ashrrev_i32_e32 v5, 4, v2
	v_and_b32_e32 v2, 0x3fffff0, v2
	v_and_b32_e32 v8, 63, v6
	v_sub_u32_e32 v2, v1, v2
	v_lshlrev_b32_e32 v1, 6, v5
	v_readlane_b32 s68, v247, 17
	v_readlane_b32 s8, v247, 1
	v_or_b32_e32 v4, v1, v8
	s_movk_i32 s0, 0x1600
	v_lshlrev_b32_e32 v9, 5, v5
	s_movk_i32 s4, 0x7f
	v_and_b32_e32 v5, 2, v5
	v_readlane_b32 s69, v247, 18
	v_readlane_b32 s23, v247, 16
	v_cmp_gt_i32_e64 s[0:1], s0, v4
	v_bfi_b32 v4, s4, v4, v9
	v_mov_b32_e32 v9, s69
	v_readlane_b32 s22, v247, 15
	v_mov_b32_e32 v10, s23
	v_cmp_eq_u32_e32 vcc, 0, v5
	v_mov_b32_e32 v5, s68
	v_lshlrev_b32_e32 v2, 6, v2
	v_cndmask_b32_e32 v13, v9, v10, vcc
	v_mov_b32_e32 v9, s22
	v_cndmask_b32_e32 v12, v5, v9, vcc
	v_lshrrev_b32_e32 v5, 2, v6
	v_and_b32_e32 v9, 48, v5
	v_ashrrev_i32_e32 v5, 31, v4
	v_or_b32_e32 v11, v2, v9
	v_lshl_add_u64 v[4:5], v[4:5], 2, v[12:13]
	v_mov_b32_e32 v10, 0
	v_readlane_b32 s70, v247, 19
	v_readlane_b32 s71, v247, 20
	v_readlane_b32 s72, v247, 21
	v_readlane_b32 s73, v247, 22
	v_readlane_b32 s74, v247, 23
	v_readlane_b32 s75, v247, 24
	v_readlane_b32 s76, v247, 25
	v_readlane_b32 s77, v247, 26
	v_readlane_b32 s78, v247, 27
	v_readlane_b32 s79, v247, 28
	v_readlane_b32 s80, v247, 29
	v_readlane_b32 s81, v247, 30
	v_readlane_b32 s82, v247, 31
	v_readlane_b32 s83, v247, 32
	v_readlane_b32 s9, v247, 2
	v_readlane_b32 s10, v247, 3
	v_readlane_b32 s11, v247, 4
	v_readlane_b32 s12, v247, 5
	v_readlane_b32 s13, v247, 6
	v_readlane_b32 s14, v247, 7
	v_readlane_b32 s15, v247, 8
	v_readlane_b32 s16, v247, 9
	v_readlane_b32 s17, v247, 10
	v_readlane_b32 s18, v247, 11
	v_readlane_b32 s19, v247, 12
	v_readlane_b32 s20, v247, 13
	v_readlane_b32 s21, v247, 14
	s_and_saveexec_b64 s[4:5], s[0:1]
	s_cbranch_execz .LBB0_127
	s_movk_i32 s8, 0xb00
	v_mul_lo_u32 v12, v11, s8
	v_ashrrev_i32_e32 v13, 31, v12
	v_lshl_add_u64 v[12:13], v[12:13], 2, v[4:5]
	global_load_dword v10, v[12:13], off nt
.LBB0_127:
	s_or_b64 exec, exec, s[4:5]
	s_and_saveexec_b64 s[4:5], s[0:1]
	s_cbranch_execz .LBB0_129
	s_movk_i32 s8, 0xb00
	v_mul_lo_u32 v12, v11, s8
	v_ashrrev_i32_e32 v13, 31, v12
	v_lshl_add_u64 v[12:13], v[12:13], 2, v[4:5]
	v_add_co_u32_e32 v12, vcc, 0x2000, v12
	s_nop 1
	v_addc_co_u32_e32 v13, vcc, 0, v13, vcc
	global_load_dword v3, v[12:13], off offset:3072 nt

.LBB0_157:
	s_or_b64 exec, exec, s[4:5]
	v_mul_i32_i24_e32 v4, 0x4100, v7
	v_lshl_or_b32 v5, v8, 2, v4
	s_movk_i32 s0, 0x104
	v_mad_u32_u24 v5, v9, s0, v5
	s_waitcnt vmcnt(0)
	ds_write2_b32 v5, v10, v3 offset1:65
	ds_write2_b32 v5, v13, v12 offset0:130 offset1:195
	v_add_u32_e32 v3, 0x400, v5
	ds_write2_b32 v3, v15, v14 offset0:4 offset1:69
	ds_write2_b32 v3, v17, v16 offset0:134 offset1:199
	v_add_u32_e32 v3, 0x800, v5
	ds_write2_b32 v3, v19, v18 offset0:8 offset1:73
	ds_write2_b32 v3, v21, v20 offset0:138 offset1:203
	v_add_u32_e32 v3, 0xc00, v5
	ds_write2_b32 v3, v23, v22 offset0:12 offset1:77
	ds_write2_b32 v3, v25, v24 offset0:142 offset1:207
	v_bfe_u32 v3, v6, 2, 6
	v_lshlrev_b32_e32 v5, 4, v6
	v_and_b32_e32 v20, 48, v5
	v_lshl_or_b32 v4, v3, 2, v4
	v_mad_u32_u24 v16, v20, s0, v4
	s_waitcnt lgkmcnt(0)
	s_barrier
	ds_read2_b32 v[4:5], v16 offset1:65
	ds_read2_b32 v[6:7], v16 offset0:130 offset1:195
	v_add_u32_e32 v10, 0x400, v16
	v_add_u32_e32 v14, 0x800, v16
	ds_read2_b32 v[8:9], v10 offset0:4 offset1:69
	ds_read2_b32 v[10:11], v10 offset0:134 offset1:199
	ds_read2_b32 v[12:13], v14 offset0:8 offset1:73
	ds_read2_b32 v[14:15], v14 offset0:138 offset1:203
	v_add_u32_e32 v18, 0xc00, v16
	s_waitcnt lgkmcnt(5)
	v_cvt_pk_bf16_f32 v4, v4, v5
	s_waitcnt lgkmcnt(4)
	v_cvt_pk_bf16_f32 v5, v6, v7
	s_waitcnt lgkmcnt(3)
	v_cvt_pk_bf16_f32 v6, v8, v9
	s_waitcnt lgkmcnt(1)
	v_cvt_pk_bf16_f32 v8, v12, v13
	v_or_b32_e32 v12, v1, v3
	ds_read2_b32 v[16:17], v18 offset0:12 offset1:77
	ds_read2_b32 v[18:19], v18 offset0:142 offset1:207
	v_ashrrev_i32_e32 v13, 31, v12
	v_lshlrev_b64 v[12:13], 11, v[12:13]
	v_lshl_add_u64 v[12:13], s[46:47], 0, v[12:13]
	v_ashrrev_i32_e32 v3, 31, v2
	v_lshl_add_u64 v[12:13], v[2:3], 1, v[12:13]
	v_lshlrev_b32_e32 v2, 1, v20
	v_mov_b32_e32 v3, 0
	v_cvt_pk_bf16_f32 v7, v10, v11
	v_lshl_add_u64 v[12:13], v[12:13], 0, v[2:3]
	s_waitcnt lgkmcnt(2)
	v_cvt_pk_bf16_f32 v9, v14, v15
	s_waitcnt lgkmcnt(1)
	v_cvt_pk_bf16_f32 v10, v16, v17
	s_waitcnt lgkmcnt(0)
	v_cvt_pk_bf16_f32 v11, v18, v19
	global_store_dwordx4 v[12:13], v[4:7], off
	global_store_dwordx4 v[12:13], v[8:11], off offset:16
	s_nop 0
	v_mov_b32_e32 v6, v162
	s_barrier
	s_add_i32 s0, s3, 0xfffffb84
	v_ashrrev_i32_e32 v7, 8, v6
	v_add_u32_e32 v1, s0, v7
	v_ashrrev_i32_e32 v2, 31, v1
	v_lshrrev_b32_e32 v2, 28, v2
	v_add_u32_e32 v2, v1, v2
	v_ashrrev_i32_e32 v5, 4, v2
	v_and_b32_e32 v2, 0x3fffff0, v2
	v_and_b32_e32 v8, 63, v6
	v_sub_u32_e32 v2, v1, v2
	v_lshlrev_b32_e32 v1, 6, v5
	v_readlane_b32 s68, v247, 17
	v_readlane_b32 s8, v247, 1
	v_or_b32_e32 v4, v1, v8
	s_movk_i32 s0, 0x1600
	v_lshlrev_b32_e32 v9, 5, v5
	s_movk_i32 s4, 0x7f
	v_and_b32_e32 v5, 2, v5
	v_readlane_b32 s69, v247, 18
	v_readlane_b32 s23, v247, 16
	v_cmp_gt_i32_e64 s[0:1], s0, v4
	v_bfi_b32 v4, s4, v4, v9
	v_mov_b32_e32 v9, s69
	v_readlane_b32 s22, v247, 15
	v_mov_b32_e32 v10, s23
	v_cmp_eq_u32_e32 vcc, 0, v5
	v_mov_b32_e32 v5, s68
	v_lshlrev_b32_e32 v2, 6, v2
	v_cndmask_b32_e32 v13, v9, v10, vcc
	v_mov_b32_e32 v9, s22
	v_cndmask_b32_e32 v12, v5, v9, vcc
	v_lshrrev_b32_e32 v5, 2, v6
	v_and_b32_e32 v9, 48, v5
	v_ashrrev_i32_e32 v5, 31, v4
	v_or_b32_e32 v11, v2, v9
	v_lshl_add_u64 v[4:5], v[4:5], 2, v[12:13]
	v_mov_b32_e32 v10, 0
	v_readlane_b32 s70, v247, 19
	v_readlane_b32 s71, v247, 20
	v_readlane_b32 s72, v247, 21
	v_readlane_b32 s73, v247, 22
	v_readlane_b32 s74, v247, 23
	v_readlane_b32 s75, v247, 24
	v_readlane_b32 s76, v247, 25
	v_readlane_b32 s77, v247, 26
	v_readlane_b32 s78, v247, 27
	v_readlane_b32 s79, v247, 28
	v_readlane_b32 s80, v247, 29
	v_readlane_b32 s81, v247, 30
	v_readlane_b32 s82, v247, 31
	v_readlane_b32 s83, v247, 32
	v_readlane_b32 s9, v247, 2
	v_readlane_b32 s10, v247, 3
	v_readlane_b32 s11, v247, 4
	v_readlane_b32 s12, v247, 5
	v_readlane_b32 s13, v247, 6
	v_readlane_b32 s14, v247, 7
	v_readlane_b32 s15, v247, 8
	v_readlane_b32 s16, v247, 9
	v_readlane_b32 s17, v247, 10
	v_readlane_b32 s18, v247, 11
	v_readlane_b32 s19, v247, 12
	v_readlane_b32 s20, v247, 13
	v_readlane_b32 s21, v247, 14
	s_and_saveexec_b64 s[4:5], s[0:1]
	s_cbranch_execz .LBB0_159
	s_movk_i32 s8, 0xb00
	v_mul_lo_u32 v12, v11, s8
	v_ashrrev_i32_e32 v13, 31, v12
	v_lshl_add_u64 v[12:13], v[12:13], 2, v[4:5]
	global_load_dword v10, v[12:13], off nt

.LBB0_189:
	s_or_b64 exec, exec, s[4:5]
	v_mul_i32_i24_e32 v4, 0x4100, v7
	v_lshl_or_b32 v5, v8, 2, v4
	s_movk_i32 s0, 0x104
	v_mad_u32_u24 v5, v9, s0, v5
	s_waitcnt vmcnt(0)
	ds_write2_b32 v5, v10, v3 offset1:65
	ds_write2_b32 v5, v13, v12 offset0:130 offset1:195
	v_add_u32_e32 v3, 0x400, v5
	ds_write2_b32 v3, v15, v14 offset0:4 offset1:69
	ds_write2_b32 v3, v17, v16 offset0:134 offset1:199
	v_add_u32_e32 v3, 0x800, v5
	ds_write2_b32 v3, v19, v18 offset0:8 offset1:73
	ds_write2_b32 v3, v21, v20 offset0:138 offset1:203
	v_add_u32_e32 v3, 0xc00, v5
	ds_write2_b32 v3, v23, v22 offset0:12 offset1:77
	ds_write2_b32 v3, v25, v24 offset0:142 offset1:207
	v_bfe_u32 v3, v6, 2, 6
	v_lshlrev_b32_e32 v5, 4, v6
	v_and_b32_e32 v20, 48, v5
	v_lshl_or_b32 v4, v3, 2, v4
	v_mad_u32_u24 v16, v20, s0, v4
	s_waitcnt lgkmcnt(0)
	s_barrier
	ds_read2_b32 v[4:5], v16 offset1:65
	ds_read2_b32 v[6:7], v16 offset0:130 offset1:195
	v_add_u32_e32 v10, 0x400, v16
	v_add_u32_e32 v14, 0x800, v16
	ds_read2_b32 v[8:9], v10 offset0:4 offset1:69
	ds_read2_b32 v[10:11], v10 offset0:134 offset1:199
	ds_read2_b32 v[12:13], v14 offset0:8 offset1:73
	ds_read2_b32 v[14:15], v14 offset0:138 offset1:203
	v_add_u32_e32 v18, 0xc00, v16
	s_waitcnt lgkmcnt(5)
	v_cvt_pk_bf16_f32 v4, v4, v5
	s_waitcnt lgkmcnt(4)
	v_cvt_pk_bf16_f32 v5, v6, v7
	s_waitcnt lgkmcnt(3)
	v_cvt_pk_bf16_f32 v6, v8, v9
	s_waitcnt lgkmcnt(1)
	v_cvt_pk_bf16_f32 v8, v12, v13
	v_or_b32_e32 v12, v1, v3
	ds_read2_b32 v[16:17], v18 offset0:12 offset1:77
	ds_read2_b32 v[18:19], v18 offset0:142 offset1:207
	v_ashrrev_i32_e32 v13, 31, v12
	v_lshlrev_b64 v[12:13], 11, v[12:13]
	v_lshl_add_u64 v[12:13], s[46:47], 0, v[12:13]
	v_ashrrev_i32_e32 v3, 31, v2
	v_lshl_add_u64 v[12:13], v[2:3], 1, v[12:13]
	v_lshlrev_b32_e32 v2, 1, v20
	v_mov_b32_e32 v3, 0
	v_cvt_pk_bf16_f32 v7, v10, v11
	v_lshl_add_u64 v[12:13], v[12:13], 0, v[2:3]
	s_waitcnt lgkmcnt(2)
	v_cvt_pk_bf16_f32 v9, v14, v15
	s_waitcnt lgkmcnt(1)
	v_cvt_pk_bf16_f32 v10, v16, v17
	s_waitcnt lgkmcnt(0)
	v_cvt_pk_bf16_f32 v11, v18, v19
	global_store_dwordx4 v[12:13], v[4:7], off
	global_store_dwordx4 v[12:13], v[8:11], off offset:16
	s_nop 0
	v_mov_b32_e32 v6, v162
	s_barrier
	s_add_i32 s0, s3, 0xfffffb86
	v_ashrrev_i32_e32 v7, 8, v6
	v_add_u32_e32 v1, s0, v7
	v_ashrrev_i32_e32 v2, 31, v1
	v_lshrrev_b32_e32 v2, 28, v2
	v_add_u32_e32 v2, v1, v2
	v_ashrrev_i32_e32 v5, 4, v2
	v_and_b32_e32 v2, 0x3fffff0, v2
	v_and_b32_e32 v8, 63, v6
	v_sub_u32_e32 v2, v1, v2
	v_lshlrev_b32_e32 v1, 6, v5
	v_readlane_b32 s68, v247, 17
	v_readlane_b32 s8, v247, 1
	v_or_b32_e32 v4, v1, v8
	s_movk_i32 s0, 0x1600
	v_lshlrev_b32_e32 v9, 5, v5
	s_movk_i32 s4, 0x7f
	v_and_b32_e32 v5, 2, v5
	v_readlane_b32 s69, v247, 18
	v_readlane_b32 s23, v247, 16
	v_cmp_gt_i32_e64 s[0:1], s0, v4
	v_bfi_b32 v4, s4, v4, v9
	v_mov_b32_e32 v9, s69
	v_readlane_b32 s22, v247, 15
	v_mov_b32_e32 v10, s23
	v_cmp_eq_u32_e32 vcc, 0, v5
	v_mov_b32_e32 v5, s68
	v_lshlrev_b32_e32 v2, 6, v2
	v_cndmask_b32_e32 v13, v9, v10, vcc
	v_mov_b32_e32 v9, s22
	v_cndmask_b32_e32 v12, v5, v9, vcc
	v_lshrrev_b32_e32 v5, 2, v6
	v_and_b32_e32 v9, 48, v5
	v_ashrrev_i32_e32 v5, 31, v4
	v_or_b32_e32 v11, v2, v9
	v_lshl_add_u64 v[4:5], v[4:5], 2, v[12:13]
	v_mov_b32_e32 v10, 0
	v_readlane_b32 s70, v247, 19
	v_readlane_b32 s71, v247, 20
	v_readlane_b32 s72, v247, 21
	v_readlane_b32 s73, v247, 22
	v_readlane_b32 s74, v247, 23
	v_readlane_b32 s75, v247, 24
	v_readlane_b32 s76, v247, 25
	v_readlane_b32 s77, v247, 26
	v_readlane_b32 s78, v247, 27
	v_readlane_b32 s79, v247, 28
	v_readlane_b32 s80, v247, 29
	v_readlane_b32 s81, v247, 30
	v_readlane_b32 s82, v247, 31
	v_readlane_b32 s83, v247, 32
	v_readlane_b32 s9, v247, 2
	v_readlane_b32 s10, v247, 3
	v_readlane_b32 s11, v247, 4
	v_readlane_b32 s12, v247, 5
	v_readlane_b32 s13, v247, 6
	v_readlane_b32 s14, v247, 7
	v_readlane_b32 s15, v247, 8
	v_readlane_b32 s16, v247, 9
	v_readlane_b32 s17, v247, 10
	v_readlane_b32 s18, v247, 11
	v_readlane_b32 s19, v247, 12
	v_readlane_b32 s20, v247, 13
	v_readlane_b32 s21, v247, 14
	s_and_saveexec_b64 s[4:5], s[0:1]
	s_cbranch_execz .LBB0_191
	s_movk_i32 s8, 0xb00
	v_mul_lo_u32 v12, v11, s8
	v_ashrrev_i32_e32 v13, 31, v12
	v_lshl_add_u64 v[12:13], v[12:13], 2, v[4:5]
	global_load_dword v10, v[12:13], off nt

.LBB0_221:
	s_or_b64 exec, exec, s[4:5]
	v_mul_i32_i24_e32 v4, 0x4100, v7
	v_lshl_or_b32 v5, v8, 2, v4
	s_movk_i32 s0, 0x104
	v_mad_u32_u24 v5, v9, s0, v5
	s_waitcnt vmcnt(0)
	ds_write2_b32 v5, v10, v3 offset1:65
	ds_write2_b32 v5, v13, v12 offset0:130 offset1:195
	v_add_u32_e32 v3, 0x400, v5
	ds_write2_b32 v3, v15, v14 offset0:4 offset1:69
	ds_write2_b32 v3, v17, v16 offset0:134 offset1:199
	v_add_u32_e32 v3, 0x800, v5
	ds_write2_b32 v3, v19, v18 offset0:8 offset1:73
	ds_write2_b32 v3, v21, v20 offset0:138 offset1:203
	v_add_u32_e32 v3, 0xc00, v5
	ds_write2_b32 v3, v23, v22 offset0:12 offset1:77
	ds_write2_b32 v3, v25, v24 offset0:142 offset1:207
	v_bfe_u32 v3, v6, 2, 6
	v_lshlrev_b32_e32 v5, 4, v6
	v_and_b32_e32 v20, 48, v5
	v_lshl_or_b32 v4, v3, 2, v4
	v_mad_u32_u24 v16, v20, s0, v4
	s_waitcnt lgkmcnt(0)
	s_barrier
	ds_read2_b32 v[4:5], v16 offset1:65
	ds_read2_b32 v[6:7], v16 offset0:130 offset1:195
	v_add_u32_e32 v10, 0x400, v16
	v_add_u32_e32 v14, 0x800, v16
	ds_read2_b32 v[8:9], v10 offset0:4 offset1:69
	ds_read2_b32 v[10:11], v10 offset0:134 offset1:199
	ds_read2_b32 v[12:13], v14 offset0:8 offset1:73
	ds_read2_b32 v[14:15], v14 offset0:138 offset1:203
	v_add_u32_e32 v18, 0xc00, v16
	s_waitcnt lgkmcnt(5)
	v_cvt_pk_bf16_f32 v4, v4, v5
	s_waitcnt lgkmcnt(4)
	v_cvt_pk_bf16_f32 v5, v6, v7
	s_waitcnt lgkmcnt(3)
	v_cvt_pk_bf16_f32 v6, v8, v9
	s_waitcnt lgkmcnt(1)
	v_cvt_pk_bf16_f32 v8, v12, v13
	v_or_b32_e32 v12, v1, v3
	ds_read2_b32 v[16:17], v18 offset0:12 offset1:77
	ds_read2_b32 v[18:19], v18 offset0:142 offset1:207
	v_ashrrev_i32_e32 v13, 31, v12
	v_lshlrev_b64 v[12:13], 11, v[12:13]
	v_lshl_add_u64 v[12:13], s[46:47], 0, v[12:13]
	v_ashrrev_i32_e32 v3, 31, v2
	v_lshl_add_u64 v[12:13], v[2:3], 1, v[12:13]
	v_lshlrev_b32_e32 v2, 1, v20
	v_mov_b32_e32 v3, 0
	v_cvt_pk_bf16_f32 v7, v10, v11
	v_lshl_add_u64 v[12:13], v[12:13], 0, v[2:3]
	s_waitcnt lgkmcnt(2)
	v_cvt_pk_bf16_f32 v9, v14, v15
	s_waitcnt lgkmcnt(1)
	v_cvt_pk_bf16_f32 v10, v16, v17
	s_waitcnt lgkmcnt(0)
	v_cvt_pk_bf16_f32 v11, v18, v19
	global_store_dwordx4 v[12:13], v[4:7], off
	global_store_dwordx4 v[12:13], v[8:11], off offset:16
	s_nop 0
	v_mov_b32_e32 v6, v162
	s_barrier
	s_addk_i32 s3, 0xfb88
	v_ashrrev_i32_e32 v7, 8, v6
	v_add_u32_e32 v1, s3, v7
	v_ashrrev_i32_e32 v2, 31, v1
	v_lshrrev_b32_e32 v2, 28, v2
	v_add_u32_e32 v2, v1, v2
	v_ashrrev_i32_e32 v5, 4, v2
	v_and_b32_e32 v2, 0x3fffff0, v2
	v_and_b32_e32 v8, 63, v6
	v_sub_u32_e32 v2, v1, v2
	v_lshlrev_b32_e32 v1, 6, v5
	v_readlane_b32 s68, v247, 17
	v_readlane_b32 s8, v247, 1
	v_or_b32_e32 v4, v1, v8
	s_movk_i32 s0, 0x1600
	v_lshlrev_b32_e32 v9, 5, v5
	s_movk_i32 s3, 0x7f
	v_and_b32_e32 v5, 2, v5
	v_readlane_b32 s69, v247, 18
	v_readlane_b32 s23, v247, 16
	v_cmp_gt_i32_e64 s[0:1], s0, v4
	v_bfi_b32 v4, s3, v4, v9
	v_mov_b32_e32 v9, s69
	v_readlane_b32 s22, v247, 15
	v_mov_b32_e32 v10, s23
	v_cmp_eq_u32_e32 vcc, 0, v5
	v_mov_b32_e32 v5, s68
	v_lshlrev_b32_e32 v2, 6, v2
	v_cndmask_b32_e32 v13, v9, v10, vcc
	v_mov_b32_e32 v9, s22
	v_cndmask_b32_e32 v12, v5, v9, vcc
	v_lshrrev_b32_e32 v5, 2, v6
	v_and_b32_e32 v9, 48, v5
	v_ashrrev_i32_e32 v5, 31, v4
	v_or_b32_e32 v11, v2, v9
	v_lshl_add_u64 v[4:5], v[4:5], 2, v[12:13]
	v_mov_b32_e32 v10, 0
	v_readlane_b32 s70, v247, 19
	v_readlane_b32 s71, v247, 20
	v_readlane_b32 s72, v247, 21
	v_readlane_b32 s73, v247, 22
	v_readlane_b32 s74, v247, 23
	v_readlane_b32 s75, v247, 24
	v_readlane_b32 s76, v247, 25
	v_readlane_b32 s77, v247, 26
	v_readlane_b32 s78, v247, 27
	v_readlane_b32 s79, v247, 28
	v_readlane_b32 s80, v247, 29
	v_readlane_b32 s81, v247, 30
	v_readlane_b32 s82, v247, 31
	v_readlane_b32 s83, v247, 32
	v_readlane_b32 s9, v247, 2
	v_readlane_b32 s10, v247, 3
	v_readlane_b32 s11, v247, 4
	v_readlane_b32 s12, v247, 5
	v_readlane_b32 s13, v247, 6
	v_readlane_b32 s14, v247, 7
	v_readlane_b32 s15, v247, 8
	v_readlane_b32 s16, v247, 9
	v_readlane_b32 s17, v247, 10
	v_readlane_b32 s18, v247, 11
	v_readlane_b32 s19, v247, 12
	v_readlane_b32 s20, v247, 13
	v_readlane_b32 s21, v247, 14
	s_and_saveexec_b64 s[4:5], s[0:1]
	s_cbranch_execz .LBB0_223
	s_movk_i32 s3, 0xb00
	v_mul_lo_u32 v12, v11, s3
	v_ashrrev_i32_e32 v13, 31, v12
	v_lshl_add_u64 v[12:13], v[12:13], 2, v[4:5]
	global_load_dword v10, v[12:13], off nt
.LBB0_223:
	s_or_b64 exec, exec, s[4:5]
	s_and_saveexec_b64 s[4:5], s[0:1]
	s_cbranch_execz .LBB0_225
	s_movk_i32 s3, 0xb00
	v_mul_lo_u32 v12, v11, s3
	v_ashrrev_i32_e32 v13, 31, v12
	v_lshl_add_u64 v[12:13], v[12:13], 2, v[4:5]
	v_add_co_u32_e32 v12, vcc, 0x2000, v12
	s_nop 1
	v_addc_co_u32_e32 v13, vcc, 0, v13, vcc
	global_load_dword v3, v[12:13], off offset:3072 nt
.LBB0_225:
	s_or_b64 exec, exec, s[4:5]
	v_mov_b32_e32 v12, 0
	v_mov_b32_e32 v13, 0
	s_and_saveexec_b64 s[4:5], s[0:1]
	s_cbranch_execz .LBB0_227
	s_movk_i32 s3, 0xb00
	v_mul_lo_u32 v14, v11, s3
	v_ashrrev_i32_e32 v15, 31, v14
	v_lshl_add_u64 v[14:15], v[14:15], 2, v[4:5]
	v_add_co_u32_e32 v14, vcc, 0x5000, v14
	s_nop 1
	v_addc_co_u32_e32 v15, vcc, 0, v15, vcc
	global_load_dword v13, v[14:15], off offset:2048 nt
.LBB0_227:
	s_or_b64 exec, exec, s[4:5]
	s_and_saveexec_b64 s[4:5], s[0:1]
	s_cbranch_execz .LBB0_229
	s_movk_i32 s3, 0xb00
	v_mul_lo_u32 v14, v11, s3
	v_ashrrev_i32_e32 v15, 31, v14
	v_lshl_add_u64 v[14:15], v[14:15], 2, v[4:5]
	v_add_co_u32_e32 v14, vcc, 0x8000, v14
	s_nop 1
	v_addc_co_u32_e32 v15, vcc, 0, v15, vcc
	global_load_dword v12, v[14:15], off offset:1024 nt
.LBB0_229:
	s_or_b64 exec, exec, s[4:5]
	v_mov_b32_e32 v14, 0
	v_mov_b32_e32 v15, 0
	s_and_saveexec_b64 s[4:5], s[0:1]
	s_cbranch_execz .LBB0_231
	s_movk_i32 s3, 0xb00
	v_mul_lo_u32 v16, v11, s3
	v_ashrrev_i32_e32 v17, 31, v16
	v_lshl_add_u64 v[16:17], v[16:17], 2, v[4:5]
	v_add_co_u32_e32 v16, vcc, 0xb000, v16
	s_nop 1
	v_addc_co_u32_e32 v17, vcc, 0, v17, vcc
	global_load_dword v15, v[16:17], off nt
.LBB0_231:
	s_or_b64 exec, exec, s[4:5]
	s_and_saveexec_b64 s[4:5], s[0:1]
	s_cbranch_execz .LBB0_233
	s_movk_i32 s3, 0xb00
	v_mul_lo_u32 v16, v11, s3
	v_ashrrev_i32_e32 v17, 31, v16
	v_lshl_add_u64 v[16:17], v[16:17], 2, v[4:5]
	v_add_co_u32_e32 v16, vcc, 0xd000, v16
	s_nop 1
	v_addc_co_u32_e32 v17, vcc, 0, v17, vcc
	global_load_dword v14, v[16:17], off offset:3072 nt
.LBB0_233:
	s_or_b64 exec, exec, s[4:5]
	v_mov_b32_e32 v16, 0
	v_mov_b32_e32 v17, 0
	s_and_saveexec_b64 s[4:5], s[0:1]
	s_cbranch_execz .LBB0_235
	s_movk_i32 s3, 0xb00
	v_mul_lo_u32 v18, v11, s3
	v_ashrrev_i32_e32 v19, 31, v18
	v_lshl_add_u64 v[18:19], v[18:19], 2, v[4:5]
	v_add_co_u32_e32 v18, vcc, 0x10000, v18
	s_nop 1
	v_addc_co_u32_e32 v19, vcc, 0, v19, vcc
	global_load_dword v17, v[18:19], off offset:2048 nt
.LBB0_235:
	s_or_b64 exec, exec, s[4:5]
	s_and_saveexec_b64 s[4:5], s[0:1]
	s_cbranch_execz .LBB0_237
	s_movk_i32 s3, 0xb00
	v_mul_lo_u32 v18, v11, s3
	v_ashrrev_i32_e32 v19, 31, v18
	v_lshl_add_u64 v[18:19], v[18:19], 2, v[4:5]
	v_add_co_u32_e32 v18, vcc, 0x13000, v18
	s_nop 1
	v_addc_co_u32_e32 v19, vcc, 0, v19, vcc
	global_load_dword v16, v[18:19], off offset:1024 nt
.LBB0_237:
	s_or_b64 exec, exec, s[4:5]
	v_mov_b32_e32 v18, 0
	v_mov_b32_e32 v19, 0
	s_and_saveexec_b64 s[4:5], s[0:1]
	s_cbranch_execz .LBB0_239
	s_movk_i32 s3, 0xb00
	v_mul_lo_u32 v20, v11, s3
	v_ashrrev_i32_e32 v21, 31, v20
	v_lshl_add_u64 v[20:21], v[20:21], 2, v[4:5]
	v_add_co_u32_e32 v20, vcc, 0x16000, v20
	s_nop 1
	v_addc_co_u32_e32 v21, vcc, 0, v21, vcc
	global_load_dword v19, v[20:21], off nt
.LBB0_239:
	s_or_b64 exec, exec, s[4:5]
	s_and_saveexec_b64 s[4:5], s[0:1]
	s_cbranch_execz .LBB0_241
	s_movk_i32 s3, 0xb00
	v_mul_lo_u32 v20, v11, s3
	v_ashrrev_i32_e32 v21, 31, v20
	v_lshl_add_u64 v[20:21], v[20:21], 2, v[4:5]
	v_add_co_u32_e32 v20, vcc, 0x18000, v20
	s_nop 1
	v_addc_co_u32_e32 v21, vcc, 0, v21, vcc
	global_load_dword v18, v[20:21], off offset:3072 nt
.LBB0_241:
	s_or_b64 exec, exec, s[4:5]
	v_mov_b32_e32 v20, 0
	v_mov_b32_e32 v21, 0
	s_and_saveexec_b64 s[4:5], s[0:1]
	s_cbranch_execz .LBB0_243
	s_movk_i32 s3, 0xb00
	v_mul_lo_u32 v22, v11, s3
	v_ashrrev_i32_e32 v23, 31, v22
	v_lshl_add_u64 v[22:23], v[22:23], 2, v[4:5]
	v_add_co_u32_e32 v22, vcc, 0x1b000, v22
	s_nop 1
	v_addc_co_u32_e32 v23, vcc, 0, v23, vcc
	global_load_dword v21, v[22:23], off offset:2048 nt
.LBB0_243:
	s_or_b64 exec, exec, s[4:5]
	s_and_saveexec_b64 s[4:5], s[0:1]
	s_cbranch_execz .LBB0_245
	s_movk_i32 s3, 0xb00
	v_mul_lo_u32 v22, v11, s3
	v_ashrrev_i32_e32 v23, 31, v22
	v_lshl_add_u64 v[22:23], v[22:23], 2, v[4:5]
	v_add_co_u32_e32 v22, vcc, 0x1e000, v22
	s_nop 1
	v_addc_co_u32_e32 v23, vcc, 0, v23, vcc
	global_load_dword v20, v[22:23], off offset:1024 nt
.LBB0_245:
	s_or_b64 exec, exec, s[4:5]
	v_mov_b32_e32 v22, 0
	v_mov_b32_e32 v23, 0
	s_and_saveexec_b64 s[4:5], s[0:1]
	s_cbranch_execz .LBB0_247
	s_movk_i32 s3, 0xb00
	v_mul_lo_u32 v24, v11, s3
	v_ashrrev_i32_e32 v25, 31, v24
	v_lshl_add_u64 v[24:25], v[24:25], 2, v[4:5]
	v_add_co_u32_e32 v24, vcc, 0x21000, v24
	s_nop 1
	v_addc_co_u32_e32 v25, vcc, 0, v25, vcc
	global_load_dword v23, v[24:25], off nt
.LBB0_247:
	s_or_b64 exec, exec, s[4:5]
	s_and_saveexec_b64 s[4:5], s[0:1]
	s_cbranch_execz .LBB0_249
	s_movk_i32 s3, 0xb00
	v_mul_lo_u32 v24, v11, s3
	v_ashrrev_i32_e32 v25, 31, v24
	v_lshl_add_u64 v[24:25], v[24:25], 2, v[4:5]
	v_add_co_u32_e32 v24, vcc, 0x23000, v24
	s_nop 1
	v_addc_co_u32_e32 v25, vcc, 0, v25, vcc
	global_load_dword v22, v[24:25], off offset:3072 nt
.LBB0_249:
	s_or_b64 exec, exec, s[4:5]
	v_mov_b32_e32 v24, 0
	v_mov_b32_e32 v25, 0
	s_and_saveexec_b64 s[4:5], s[0:1]
	s_cbranch_execz .LBB0_251
	s_movk_i32 s3, 0xb00
	v_mul_lo_u32 v26, v11, s3
	v_ashrrev_i32_e32 v27, 31, v26
	v_lshl_add_u64 v[26:27], v[26:27], 2, v[4:5]
	v_add_co_u32_e32 v26, vcc, 0x26000, v26
	s_nop 1
	v_addc_co_u32_e32 v27, vcc, 0, v27, vcc
	global_load_dword v25, v[26:27], off offset:2048 nt

.LBB0_254:
	s_and_b64 vcc, exec, s[0:1]
	s_cbranch_vccz .LBB0_293
	v_mov_b32_e32 v76, v162
	v_readlane_b32 s8, v247, 1
	v_and_b32_e32 v2, 0x3ff, v76
	v_readlane_b32 s14, v247, 7
	v_readlane_b32 s15, v247, 8
	v_lshlrev_b32_e32 v2, 2, v2
	v_mov_b32_e32 v3, 0
	s_movk_i32 s0, 0x4000
	v_ashrrev_i32_e32 v77, 31, v76
	v_readlane_b32 s10, v247, 3
	v_readlane_b32 s11, v247, 4
	v_lshl_add_u64 v[6:7], s[14:15], 0, v[2:3]
	v_add_u32_e32 v2, 0x200, v76
	v_lshl_add_u64 v[4:5], v[76:77], 2, s[10:11]
	v_cmp_gt_i32_e32 vcc, s0, v76
	v_and_b32_e32 v2, 0x3ff, v2
	s_movk_i32 s1, 0x3e00
	v_cndmask_b32_e32 v9, v7, v5, vcc
	v_cndmask_b32_e32 v8, v6, v4, vcc
	s_mov_b64 s[4:5], 0x800
	v_lshlrev_b32_e32 v2, 2, v2
	global_load_dword v12, v[8:9], off nt
	v_lshl_add_u64 v[8:9], v[4:5], 0, s[4:5]
	v_lshl_add_u64 v[10:11], s[14:15], 0, v[2:3]
	v_cmp_gt_i32_e32 vcc, s1, v76
	s_movk_i32 s1, 0x3c00
	s_mov_b64 s[4:5], 0x1000
	v_cndmask_b32_e32 v9, v11, v9, vcc
	v_cndmask_b32_e32 v8, v10, v8, vcc
	global_load_dword v13, v[8:9], off nt
	v_lshl_add_u64 v[8:9], v[4:5], 0, s[4:5]
	v_cmp_gt_i32_e32 vcc, s1, v76
	v_add_u32_e32 v2, 0x600, v76
	v_and_b32_e32 v2, 0x3ff, v2
	v_cndmask_b32_e32 v9, v7, v9, vcc
	v_cndmask_b32_e32 v8, v6, v8, vcc
	global_load_dword v14, v[8:9], off nt
	s_movk_i32 s3, 0x3a00
	s_mov_b64 s[4:5], 0x1800
	v_lshlrev_b32_e32 v2, 2, v2
	v_lshl_add_u64 v[8:9], v[4:5], 0, s[4:5]
	v_lshl_add_u64 v[10:11], s[14:15], 0, v[2:3]
	v_cmp_gt_i32_e32 vcc, s3, v76
	s_movk_i32 s3, 0x3800
	s_mov_b64 s[4:5], 0x2000
	v_cndmask_b32_e32 v9, v11, v9, vcc
	v_cndmask_b32_e32 v8, v10, v8, vcc
	global_load_dword v15, v[8:9], off nt
	v_lshl_add_u64 v[8:9], v[4:5], 0, s[4:5]
	v_cmp_gt_i32_e32 vcc, s3, v76
	v_add_u32_e32 v2, 0xa00, v76
	v_and_b32_e32 v2, 0x3ff, v2
	v_cndmask_b32_e32 v9, v7, v9, vcc
	v_cndmask_b32_e32 v8, v6, v8, vcc
	global_load_dword v16, v[8:9], off nt
	s_movk_i32 s8, 0x3600
	s_mov_b64 s[4:5], 0x2800
	v_lshlrev_b32_e32 v2, 2, v2
	v_lshl_add_u64 v[8:9], v[4:5], 0, s[4:5]
	v_lshl_add_u64 v[10:11], s[14:15], 0, v[2:3]
	v_cmp_gt_i32_e32 vcc, s8, v76
	s_movk_i32 s8, 0x3400
	s_mov_b64 s[4:5], 0x3000
	v_cndmask_b32_e32 v9, v11, v9, vcc
	v_cndmask_b32_e32 v8, v10, v8, vcc
	global_load_dword v17, v[8:9], off nt
	v_lshl_add_u64 v[8:9], v[4:5], 0, s[4:5]
	v_cmp_gt_i32_e32 vcc, s8, v76
	v_add_u32_e32 v2, 0xe00, v76
	v_readlane_b32 s9, v247, 2
	v_cndmask_b32_e32 v9, v7, v9, vcc
	v_cndmask_b32_e32 v8, v6, v8, vcc
	global_load_dword v18, v[8:9], off nt
	v_and_b32_e32 v2, 0x3ff, v2
	s_movk_i32 s5, 0x3200
	s_mov_b64 s[8:9], 0x3800
	v_lshlrev_b32_e32 v2, 2, v2
	v_lshl_add_u64 v[8:9], v[4:5], 0, s[8:9]
	v_lshl_add_u64 v[10:11], s[14:15], 0, v[2:3]
	v_cmp_gt_i32_e32 vcc, s5, v76
	s_movk_i32 s5, 0x3000
	s_mov_b64 s[8:9], 0x4000
	v_cndmask_b32_e32 v9, v11, v9, vcc
	v_cndmask_b32_e32 v8, v10, v8, vcc
	v_add_u32_e32 v2, 0x1200, v76
	global_load_dword v19, v[8:9], off nt
	v_lshl_add_u64 v[8:9], v[4:5], 0, s[8:9]
	v_cmp_gt_i32_e32 vcc, s5, v76
	v_and_b32_e32 v2, 0x3ff, v2
	s_movk_i32 s10, 0x2e00
	v_cndmask_b32_e32 v9, v7, v9, vcc
	v_cndmask_b32_e32 v8, v6, v8, vcc
	s_mov_b64 s[8:9], 0x4800
	v_lshlrev_b32_e32 v2, 2, v2
	global_load_dword v20, v[8:9], off nt
	v_lshl_add_u64 v[8:9], v[4:5], 0, s[8:9]
	v_lshl_add_u64 v[10:11], s[14:15], 0, v[2:3]
	v_cmp_gt_i32_e32 vcc, s10, v76
	s_movk_i32 s10, 0x2c00
	s_mov_b64 s[8:9], 0x5000
	v_cndmask_b32_e32 v9, v11, v9, vcc
	v_cndmask_b32_e32 v8, v10, v8, vcc
	v_add_u32_e32 v2, 0x1600, v76
	global_load_dword v21, v[8:9], off nt
	v_lshl_add_u64 v[8:9], v[4:5], 0, s[8:9]
	v_cmp_gt_i32_e32 vcc, s10, v76
	v_and_b32_e32 v2, 0x3ff, v2
	s_movk_i32 s11, 0x2a00
	v_cndmask_b32_e32 v9, v7, v9, vcc
	v_cndmask_b32_e32 v8, v6, v8, vcc
	s_mov_b64 s[8:9], 0x5800
	v_lshlrev_b32_e32 v2, 2, v2
	global_load_dword v22, v[8:9], off nt
	v_lshl_add_u64 v[8:9], v[4:5], 0, s[8:9]
	v_lshl_add_u64 v[10:11], s[14:15], 0, v[2:3]
	v_cmp_gt_i32_e32 vcc, s11, v76
	s_movk_i32 s11, 0x2800
	s_mov_b64 s[8:9], 0x6000
	v_cndmask_b32_e32 v9, v11, v9, vcc
	v_cndmask_b32_e32 v8, v10, v8, vcc
	v_add_u32_e32 v2, 0x1a00, v76
	v_readlane_b32 s12, v247, 5
	global_load_dword v23, v[8:9], off nt
	v_lshl_add_u64 v[8:9], v[4:5], 0, s[8:9]
	v_cmp_gt_i32_e32 vcc, s11, v76
	v_and_b32_e32 v2, 0x3ff, v2
	s_movk_i32 s12, 0x2600
	v_cndmask_b32_e32 v9, v7, v9, vcc
	v_cndmask_b32_e32 v8, v6, v8, vcc
	s_mov_b64 s[8:9], 0x6800
	v_lshlrev_b32_e32 v2, 2, v2
	global_load_dword v24, v[8:9], off nt
	v_lshl_add_u64 v[8:9], v[4:5], 0, s[8:9]
	v_lshl_add_u64 v[10:11], s[14:15], 0, v[2:3]
	v_cmp_gt_i32_e32 vcc, s12, v76
	s_movk_i32 s12, 0x2400
	s_mov_b64 s[8:9], 0x7000
	v_cndmask_b32_e32 v9, v11, v9, vcc
	v_cndmask_b32_e32 v8, v10, v8, vcc
	v_add_u32_e32 v2, 0x1e00, v76
	v_readlane_b32 s13, v247, 6
	global_load_dword v25, v[8:9], off nt
	v_lshl_add_u64 v[8:9], v[4:5], 0, s[8:9]
	v_cmp_gt_i32_e32 vcc, s12, v76
	v_and_b32_e32 v2, 0x3ff, v2
	s_movk_i32 s13, 0x2200
	v_cndmask_b32_e32 v9, v7, v9, vcc
	v_cndmask_b32_e32 v8, v6, v8, vcc
	s_mov_b64 s[8:9], 0x7800
	v_lshlrev_b32_e32 v2, 2, v2
	global_load_dword v26, v[8:9], off nt
	v_lshl_add_u64 v[8:9], v[4:5], 0, s[8:9]
	v_lshl_add_u64 v[10:11], s[14:15], 0, v[2:3]
	v_cmp_gt_i32_e32 vcc, s13, v76
	s_movk_i32 s13, 0x2000
	s_mov_b64 s[8:9], 0x8000
	v_cndmask_b32_e32 v9, v11, v9, vcc
	v_cndmask_b32_e32 v8, v10, v8, vcc
	v_add_u32_e32 v2, 0x2200, v76
	global_load_dword v27, v[8:9], off nt
	v_lshl_add_u64 v[8:9], v[4:5], 0, s[8:9]
	v_cmp_gt_i32_e32 vcc, s13, v76
	v_and_b32_e32 v2, 0x3ff, v2
	s_movk_i32 s12, 0x1e00
	v_cndmask_b32_e32 v9, v7, v9, vcc
	v_cndmask_b32_e32 v8, v6, v8, vcc
	s_mov_b64 s[8:9], 0x8800
	v_lshlrev_b32_e32 v2, 2, v2
	global_load_dword v28, v[8:9], off nt
	v_lshl_add_u64 v[8:9], v[4:5], 0, s[8:9]
	v_lshl_add_u64 v[10:11], s[14:15], 0, v[2:3]
	v_cmp_gt_i32_e32 vcc, s12, v76
	s_movk_i32 s12, 0x1c00
	s_mov_b64 s[8:9], 0x9000
	v_cndmask_b32_e32 v9, v11, v9, vcc
	v_cndmask_b32_e32 v8, v10, v8, vcc
	v_add_u32_e32 v2, 0x2600, v76
	global_load_dword v29, v[8:9], off nt
	v_lshl_add_u64 v[8:9], v[4:5], 0, s[8:9]
	v_cmp_gt_i32_e32 vcc, s12, v76
	v_and_b32_e32 v2, 0x3ff, v2
	s_movk_i32 s11, 0x1a00
	v_cndmask_b32_e32 v9, v7, v9, vcc
	v_cndmask_b32_e32 v8, v6, v8, vcc
	s_mov_b64 s[8:9], 0x9800
	v_lshlrev_b32_e32 v2, 2, v2
	global_load_dword v30, v[8:9], off nt
	v_lshl_add_u64 v[8:9], v[4:5], 0, s[8:9]
	v_lshl_add_u64 v[10:11], s[14:15], 0, v[2:3]
	v_cmp_gt_i32_e32 vcc, s11, v76
	s_movk_i32 s11, 0x1800
	s_mov_b64 s[8:9], 0xa000
	v_cndmask_b32_e32 v9, v11, v9, vcc
	v_cndmask_b32_e32 v8, v10, v8, vcc
	v_add_u32_e32 v2, 0x2a00, v76
	global_load_dword v31, v[8:9], off nt
	v_lshl_add_u64 v[8:9], v[4:5], 0, s[8:9]
	v_cmp_gt_i32_e32 vcc, s11, v76
	v_and_b32_e32 v2, 0x3ff, v2
	s_movk_i32 s10, 0x1600
	v_cndmask_b32_e32 v9, v7, v9, vcc
	v_cndmask_b32_e32 v8, v6, v8, vcc
	s_mov_b64 s[8:9], 0xa800
	v_lshlrev_b32_e32 v2, 2, v2
	global_load_dword v32, v[8:9], off nt
	v_lshl_add_u64 v[8:9], v[4:5], 0, s[8:9]
	v_lshl_add_u64 v[10:11], s[14:15], 0, v[2:3]
	v_cmp_gt_i32_e32 vcc, s10, v76
	s_movk_i32 s10, 0x1400
	s_mov_b64 s[8:9], 0xb000
	v_cndmask_b32_e32 v9, v11, v9, vcc
	v_cndmask_b32_e32 v8, v10, v8, vcc
	v_add_u32_e32 v2, 0x2e00, v76
	global_load_dword v33, v[8:9], off nt
	v_lshl_add_u64 v[8:9], v[4:5], 0, s[8:9]
	v_cmp_gt_i32_e32 vcc, s10, v76
	v_and_b32_e32 v2, 0x3ff, v2
	s_movk_i32 s5, 0x1200
	v_cndmask_b32_e32 v9, v7, v9, vcc
	v_cndmask_b32_e32 v8, v6, v8, vcc
	s_mov_b64 s[8:9], 0xb800
	v_lshlrev_b32_e32 v2, 2, v2
	global_load_dword v34, v[8:9], off nt
	v_lshl_add_u64 v[8:9], v[4:5], 0, s[8:9]
	v_lshl_add_u64 v[10:11], s[14:15], 0, v[2:3]
	v_cmp_gt_i32_e32 vcc, s5, v76
	s_movk_i32 s5, 0x1000
	s_mov_b64 s[8:9], 0xc000
	v_cndmask_b32_e32 v9, v11, v9, vcc
	v_cndmask_b32_e32 v8, v10, v8, vcc
	v_add_u32_e32 v2, 0x3200, v76
	global_load_dword v35, v[8:9], off nt
	v_lshl_add_u64 v[8:9], v[4:5], 0, s[8:9]
	v_cmp_gt_i32_e32 vcc, s5, v76
	v_and_b32_e32 v2, 0x3ff, v2
	s_movk_i32 s4, 0xe00
	v_cndmask_b32_e32 v9, v7, v9, vcc
	v_cndmask_b32_e32 v8, v6, v8, vcc
	s_mov_b64 s[8:9], 0xc800
	v_lshlrev_b32_e32 v2, 2, v2
	global_load_dword v36, v[8:9], off nt
	v_lshl_add_u64 v[8:9], v[4:5], 0, s[8:9]
	v_lshl_add_u64 v[10:11], s[14:15], 0, v[2:3]
	v_cmp_gt_i32_e32 vcc, s4, v76
	s_movk_i32 s8, 0xc00
	s_mov_b64 s[4:5], 0xd000
	v_cndmask_b32_e32 v9, v11, v9, vcc
	v_cndmask_b32_e32 v8, v10, v8, vcc
	v_add_u32_e32 v2, 0x3600, v76
	global_load_dword v37, v[8:9], off nt
	v_lshl_add_u64 v[8:9], v[4:5], 0, s[4:5]
	v_cmp_gt_i32_e32 vcc, s8, v76
	v_and_b32_e32 v2, 0x3ff, v2
	s_movk_i32 s3, 0xa00
	v_cndmask_b32_e32 v9, v7, v9, vcc
	v_cndmask_b32_e32 v8, v6, v8, vcc
	s_mov_b64 s[4:5], 0xd800
	v_lshlrev_b32_e32 v2, 2, v2
	global_load_dword v38, v[8:9], off nt
	v_lshl_add_u64 v[8:9], v[4:5], 0, s[4:5]
	v_lshl_add_u64 v[10:11], s[14:15], 0, v[2:3]
	v_cmp_gt_i32_e32 vcc, s3, v76
	s_movk_i32 s3, 0x800
	s_mov_b64 s[4:5], 0xe000
	v_cndmask_b32_e32 v9, v11, v9, vcc
	v_cndmask_b32_e32 v8, v10, v8, vcc
	v_add_u32_e32 v2, 0x3a00, v76
	global_load_dword v39, v[8:9], off nt
	v_lshl_add_u64 v[8:9], v[4:5], 0, s[4:5]
	v_cmp_gt_i32_e32 vcc, s3, v76
	v_and_b32_e32 v2, 0x3ff, v2
	s_movk_i32 s1, 0x600
	v_cndmask_b32_e32 v9, v7, v9, vcc
	v_cndmask_b32_e32 v8, v6, v8, vcc
	s_mov_b64 s[4:5], 0xe800
	v_lshlrev_b32_e32 v2, 2, v2
	global_load_dword v40, v[8:9], off nt
	v_lshl_add_u64 v[8:9], v[4:5], 0, s[4:5]
	v_lshl_add_u64 v[10:11], s[14:15], 0, v[2:3]
	v_cmp_gt_i32_e32 vcc, s1, v76
	s_movk_i32 s1, 0x400
	s_mov_b64 s[4:5], 0xf000
	v_cndmask_b32_e32 v9, v11, v9, vcc
	v_cndmask_b32_e32 v8, v10, v8, vcc
	v_add_u32_e32 v2, 0x3e00, v76
	global_load_dword v41, v[8:9], off nt
	v_lshl_add_u64 v[8:9], v[4:5], 0, s[4:5]
	v_cmp_gt_i32_e32 vcc, s1, v76
	v_and_b32_e32 v2, 0x3ff, v2
	s_movk_i32 s0, 0x200
	v_cndmask_b32_e32 v9, v7, v9, vcc
	v_cndmask_b32_e32 v8, v6, v8, vcc
	s_mov_b64 s[4:5], 0xf800
	v_lshlrev_b32_e32 v2, 2, v2
	global_load_dword v42, v[8:9], off nt
	v_lshl_add_u64 v[8:9], v[4:5], 0, s[4:5]
	v_lshl_add_u64 v[10:11], s[14:15], 0, v[2:3]
	v_cmp_gt_i32_e32 vcc, s0, v76
	s_mov_b64 s[0:1], 0x10000
	v_add_u32_e32 v2, 0x4200, v76
	v_cndmask_b32_e32 v9, v11, v9, vcc
	v_cndmask_b32_e32 v8, v10, v8, vcc
	global_load_dword v10, v[8:9], off nt
	v_lshl_add_u64 v[8:9], v[4:5], 0, s[0:1]
	v_cmp_gt_i32_e32 vcc, 0, v76
	v_and_b32_e32 v2, 0x3ff, v2
	s_movk_i32 s3, 0xfe00
	v_cndmask_b32_e32 v7, v7, v9, vcc
	v_cndmask_b32_e32 v6, v6, v8, vcc
	s_mov_b64 s[0:1], 0x10800
	v_lshlrev_b32_e32 v2, 2, v2
	global_load_dword v8, v[6:7], off nt
	v_lshl_add_u64 v[4:5], v[4:5], 0, s[0:1]
	v_lshl_add_u64 v[6:7], s[14:15], 0, v[2:3]
	v_cmp_gt_i32_e32 vcc, s3, v76
	s_waitcnt vmcnt(32)
	v_mul_f32_e32 v2, 0xbfb8aa3b, v12
	v_exp_f32_e32 v2, v2
	v_cndmask_b32_e32 v5, v7, v5, vcc
	v_cndmask_b32_e32 v4, v6, v4, vcc
	global_load_dword v4, v[4:5], off nt
	s_waitcnt vmcnt(32)
	v_mul_f32_e32 v5, 0xbfb8aa3b, v13
	v_exp_f32_e32 v5, v5
	s_waitcnt vmcnt(31)
	v_mul_f32_e32 v7, 0xbfb8aa3b, v14
	v_exp_f32_e32 v7, v7
	v_add_f32_e32 v2, 1.0, v2
	v_add_f32_e32 v5, 1.0, v5
	v_rcp_f32_e32 v2, v2
	v_rcp_f32_e32 v5, v5
	v_add_f32_e32 v7, 1.0, v7
	v_rcp_f32_e32 v7, v7
	v_lshlrev_b32_e32 v6, 2, v76
	v_mul_f32_e32 v2, v12, v2
	v_mul_f32_e32 v5, v13, v5
	s_waitcnt vmcnt(30)
	v_mul_f32_e32 v9, 0xbfb8aa3b, v15
	v_exp_f32_e32 v9, v9
	ds_write2st64_b32 v6, v2, v5 offset1:8
	v_mul_f32_e32 v5, v14, v7
	s_waitcnt vmcnt(29)
	v_mul_f32_e32 v7, 0xbfb8aa3b, v16
	v_exp_f32_e32 v7, v7
	v_add_f32_e32 v2, 1.0, v9
	v_rcp_f32_e32 v2, v2
	s_waitcnt vmcnt(28)
	v_mul_f32_e32 v9, 0xbfb8aa3b, v17
	v_add_f32_e32 v7, 1.0, v7
	v_rcp_f32_e32 v7, v7
	v_mul_f32_e32 v2, v15, v2
	v_exp_f32_e32 v9, v9
	ds_write2st64_b32 v6, v5, v2 offset0:16 offset1:24
	v_mul_f32_e32 v5, v16, v7
	s_waitcnt vmcnt(27)
	v_mul_f32_e32 v7, 0xbfb8aa3b, v18
	v_exp_f32_e32 v7, v7
	v_add_f32_e32 v2, 1.0, v9
	v_rcp_f32_e32 v2, v2
	s_waitcnt vmcnt(26)
	v_mul_f32_e32 v9, 0xbfb8aa3b, v19
	v_add_f32_e32 v7, 1.0, v7
	v_rcp_f32_e32 v7, v7
	v_mul_f32_e32 v2, v17, v2
	v_exp_f32_e32 v9, v9
	ds_write2st64_b32 v6, v5, v2 offset0:32 offset1:40
	v_mul_f32_e32 v5, v18, v7
	s_waitcnt vmcnt(25)
	v_mul_f32_e32 v7, 0xbfb8aa3b, v20
	v_exp_f32_e32 v7, v7
	v_add_f32_e32 v2, 1.0, v9
	v_rcp_f32_e32 v2, v2
	s_waitcnt vmcnt(24)
	v_mul_f32_e32 v9, 0xbfb8aa3b, v21
	v_add_f32_e32 v7, 1.0, v7
	v_rcp_f32_e32 v7, v7
	v_mul_f32_e32 v2, v19, v2
	v_exp_f32_e32 v9, v9
	ds_write2st64_b32 v6, v5, v2 offset0:48 offset1:56
	v_mul_f32_e32 v5, v20, v7
	s_waitcnt vmcnt(23)
	v_mul_f32_e32 v7, 0xbfb8aa3b, v22
	v_exp_f32_e32 v7, v7
	v_add_f32_e32 v2, 1.0, v9
	v_rcp_f32_e32 v2, v2
	s_waitcnt vmcnt(22)
	v_mul_f32_e32 v9, 0xbfb8aa3b, v23
	v_add_f32_e32 v7, 1.0, v7
	v_rcp_f32_e32 v7, v7
	v_mul_f32_e32 v2, v21, v2
	v_exp_f32_e32 v9, v9
	ds_write2st64_b32 v6, v5, v2 offset0:64 offset1:72
	v_mul_f32_e32 v5, v22, v7
	s_waitcnt vmcnt(21)
	v_mul_f32_e32 v7, 0xbfb8aa3b, v24
	v_exp_f32_e32 v7, v7
	v_add_f32_e32 v2, 1.0, v9
	v_rcp_f32_e32 v2, v2
	s_waitcnt vmcnt(20)
	v_mul_f32_e32 v9, 0xbfb8aa3b, v25
	v_add_f32_e32 v7, 1.0, v7
	v_rcp_f32_e32 v7, v7
	v_mul_f32_e32 v2, v23, v2
	v_exp_f32_e32 v9, v9
	ds_write2st64_b32 v6, v5, v2 offset0:80 offset1:88
	v_mul_f32_e32 v5, v24, v7
	s_waitcnt vmcnt(19)
	v_mul_f32_e32 v7, 0xbfb8aa3b, v26
	v_exp_f32_e32 v7, v7
	v_add_f32_e32 v2, 1.0, v9
	v_rcp_f32_e32 v2, v2
	s_waitcnt vmcnt(18)
	v_mul_f32_e32 v9, 0xbfb8aa3b, v27
	v_add_f32_e32 v7, 1.0, v7
	v_rcp_f32_e32 v7, v7
	v_mul_f32_e32 v2, v25, v2
	v_exp_f32_e32 v9, v9
	ds_write2st64_b32 v6, v5, v2 offset0:96 offset1:104
	v_mul_f32_e32 v5, v26, v7
	s_waitcnt vmcnt(17)
	v_mul_f32_e32 v7, 0xbfb8aa3b, v28
	v_exp_f32_e32 v7, v7
	v_add_f32_e32 v2, 1.0, v9
	v_rcp_f32_e32 v2, v2
	s_waitcnt vmcnt(16)
	v_mul_f32_e32 v9, 0xbfb8aa3b, v29
	v_add_f32_e32 v7, 1.0, v7
	v_rcp_f32_e32 v7, v7
	v_mul_f32_e32 v2, v27, v2
	v_exp_f32_e32 v9, v9
	ds_write2st64_b32 v6, v5, v2 offset0:112 offset1:120
	v_mul_f32_e32 v5, v28, v7
	s_waitcnt vmcnt(15)
	v_mul_f32_e32 v7, 0xbfb8aa3b, v30
	v_exp_f32_e32 v7, v7
	v_add_f32_e32 v2, 1.0, v9
	v_rcp_f32_e32 v2, v2
	s_waitcnt vmcnt(14)
	v_mul_f32_e32 v9, 0xbfb8aa3b, v31
	v_add_f32_e32 v7, 1.0, v7
	v_rcp_f32_e32 v7, v7
	v_mul_f32_e32 v2, v29, v2
	v_exp_f32_e32 v9, v9
	ds_write2st64_b32 v6, v5, v2 offset0:128 offset1:136
	v_mul_f32_e32 v5, v30, v7
	s_waitcnt vmcnt(13)
	v_mul_f32_e32 v7, 0xbfb8aa3b, v32
	v_exp_f32_e32 v7, v7
	v_add_f32_e32 v2, 1.0, v9
	v_rcp_f32_e32 v2, v2
	s_waitcnt vmcnt(12)
	v_mul_f32_e32 v9, 0xbfb8aa3b, v33
	v_add_f32_e32 v7, 1.0, v7
	v_rcp_f32_e32 v7, v7
	v_mul_f32_e32 v2, v31, v2
	v_exp_f32_e32 v9, v9
	ds_write2st64_b32 v6, v5, v2 offset0:144 offset1:152
	v_mul_f32_e32 v5, v32, v7
	s_waitcnt vmcnt(11)
	v_mul_f32_e32 v7, 0xbfb8aa3b, v34
	v_exp_f32_e32 v7, v7
	v_add_f32_e32 v2, 1.0, v9
	v_rcp_f32_e32 v2, v2
	s_waitcnt vmcnt(10)
	v_mul_f32_e32 v9, 0xbfb8aa3b, v35
	v_add_f32_e32 v7, 1.0, v7
	v_rcp_f32_e32 v7, v7
	v_mul_f32_e32 v2, v33, v2
	v_exp_f32_e32 v9, v9
	ds_write2st64_b32 v6, v5, v2 offset0:160 offset1:168
	v_mul_f32_e32 v5, v34, v7
	s_waitcnt vmcnt(9)
	v_mul_f32_e32 v7, 0xbfb8aa3b, v36
	v_exp_f32_e32 v7, v7
	v_add_f32_e32 v2, 1.0, v9
	v_rcp_f32_e32 v2, v2
	s_waitcnt vmcnt(8)
	v_mul_f32_e32 v9, 0xbfb8aa3b, v37
	v_add_f32_e32 v7, 1.0, v7
	v_rcp_f32_e32 v7, v7
	v_mul_f32_e32 v2, v35, v2
	v_exp_f32_e32 v9, v9
	ds_write2st64_b32 v6, v5, v2 offset0:176 offset1:184
	v_mul_f32_e32 v5, v36, v7
	s_waitcnt vmcnt(7)
	v_mul_f32_e32 v7, 0xbfb8aa3b, v38
	v_exp_f32_e32 v7, v7
	v_add_f32_e32 v2, 1.0, v9
	v_rcp_f32_e32 v2, v2
	s_waitcnt vmcnt(6)
	v_mul_f32_e32 v9, 0xbfb8aa3b, v39
	v_add_f32_e32 v7, 1.0, v7
	v_rcp_f32_e32 v7, v7
	v_mul_f32_e32 v2, v37, v2
	v_exp_f32_e32 v9, v9
	ds_write2st64_b32 v6, v5, v2 offset0:192 offset1:200
	v_mul_f32_e32 v5, v38, v7
	s_waitcnt vmcnt(5)
	v_mul_f32_e32 v7, 0xbfb8aa3b, v40
	v_exp_f32_e32 v7, v7
	v_add_f32_e32 v2, 1.0, v9
	v_rcp_f32_e32 v2, v2
	s_waitcnt vmcnt(4)
	v_mul_f32_e32 v9, 0xbfb8aa3b, v41
	v_add_f32_e32 v7, 1.0, v7
	v_rcp_f32_e32 v7, v7
	v_mul_f32_e32 v2, v39, v2
	v_exp_f32_e32 v9, v9
	ds_write2st64_b32 v6, v5, v2 offset0:208 offset1:216
	v_mul_f32_e32 v5, v40, v7
	s_waitcnt vmcnt(3)
	v_mul_f32_e32 v7, 0xbfb8aa3b, v42
	v_exp_f32_e32 v7, v7
	v_add_f32_e32 v2, 1.0, v9
	v_rcp_f32_e32 v2, v2
	s_waitcnt vmcnt(2)
	v_mul_f32_e32 v9, 0xbfb8aa3b, v10
	v_exp_f32_e32 v9, v9
	v_add_f32_e32 v7, 1.0, v7
	v_rcp_f32_e32 v7, v7
	v_mul_f32_e32 v2, v41, v2
	ds_write2st64_b32 v6, v5, v2 offset0:224 offset1:232
	v_add_f32_e32 v2, 1.0, v9
	v_rcp_f32_e32 v2, v2
	v_mul_f32_e32 v5, v42, v7
	s_waitcnt vmcnt(1)
	v_mul_f32_e32 v7, 0xbfb8aa3b, v8
	s_waitcnt vmcnt(0)
	v_mul_f32_e32 v9, 0xbfb8aa3b, v4
	v_exp_f32_e32 v7, v7
	v_exp_f32_e32 v9, v9
	v_mul_f32_e32 v2, v10, v2
	ds_write2st64_b32 v6, v5, v2 offset0:240 offset1:248
	v_add_f32_e32 v7, 1.0, v7
	v_add_f32_e32 v2, 1.0, v9
	v_rcp_f32_e32 v7, v7
	v_rcp_f32_e32 v2, v2
	v_and_b32_e32 v1, 63, v76
	v_readlane_b32 s16, v247, 9
	v_readlane_b32 s17, v247, 10
	v_mul_f32_e32 v5, v8, v7
	v_add_u32_e32 v7, 0x10000, v6
	v_mul_f32_e32 v2, v4, v2
	v_add_u32_e32 v4, 0x10800, v6
	v_ashrrev_i32_e32 v77, 6, v76
	ds_write_b32 v7, v5
	ds_write_b32 v4, v2
	v_lshl_or_b32 v78, s2, 6, v1
	v_lshlrev_b32_e32 v2, 7, v77
	s_mov_b32 s3, 0x9000
	v_mov_b64_e32 v[4:5], s[16:17]
	v_mad_i64_i32 v[4:5], s[0:1], v2, s3, v[4:5]
	v_ashrrev_i32_e32 v79, 31, v78
	v_lshl_add_u64 v[80:81], v[78:79], 2, v[4:5]
	v_lshlrev_b32_e32 v85, 9, v77
	s_mov_b32 s4, -16
	s_mov_b32 s5, 0x75000
	s_mov_b32 s8, 0x7e000
	s_mov_b32 s9, 0x87000
	s_mov_b64 s[0:1], 0x90000
	v_mov_b32_e32 v2, v3
	v_mov_b32_e32 v20, v3
	v_mov_b32_e32 v21, v3
	v_mov_b32_e32 v28, v3
	v_mov_b32_e32 v29, v3
	v_mov_b32_e32 v96, v3
	v_mov_b32_e32 v97, v3
	v_mov_b32_e32 v98, v3
	v_mov_b32_e32 v99, v3
	v_mov_b32_e32 v100, v3
	v_mov_b32_e32 v101, v3
	v_mov_b32_e32 v102, v3
	v_mov_b32_e32 v103, v3
	v_mov_b32_e32 v104, v3
	v_mov_b32_e32 v105, v3
	v_mov_b32_e32 v83, v3
	v_readlane_b32 s18, v247, 11
	v_readlane_b32 s19, v247, 12
	v_readlane_b32 s20, v247, 13
	v_readlane_b32 s21, v247, 14
	v_readlane_b32 s22, v247, 15
	v_readlane_b32 s23, v247, 16
	s_waitcnt lgkmcnt(0)
	s_barrier
.LBB0_256:
	v_add_co_u32_e32 v4, vcc, s3, v80
	s_mov_b32 s10, 0x12000
	s_nop 0
	v_addc_co_u32_e32 v5, vcc, 0, v81, vcc
	global_load_dword v110, v[80:81], off nt
	global_load_dword v112, v[4:5], off nt
	v_add_co_u32_e32 v4, vcc, s10, v80
	s_mov_b32 s10, 0x1b000
	s_nop 0
	v_addc_co_u32_e32 v5, vcc, 0, v81, vcc
	global_load_dword v114, v[4:5], off nt
	v_add_co_u32_e32 v4, vcc, s10, v80
	s_mov_b32 s10, 0x24000
	s_nop 0
	v_addc_co_u32_e32 v5, vcc, 0, v81, vcc
	global_load_dword v116, v[4:5], off nt
	v_add_co_u32_e32 v4, vcc, s10, v80
	s_mov_b32 s10, 0x2d000
	s_nop 0
	v_addc_co_u32_e32 v5, vcc, 0, v81, vcc
	global_load_dword v106, v[4:5], off nt
	v_add_co_u32_e32 v4, vcc, s10, v80
	s_mov_b32 s10, 0x36000
	s_nop 0
	v_addc_co_u32_e32 v5, vcc, 0, v81, vcc
	global_load_dword v94, v[4:5], off nt
	v_add_co_u32_e32 v4, vcc, s10, v80
	s_mov_b32 s10, 0x3f000
	s_nop 0
	v_addc_co_u32_e32 v5, vcc, 0, v81, vcc
	global_load_dword v92, v[4:5], off nt
	v_add_co_u32_e32 v4, vcc, s10, v80
	s_mov_b32 s10, 0x48000
	s_nop 0
	v_addc_co_u32_e32 v5, vcc, 0, v81, vcc
	global_load_dword v93, v[4:5], off nt
	v_add_co_u32_e32 v4, vcc, s10, v80
	s_mov_b32 s10, 0x51000
	s_nop 0
	v_addc_co_u32_e32 v5, vcc, 0, v81, vcc
	global_load_dword v88, v[4:5], off nt
	v_add_co_u32_e32 v4, vcc, s10, v80
	s_mov_b32 s10, 0x5a000
	s_nop 0
	v_addc_co_u32_e32 v5, vcc, 0, v81, vcc
	global_load_dword v89, v[4:5], off nt
	v_add_co_u32_e32 v4, vcc, s10, v80
	s_mov_b32 s10, 0x63000
	s_nop 0
	v_addc_co_u32_e32 v5, vcc, 0, v81, vcc
	global_load_dword v90, v[4:5], off nt
	v_add_co_u32_e32 v4, vcc, s10, v80
	s_mov_b32 s10, 0x6c000
	s_nop 0
	v_addc_co_u32_e32 v5, vcc, 0, v81, vcc
	global_load_dword v91, v[4:5], off nt
	v_add_co_u32_e32 v4, vcc, s10, v80
	s_add_i32 s4, s4, 16
	s_nop 0
	v_addc_co_u32_e32 v5, vcc, 0, v81, vcc
	global_load_dword v86, v[4:5], off nt
	v_add_co_u32_e32 v4, vcc, s5, v80
	s_cmpk_gt_u32 s4, 0x6f
	s_nop 0
	v_addc_co_u32_e32 v5, vcc, 0, v81, vcc
	global_load_dword v87, v[4:5], off nt
	v_add_co_u32_e32 v4, vcc, s8, v80
	s_nop 1
	v_addc_co_u32_e32 v5, vcc, 0, v81, vcc
	global_load_dword v82, v[4:5], off nt
	v_add_co_u32_e32 v4, vcc, s9, v80
	s_nop 1
	v_addc_co_u32_e32 v5, vcc, 0, v81, vcc
	global_load_dword v84, v[4:5], off nt
	v_add_u32_e32 v4, 0x10000, v85
	ds_read_b128 v[4:7], v4
	v_lshl_add_u64 v[80:81], v[80:81], 0, s[0:1]
	s_waitcnt vmcnt(15) lgkmcnt(0)
	v_fmac_f32_e32 v83, v110, v4
	s_waitcnt vmcnt(14)
	v_fmac_f32_e32 v83, v112, v5
	s_waitcnt vmcnt(13)
	v_fmac_f32_e32 v83, v114, v6
	s_waitcnt vmcnt(12)
	v_fmac_f32_e32 v83, v116, v7
	ds_read_b128 v[4:7], v85
	ds_read_b128 v[68:71], v85 offset:16
	ds_read_b128 v[56:59], v85 offset:32
	ds_read_b128 v[44:47], v85 offset:48
	ds_read_b128 v[72:75], v85 offset:4112
	ds_read_b128 v[8:11], v85 offset:4096
	s_waitcnt lgkmcnt(5)
	v_mov_b32_e32 v12, v4
	v_mov_b32_e32 v4, v6
	s_waitcnt lgkmcnt(0)
	v_mov_b32_e32 v13, v8
	v_pk_fma_f32 v[2:3], v[110:111], v[12:13], v[2:3] op_sel_hi:[0,1,1]
	v_mov_b32_e32 v8, v5
	v_pk_fma_f32 v[2:3], v[112:113], v[8:9], v[2:3] op_sel_hi:[0,1,1]
	v_mov_b32_e32 v5, v10
	v_pk_fma_f32 v[2:3], v[114:115], v[4:5], v[2:3] op_sel_hi:[0,1,1]
	v_mov_b32_e32 v10, v7
	v_pk_fma_f32 v[2:3], v[116:117], v[10:11], v[2:3] op_sel_hi:[0,1,1]
	v_mov_b32_e32 v4, v68
	v_mov_b32_e32 v5, v72
	s_waitcnt vmcnt(11)
	v_pk_fma_f32 v[120:121], v[106:107], v[4:5], v[2:3] op_sel_hi:[0,1,1]
	ds_read_b128 v[60:63], v85 offset:8208
	ds_read_b128 v[64:67], v85 offset:12304
	ds_read_b128 v[2:5], v85 offset:8192
	ds_read_b128 v[6:9], v85 offset:12288
	v_mov_b32_e32 v72, v69
	s_waitcnt lgkmcnt(1)
	v_mov_b32_e32 v10, v2
	s_waitcnt lgkmcnt(0)
	v_mov_b32_e32 v11, v6
	v_pk_fma_f32 v[10:11], v[110:111], v[10:11], v[20:21] op_sel_hi:[0,1,1]
	v_mov_b32_e32 v6, v3
	v_pk_fma_f32 v[2:3], v[112:113], v[6:7], v[10:11] op_sel_hi:[0,1,1]
	v_mov_b32_e32 v6, v4
	v_mov_b32_e32 v7, v8
	v_pk_fma_f32 v[2:3], v[114:115], v[6:7], v[2:3] op_sel_hi:[0,1,1]
	v_mov_b32_e32 v8, v5
	v_pk_fma_f32 v[2:3], v[116:117], v[8:9], v[2:3] op_sel_hi:[0,1,1]
	v_mov_b32_e32 v4, v60
	v_mov_b32_e32 v5, v64
	v_pk_fma_f32 v[118:119], v[106:107], v[4:5], v[2:3] op_sel_hi:[0,1,1]
	ds_read_b128 v[48:51], v85 offset:16400
	ds_read_b128 v[52:55], v85 offset:20496
	ds_read_b128 v[2:5], v85 offset:16384
	ds_read_b128 v[6:9], v85 offset:20480
	v_mov_b32_e32 v64, v61
	s_waitcnt lgkmcnt(1)
	v_mov_b32_e32 v10, v2
	s_waitcnt lgkmcnt(0)
	v_mov_b32_e32 v11, v6
	v_pk_fma_f32 v[10:11], v[110:111], v[10:11], v[28:29] op_sel_hi:[0,1,1]
	v_mov_b32_e32 v6, v3
	v_pk_fma_f32 v[2:3], v[112:113], v[6:7], v[10:11] op_sel_hi:[0,1,1]
	v_mov_b32_e32 v6, v4
	v_mov_b32_e32 v7, v8
	v_pk_fma_f32 v[2:3], v[114:115], v[6:7], v[2:3] op_sel_hi:[0,1,1]
	v_mov_b32_e32 v8, v5
	v_pk_fma_f32 v[2:3], v[116:117], v[8:9], v[2:3] op_sel_hi:[0,1,1]
	v_mov_b32_e32 v4, v48
	v_mov_b32_e32 v5, v52
	v_pk_fma_f32 v[108:109], v[106:107], v[4:5], v[2:3] op_sel_hi:[0,1,1]
	ds_read_b128 v[36:39], v85 offset:24592
	ds_read_b128 v[40:43], v85 offset:28688
	ds_read_b128 v[2:5], v85 offset:24576
	ds_read_b128 v[6:9], v85 offset:28672
	s_waitcnt vmcnt(6)
	v_mov_b32_e32 v48, v89
	v_mov_b32_e32 v52, v49
	s_waitcnt lgkmcnt(1)
	v_mov_b32_e32 v10, v2
	s_waitcnt lgkmcnt(0)
	v_mov_b32_e32 v11, v6
	v_pk_fma_f32 v[10:11], v[110:111], v[10:11], v[96:97] op_sel_hi:[0,1,1]
	v_mov_b32_e32 v6, v3
	v_pk_fma_f32 v[2:3], v[112:113], v[6:7], v[10:11] op_sel_hi:[0,1,1]
	v_mov_b32_e32 v6, v4
	v_mov_b32_e32 v7, v8
	v_pk_fma_f32 v[2:3], v[114:115], v[6:7], v[2:3] op_sel_hi:[0,1,1]
	v_mov_b32_e32 v8, v5
	v_pk_fma_f32 v[2:3], v[116:117], v[8:9], v[2:3] op_sel_hi:[0,1,1]
	v_mov_b32_e32 v4, v36
	v_mov_b32_e32 v5, v40
	v_pk_fma_f32 v[96:97], v[106:107], v[4:5], v[2:3] op_sel_hi:[0,1,1]
	ds_read_b128 v[28:31], v85 offset:32784
	ds_read_b128 v[32:35], v85 offset:36880
	ds_read_b128 v[2:5], v85 offset:32768
	ds_read_b128 v[6:9], v85 offset:36864
	v_mov_b32_e32 v40, v37
	v_mov_b32_e32 v36, v93
	s_waitcnt lgkmcnt(1)
	v_mov_b32_e32 v10, v2
	s_waitcnt lgkmcnt(0)
	v_mov_b32_e32 v11, v6
	v_pk_fma_f32 v[10:11], v[110:111], v[10:11], v[98:99] op_sel_hi:[0,1,1]
	v_mov_b32_e32 v6, v3
	v_pk_fma_f32 v[2:3], v[112:113], v[6:7], v[10:11] op_sel_hi:[0,1,1]
	v_mov_b32_e32 v6, v4
	v_mov_b32_e32 v7, v8
	v_pk_fma_f32 v[2:3], v[114:115], v[6:7], v[2:3] op_sel_hi:[0,1,1]
	v_mov_b32_e32 v8, v5
	v_pk_fma_f32 v[2:3], v[116:117], v[8:9], v[2:3] op_sel_hi:[0,1,1]
	v_mov_b32_e32 v4, v28
	v_mov_b32_e32 v5, v32
	v_pk_fma_f32 v[98:99], v[106:107], v[4:5], v[2:3] op_sel_hi:[0,1,1]
	ds_read_b128 v[20:23], v85 offset:40976
	ds_read_b128 v[24:27], v85 offset:45072
	ds_read_b128 v[2:5], v85 offset:40960
	ds_read_b128 v[6:9], v85 offset:45056
	v_mov_b32_e32 v32, v29
	v_mov_b32_e32 v28, v50
	v_mov_b32_e32 v29, v54
	s_waitcnt lgkmcnt(1)
	v_mov_b32_e32 v10, v2
	s_waitcnt lgkmcnt(0)
	v_mov_b32_e32 v11, v6
	v_pk_fma_f32 v[10:11], v[110:111], v[10:11], v[100:101] op_sel_hi:[0,1,1]
	v_mov_b32_e32 v6, v3
	v_pk_fma_f32 v[2:3], v[112:113], v[6:7], v[10:11] op_sel_hi:[0,1,1]
	v_mov_b32_e32 v6, v4
	v_mov_b32_e32 v7, v8
	v_pk_fma_f32 v[2:3], v[114:115], v[6:7], v[2:3] op_sel_hi:[0,1,1]
	v_mov_b32_e32 v8, v5
	v_pk_fma_f32 v[2:3], v[116:117], v[8:9], v[2:3] op_sel_hi:[0,1,1]
	v_mov_b32_e32 v4, v20
	v_mov_b32_e32 v5, v24
	v_pk_fma_f32 v[100:101], v[106:107], v[4:5], v[2:3] op_sel_hi:[0,1,1]
	ds_read_b128 v[12:15], v85 offset:49168
	ds_read_b128 v[16:19], v85 offset:53264
	ds_read_b128 v[2:5], v85 offset:49152
	ds_read_b128 v[6:9], v85 offset:53248
	v_mov_b32_e32 v24, v21
	v_mov_b32_e32 v20, v62
	v_mov_b32_e32 v21, v66
	s_waitcnt lgkmcnt(1)
	v_mov_b32_e32 v10, v2
	s_waitcnt lgkmcnt(0)
	v_mov_b32_e32 v11, v6
	v_pk_fma_f32 v[10:11], v[110:111], v[10:11], v[102:103] op_sel_hi:[0,1,1]
	v_mov_b32_e32 v6, v3
	v_pk_fma_f32 v[2:3], v[112:113], v[6:7], v[10:11] op_sel_hi:[0,1,1]
	v_mov_b32_e32 v6, v4
	v_mov_b32_e32 v7, v8
	v_pk_fma_f32 v[2:3], v[114:115], v[6:7], v[2:3] op_sel_hi:[0,1,1]
	v_mov_b32_e32 v8, v5
	v_pk_fma_f32 v[2:3], v[116:117], v[8:9], v[2:3] op_sel_hi:[0,1,1]
	v_mov_b32_e32 v4, v12
	v_mov_b32_e32 v5, v16
	v_pk_fma_f32 v[102:103], v[106:107], v[4:5], v[2:3] op_sel_hi:[0,1,1]
	ds_read_b128 v[4:7], v85 offset:57360
	ds_read_b128 v[8:11], v85 offset:61456
	ds_read_b128 v[122:125], v85 offset:57344
	ds_read_b128 v[126:129], v85 offset:61440
	v_mov_b32_e32 v16, v13
	v_mov_b32_e32 v13, v74
	v_mov_b32_e32 v74, v71
	s_waitcnt lgkmcnt(1)
	v_mov_b32_e32 v2, v122
	s_waitcnt lgkmcnt(0)
	v_mov_b32_e32 v3, v126
	v_pk_fma_f32 v[2:3], v[110:111], v[2:3], v[104:105] op_sel_hi:[0,1,1]
	v_mov_b32_e32 v126, v123
	v_pk_fma_f32 v[2:3], v[112:113], v[126:127], v[2:3] op_sel_hi:[0,1,1]
	v_mov_b32_e32 v104, v124
	v_mov_b32_e32 v105, v128
	v_pk_fma_f32 v[2:3], v[114:115], v[104:105], v[2:3] op_sel_hi:[0,1,1]
	v_mov_b32_e32 v128, v125
	v_pk_fma_f32 v[2:3], v[116:117], v[128:129], v[2:3] op_sel_hi:[0,1,1]
	v_mov_b32_e32 v104, v4
	v_mov_b32_e32 v105, v8
	v_pk_fma_f32 v[104:105], v[106:107], v[104:105], v[2:3] op_sel_hi:[0,1,1]
	v_add_u32_e32 v2, 0x10010, v85
	v_mov_b32_e32 v8, v5
	ds_read_b128 v[2:5], v2
	v_mov_b32_e32 v107, v94
	v_mov_b32_e32 v66, v63
	v_mov_b32_e32 v54, v51
	v_pk_fma_f32 v[8:9], v[94:95], v[8:9], v[104:105] op_sel_hi:[0,1,1]
	s_waitcnt lgkmcnt(0)
	v_pk_mul_f32 v[2:3], v[106:107], v[2:3]
	s_nop 0
	v_add_f32_e32 v2, v83, v2
	v_add_f32_e32 v12, v2, v3
	v_pk_mul_f32 v[2:3], v[92:93], v[4:5]
	s_nop 0
	v_add_f32_e32 v2, v12, v2
	v_add_f32_e32 v12, v2, v3
	v_add_u32_e32 v2, 0x10020, v85
	ds_read_b128 v[2:5], v2
	s_waitcnt lgkmcnt(0)
	v_pk_mul_f32 v[2:3], v[88:89], v[2:3]
	s_nop 0
	v_add_f32_e32 v2, v12, v2
	v_add_f32_e32 v12, v2, v3
	s_waitcnt vmcnt(4)
	v_pk_mul_f32 v[2:3], v[90:91], v[4:5]
	s_nop 0
	v_add_f32_e32 v2, v12, v2
	v_add_f32_e32 v12, v2, v3
	v_add_u32_e32 v2, 0x10030, v85
	ds_read_b128 v[2:5], v2
	s_waitcnt vmcnt(2) lgkmcnt(0)
	v_pk_mul_f32 v[2:3], v[86:87], v[2:3]
	s_nop 0
	v_add_f32_e32 v2, v12, v2
	v_mov_b32_e32 v12, v70
	ds_read_b128 v[68:71], v85 offset:4128
	v_add_f32_e32 v37, v2, v3
	v_pk_fma_f32 v[2:3], v[94:95], v[72:73], v[120:121] op_sel_hi:[0,1,1]
	v_pk_fma_f32 v[2:3], v[92:93], v[12:13], v[2:3] op_sel_hi:[0,1,1]
	v_pk_fma_f32 v[2:3], v[36:37], v[74:75], v[2:3] op_sel_hi:[0,1,1]
	v_mov_b32_e32 v12, v56
	s_waitcnt lgkmcnt(0)
	v_mov_b32_e32 v13, v68
	v_pk_fma_f32 v[2:3], v[88:89], v[12:13], v[2:3] op_sel_hi:[0,1,1]
	v_mov_b32_e32 v12, v58
	v_mov_b32_e32 v13, v70
	v_mov_b32_e32 v70, v59
	ds_read_b128 v[58:61], v85 offset:4144
	v_mov_b32_e32 v68, v57
	v_pk_fma_f32 v[2:3], v[48:49], v[68:69], v[2:3] op_sel_hi:[0,1,1]
	v_pk_fma_f32 v[2:3], v[90:91], v[12:13], v[2:3] op_sel_hi:[0,1,1]
	v_mov_b32_e32 v56, v91
	v_pk_fma_f32 v[2:3], v[56:57], v[70:71], v[2:3] op_sel_hi:[0,1,1]
	v_mov_b32_e32 v12, v44
	s_waitcnt lgkmcnt(0)
	v_mov_b32_e32 v13, v58
	v_pk_fma_f32 v[2:3], v[86:87], v[12:13], v[2:3] op_sel_hi:[0,1,1]
	v_mov_b32_e32 v44, v87
	v_mov_b32_e32 v58, v45
	v_pk_fma_f32 v[2:3], v[44:45], v[58:59], v[2:3] op_sel_hi:[0,1,1]
	v_mov_b32_e32 v12, v46
	v_mov_b32_e32 v13, v60
	s_waitcnt vmcnt(1)
	v_pk_fma_f32 v[2:3], v[82:83], v[12:13], v[2:3] op_sel_hi:[0,1,1]
	v_mov_b32_e32 v60, v47
	s_waitcnt vmcnt(0)
	v_pk_fma_f32 v[2:3], v[84:85], v[60:61], v[2:3] op_sel_hi:[0,1,1]
	v_pk_fma_f32 v[12:13], v[94:95], v[64:65], v[118:119] op_sel_hi:[0,1,1]
	ds_read_b128 v[58:61], v85 offset:8224
	ds_read_b128 v[62:65], v85 offset:12320
	v_pk_fma_f32 v[12:13], v[92:93], v[20:21], v[12:13] op_sel_hi:[0,1,1]
	v_pk_fma_f32 v[12:13], v[36:37], v[66:67], v[12:13] op_sel_hi:[0,1,1]
	s_waitcnt lgkmcnt(1)
	v_mov_b32_e32 v20, v58
	s_waitcnt lgkmcnt(0)
	v_mov_b32_e32 v21, v62
	v_pk_fma_f32 v[12:13], v[88:89], v[20:21], v[12:13] op_sel_hi:[0,1,1]
	v_mov_b32_e32 v62, v59
	v_pk_fma_f32 v[12:13], v[48:49], v[62:63], v[12:13] op_sel_hi:[0,1,1]
	v_mov_b32_e32 v20, v60
	v_mov_b32_e32 v21, v64
	v_pk_fma_f32 v[12:13], v[90:91], v[20:21], v[12:13] op_sel_hi:[0,1,1]
	v_mov_b32_e32 v64, v61
	v_pk_fma_f32 v[12:13], v[56:57], v[64:65], v[12:13] op_sel_hi:[0,1,1]
	ds_read_b128 v[58:61], v85 offset:8240
	ds_read_b128 v[62:65], v85 offset:12336
	s_waitcnt lgkmcnt(1)
	v_mov_b32_e32 v20, v58
	s_waitcnt lgkmcnt(0)
	v_mov_b32_e32 v21, v62
	v_pk_fma_f32 v[12:13], v[86:87], v[20:21], v[12:13] op_sel_hi:[0,1,1]
	v_mov_b32_e32 v62, v59
	v_pk_fma_f32 v[12:13], v[44:45], v[62:63], v[12:13] op_sel_hi:[0,1,1]
	v_mov_b32_e32 v20, v60
	v_mov_b32_e32 v21, v64
	v_pk_fma_f32 v[12:13], v[82:83], v[20:21], v[12:13] op_sel_hi:[0,1,1]
	v_mov_b32_e32 v64, v61
	v_pk_fma_f32 v[20:21], v[84:85], v[64:65], v[12:13] op_sel_hi:[0,1,1]
	v_pk_fma_f32 v[12:13], v[94:95], v[52:53], v[108:109] op_sel_hi:[0,1,1]
	ds_read_b128 v[50:53], v85 offset:16416
	ds_read_b128 v[58:61], v85 offset:20512
	v_pk_fma_f32 v[12:13], v[92:93], v[28:29], v[12:13] op_sel_hi:[0,1,1]
	v_pk_fma_f32 v[12:13], v[36:37], v[54:55], v[12:13] op_sel_hi:[0,1,1]
	s_waitcnt lgkmcnt(1)
	v_mov_b32_e32 v28, v50
	s_waitcnt lgkmcnt(0)
	v_mov_b32_e32 v29, v58
	v_pk_fma_f32 v[12:13], v[88:89], v[28:29], v[12:13] op_sel_hi:[0,1,1]
	v_mov_b32_e32 v58, v51
	v_pk_fma_f32 v[12:13], v[48:49], v[58:59], v[12:13] op_sel_hi:[0,1,1]
	v_mov_b32_e32 v28, v52
	v_mov_b32_e32 v29, v60
	v_pk_fma_f32 v[12:13], v[90:91], v[28:29], v[12:13] op_sel_hi:[0,1,1]
	v_mov_b32_e32 v60, v53
	v_pk_fma_f32 v[12:13], v[56:57], v[60:61], v[12:13] op_sel_hi:[0,1,1]
	ds_read_b128 v[50:53], v85 offset:16432
	ds_read_b128 v[58:61], v85 offset:20528
	s_waitcnt lgkmcnt(1)
	v_mov_b32_e32 v28, v50
	s_waitcnt lgkmcnt(0)
	v_mov_b32_e32 v29, v58
	v_pk_fma_f32 v[12:13], v[86:87], v[28:29], v[12:13] op_sel_hi:[0,1,1]
	v_mov_b32_e32 v58, v51
	v_pk_fma_f32 v[12:13], v[44:45], v[58:59], v[12:13] op_sel_hi:[0,1,1]
	v_mov_b32_e32 v28, v52
	v_mov_b32_e32 v29, v60
	v_pk_fma_f32 v[12:13], v[82:83], v[28:29], v[12:13] op_sel_hi:[0,1,1]
	v_mov_b32_e32 v60, v53
	v_pk_fma_f32 v[28:29], v[84:85], v[60:61], v[12:13] op_sel_hi:[0,1,1]
	v_pk_fma_f32 v[12:13], v[94:95], v[40:41], v[96:97] op_sel_hi:[0,1,1]
	v_mov_b32_e32 v40, v38
	v_mov_b32_e32 v41, v42
	v_pk_fma_f32 v[12:13], v[92:93], v[40:41], v[12:13] op_sel_hi:[0,1,1]
	v_mov_b32_e32 v42, v39
	ds_read_b128 v[38:41], v85 offset:24608
	ds_read_b128 v[50:53], v85 offset:28704
	v_pk_fma_f32 v[12:13], v[36:37], v[42:43], v[12:13] op_sel_hi:[0,1,1]
	s_waitcnt lgkmcnt(1)
	v_mov_b32_e32 v42, v38
	s_waitcnt lgkmcnt(0)
	v_mov_b32_e32 v43, v50
	v_pk_fma_f32 v[12:13], v[88:89], v[42:43], v[12:13] op_sel_hi:[0,1,1]
	v_mov_b32_e32 v50, v39
	v_pk_fma_f32 v[12:13], v[48:49], v[50:51], v[12:13] op_sel_hi:[0,1,1]
	v_mov_b32_e32 v38, v40
	v_mov_b32_e32 v39, v52
	v_pk_fma_f32 v[12:13], v[90:91], v[38:39], v[12:13] op_sel_hi:[0,1,1]
	v_mov_b32_e32 v52, v41
	v_pk_fma_f32 v[12:13], v[56:57], v[52:53], v[12:13] op_sel_hi:[0,1,1]
	ds_read_b128 v[38:41], v85 offset:24624
	ds_read_b128 v[50:53], v85 offset:28720
	s_waitcnt lgkmcnt(1)
	v_mov_b32_e32 v42, v38
	s_waitcnt lgkmcnt(0)
	v_mov_b32_e32 v43, v50
	v_pk_fma_f32 v[12:13], v[86:87], v[42:43], v[12:13] op_sel_hi:[0,1,1]
	v_mov_b32_e32 v50, v39
	v_pk_fma_f32 v[12:13], v[44:45], v[50:51], v[12:13] op_sel_hi:[0,1,1]
	v_mov_b32_e32 v38, v40
	v_mov_b32_e32 v39, v52
	v_pk_fma_f32 v[12:13], v[82:83], v[38:39], v[12:13] op_sel_hi:[0,1,1]
	v_mov_b32_e32 v52, v41
	v_pk_fma_f32 v[96:97], v[84:85], v[52:53], v[12:13] op_sel_hi:[0,1,1]
	v_pk_fma_f32 v[12:13], v[94:95], v[32:33], v[98:99] op_sel_hi:[0,1,1]
	v_mov_b32_e32 v32, v30
	v_mov_b32_e32 v33, v34
	v_pk_fma_f32 v[12:13], v[92:93], v[32:33], v[12:13] op_sel_hi:[0,1,1]
	v_mov_b32_e32 v34, v31
	ds_read_b128 v[30:33], v85 offset:32800
	ds_read_b128 v[38:41], v85 offset:36896
	v_pk_fma_f32 v[12:13], v[36:37], v[34:35], v[12:13] op_sel_hi:[0,1,1]
	s_waitcnt lgkmcnt(1)
	v_mov_b32_e32 v34, v30
	s_waitcnt lgkmcnt(0)
	v_mov_b32_e32 v35, v38
	v_pk_fma_f32 v[12:13], v[88:89], v[34:35], v[12:13] op_sel_hi:[0,1,1]
	v_mov_b32_e32 v38, v31
	v_pk_fma_f32 v[12:13], v[48:49], v[38:39], v[12:13] op_sel_hi:[0,1,1]
	v_mov_b32_e32 v30, v32
	v_mov_b32_e32 v31, v40
	v_pk_fma_f32 v[12:13], v[90:91], v[30:31], v[12:13] op_sel_hi:[0,1,1]
	v_mov_b32_e32 v40, v33
	v_pk_fma_f32 v[12:13], v[56:57], v[40:41], v[12:13] op_sel_hi:[0,1,1]
	ds_read_b128 v[30:33], v85 offset:32816
	ds_read_b128 v[38:41], v85 offset:36912
	s_waitcnt lgkmcnt(1)
	v_mov_b32_e32 v34, v30
	s_waitcnt lgkmcnt(0)
	v_mov_b32_e32 v35, v38
	v_pk_fma_f32 v[12:13], v[86:87], v[34:35], v[12:13] op_sel_hi:[0,1,1]
	v_mov_b32_e32 v38, v31
	v_pk_fma_f32 v[12:13], v[44:45], v[38:39], v[12:13] op_sel_hi:[0,1,1]
	v_mov_b32_e32 v30, v32
	v_mov_b32_e32 v31, v40
	v_pk_fma_f32 v[12:13], v[82:83], v[30:31], v[12:13] op_sel_hi:[0,1,1]
	v_mov_b32_e32 v40, v33
	v_pk_fma_f32 v[98:99], v[84:85], v[40:41], v[12:13] op_sel_hi:[0,1,1]
	v_pk_fma_f32 v[12:13], v[94:95], v[24:25], v[100:101] op_sel_hi:[0,1,1]
	v_mov_b32_e32 v24, v22
	v_mov_b32_e32 v25, v26
	v_pk_fma_f32 v[12:13], v[92:93], v[24:25], v[12:13] op_sel_hi:[0,1,1]
	v_mov_b32_e32 v26, v23
	ds_read_b128 v[22:25], v85 offset:40992
	ds_read_b128 v[30:33], v85 offset:45088
	v_pk_fma_f32 v[12:13], v[36:37], v[26:27], v[12:13] op_sel_hi:[0,1,1]
	s_waitcnt lgkmcnt(1)
	v_mov_b32_e32 v26, v22
	s_waitcnt lgkmcnt(0)
	v_mov_b32_e32 v27, v30
	v_pk_fma_f32 v[12:13], v[88:89], v[26:27], v[12:13] op_sel_hi:[0,1,1]
	v_mov_b32_e32 v30, v23
	v_pk_fma_f32 v[12:13], v[48:49], v[30:31], v[12:13] op_sel_hi:[0,1,1]
	v_mov_b32_e32 v22, v24
	v_mov_b32_e32 v23, v32
	v_pk_fma_f32 v[12:13], v[90:91], v[22:23], v[12:13] op_sel_hi:[0,1,1]
	v_mov_b32_e32 v32, v25
	v_pk_fma_f32 v[12:13], v[56:57], v[32:33], v[12:13] op_sel_hi:[0,1,1]
	ds_read_b128 v[22:25], v85 offset:41008
	ds_read_b128 v[30:33], v85 offset:45104
	s_waitcnt lgkmcnt(1)
	v_mov_b32_e32 v26, v22
	s_waitcnt lgkmcnt(0)
	v_mov_b32_e32 v27, v30
	v_pk_fma_f32 v[12:13], v[86:87], v[26:27], v[12:13] op_sel_hi:[0,1,1]
	v_mov_b32_e32 v30, v23
	v_pk_fma_f32 v[12:13], v[44:45], v[30:31], v[12:13] op_sel_hi:[0,1,1]
	v_mov_b32_e32 v22, v24
	v_mov_b32_e32 v23, v32
	v_pk_fma_f32 v[12:13], v[82:83], v[22:23], v[12:13] op_sel_hi:[0,1,1]
	v_mov_b32_e32 v32, v25
	v_pk_fma_f32 v[100:101], v[84:85], v[32:33], v[12:13] op_sel_hi:[0,1,1]
	v_pk_fma_f32 v[12:13], v[94:95], v[16:17], v[102:103] op_sel_hi:[0,1,1]
	v_mov_b32_e32 v16, v14
	v_mov_b32_e32 v17, v18
	v_pk_fma_f32 v[12:13], v[92:93], v[16:17], v[12:13] op_sel_hi:[0,1,1]
	v_mov_b32_e32 v18, v15
	v_pk_fma_f32 v[22:23], v[36:37], v[18:19], v[12:13] op_sel_hi:[0,1,1]
	ds_read_b128 v[12:15], v85 offset:49184
	ds_read_b128 v[16:19], v85 offset:53280
	s_waitcnt lgkmcnt(1)
	v_mov_b32_e32 v24, v12
	s_waitcnt lgkmcnt(0)
	v_mov_b32_e32 v25, v16
	v_pk_fma_f32 v[22:23], v[88:89], v[24:25], v[22:23] op_sel_hi:[0,1,1]
	v_mov_b32_e32 v16, v13
	v_pk_fma_f32 v[12:13], v[48:49], v[16:17], v[22:23] op_sel_hi:[0,1,1]
	v_mov_b32_e32 v16, v14
	v_mov_b32_e32 v17, v18
	v_pk_fma_f32 v[12:13], v[90:91], v[16:17], v[12:13] op_sel_hi:[0,1,1]
	v_mov_b32_e32 v18, v15
	v_pk_fma_f32 v[16:17], v[56:57], v[18:19], v[12:13] op_sel_hi:[0,1,1]
	ds_read_b128 v[12:15], v85 offset:49200
	ds_read_b128 v[22:25], v85 offset:53296
	s_waitcnt lgkmcnt(1)
	v_mov_b32_e32 v18, v12
	s_waitcnt lgkmcnt(0)
	v_mov_b32_e32 v19, v22
	v_pk_fma_f32 v[16:17], v[86:87], v[18:19], v[16:17] op_sel_hi:[0,1,1]
	v_mov_b32_e32 v22, v13
	v_pk_fma_f32 v[12:13], v[44:45], v[22:23], v[16:17] op_sel_hi:[0,1,1]
	v_mov_b32_e32 v16, v14
	v_mov_b32_e32 v17, v24
	v_pk_fma_f32 v[12:13], v[82:83], v[16:17], v[12:13] op_sel_hi:[0,1,1]
	v_mov_b32_e32 v24, v15
	v_pk_fma_f32 v[102:103], v[84:85], v[24:25], v[12:13] op_sel_hi:[0,1,1]
	v_mov_b32_e32 v12, v6
	v_mov_b32_e32 v13, v10
	v_pk_fma_f32 v[8:9], v[92:93], v[12:13], v[8:9] op_sel_hi:[0,1,1]
	v_mov_b32_e32 v10, v7
	v_pk_fma_f32 v[14:15], v[36:37], v[10:11], v[8:9] op_sel_hi:[0,1,1]
	ds_read_b128 v[6:9], v85 offset:57376
	ds_read_b128 v[10:13], v85 offset:61472
	s_waitcnt lgkmcnt(1)
	v_mov_b32_e32 v16, v6
	s_waitcnt lgkmcnt(0)
	v_mov_b32_e32 v17, v10
	v_pk_fma_f32 v[14:15], v[88:89], v[16:17], v[14:15] op_sel_hi:[0,1,1]
	v_mov_b32_e32 v10, v7
	v_pk_fma_f32 v[6:7], v[48:49], v[10:11], v[14:15] op_sel_hi:[0,1,1]
	v_mov_b32_e32 v10, v8
	v_mov_b32_e32 v11, v12
	v_pk_fma_f32 v[6:7], v[90:91], v[10:11], v[6:7] op_sel_hi:[0,1,1]
	v_mov_b32_e32 v12, v9
	v_pk_fma_f32 v[14:15], v[56:57], v[12:13], v[6:7] op_sel_hi:[0,1,1]
	ds_read_b128 v[6:9], v85 offset:57392
	ds_read_b128 v[10:13], v85 offset:61488
	s_waitcnt lgkmcnt(1)
	v_mov_b32_e32 v16, v6
	s_waitcnt lgkmcnt(0)
	v_mov_b32_e32 v17, v10
	v_pk_fma_f32 v[14:15], v[86:87], v[16:17], v[14:15] op_sel_hi:[0,1,1]
	v_mov_b32_e32 v10, v7
	v_pk_fma_f32 v[6:7], v[44:45], v[10:11], v[14:15] op_sel_hi:[0,1,1]
	v_mov_b32_e32 v10, v8
	v_mov_b32_e32 v11, v12
	v_pk_fma_f32 v[6:7], v[82:83], v[10:11], v[6:7] op_sel_hi:[0,1,1]
	v_mov_b32_e32 v83, v84
	v_pk_mul_f32 v[4:5], v[82:83], v[4:5]
	v_mov_b32_e32 v12, v9
	v_add_f32_e32 v4, v37, v4
	v_pk_fma_f32 v[104:105], v[84:85], v[12:13], v[6:7] op_sel_hi:[0,1,1]
	v_add_f32_e32 v83, v4, v5
	v_add_u32_e32 v85, 64, v85
	s_cbranch_scc0 .LBB0_256
	s_movk_i32 s0, 0x1100
	v_lshlrev_b32_e32 v1, 2, v1
	v_mul_lo_u32 v4, v77, s0
	s_movk_i32 s0, 0x440
	v_or_b32_e32 v4, v1, v4
	v_cmp_gt_i32_e32 vcc, s0, v76
	s_barrier
	ds_write2st64_b32 v4, v2, v3 offset1:1
	ds_write2st64_b32 v4, v20, v21 offset0:2 offset1:3
	ds_write2st64_b32 v4, v28, v29 offset0:4 offset1:5
	ds_write2st64_b32 v4, v96, v97 offset0:6 offset1:7
	ds_write2st64_b32 v4, v98, v99 offset0:8 offset1:9
	ds_write2st64_b32 v4, v100, v101 offset0:10 offset1:11
	ds_write2st64_b32 v4, v102, v103 offset0:12 offset1:13
	ds_write2st64_b32 v4, v104, v105 offset0:14 offset1:15
	ds_write_b32 v4, v83 offset:4096
	s_waitcnt lgkmcnt(0)
	s_barrier
	s_and_saveexec_b64 s[0:1], vcc
	s_cbranch_execz .LBB0_260
	v_readlane_b32 s8, v247, 1
	v_readlane_b32 s18, v247, 11
	v_readlane_b32 s19, v247, 12
	s_mov_b64 s[4:5], 0
	s_movk_i32 s3, 0x2400
	v_lshl_add_u64 v[2:3], v[78:79], 2, s[18:19]
	s_movk_i32 s8, 0x23f
	v_readlane_b32 s9, v247, 2
	v_readlane_b32 s10, v247, 3
	v_readlane_b32 s11, v247, 4
	v_readlane_b32 s12, v247, 5
	v_readlane_b32 s13, v247, 6
	v_readlane_b32 s14, v247, 7
	v_readlane_b32 s15, v247, 8
	v_readlane_b32 s16, v247, 9
	v_readlane_b32 s17, v247, 10
	v_readlane_b32 s20, v247, 13
	v_readlane_b32 s21, v247, 14
	v_readlane_b32 s22, v247, 15
	v_readlane_b32 s23, v247, 16
.LBB0_259:
	global_load_dword v14, v[2:3], off nt
	v_ashrrev_i32_e32 v4, 6, v76
	v_add_u32_e32 v6, 0x200, v76
	v_lshl_or_b32 v12, v4, 8, v1
	v_cmp_lt_i32_e32 vcc, s8, v76
	v_mov_b32_e32 v76, v6
	ds_read2st64_b32 v[6:7], v12 offset1:17
	ds_read2st64_b32 v[8:9], v12 offset0:34 offset1:51
	ds_read2st64_b32 v[10:11], v12 offset0:68 offset1:85
	ds_read2st64_b32 v[12:13], v12 offset0:102 offset1:119
	v_mad_u64_u32 v[4:5], s[10:11], v4, s3, v[78:79]
	s_waitcnt lgkmcnt(3)
	v_add_f32_e32 v6, 0, v6
	v_add_f32_e32 v6, v6, v7
	s_waitcnt lgkmcnt(2)
	v_add_f32_e32 v6, v6, v8
	v_add_f32_e32 v6, v6, v9
	s_waitcnt lgkmcnt(1)
	v_add_f32_e32 v6, v6, v10
	v_add_f32_e32 v6, v6, v11
	s_waitcnt lgkmcnt(0)
	v_add_f32_e32 v6, v6, v12
	v_ashrrev_i32_e32 v5, 31, v4
	v_add_f32_e32 v6, v6, v13
	s_or_b64 s[4:5], vcc, s[4:5]
	v_lshl_add_u64 v[4:5], v[4:5], 2, s[40:41]
	s_waitcnt vmcnt(0)
	v_add_f32_e32 v6, v6, v14
	global_store_dword v[4:5], v6, off
	s_andn2_b64 exec, exec, s[4:5]
	s_cbranch_execnz .LBB0_259
.LBB0_260:
	s_or_b64 exec, exec, s[0:1]
	v_mov_b32_e32 v3, v162
	s_barrier
	v_readlane_b32 s8, v247, 1
	v_ashrrev_i32_e32 v6, 8, v3
	v_lshl_add_u32 v1, s2, 1, v6
	v_ashrrev_i32_e32 v2, 31, v1
	v_lshrrev_b32_e32 v2, 28, v2
	v_add_u32_e32 v2, v1, v2
	v_ashrrev_i32_e32 v5, 4, v2
	v_and_b32_e32 v2, 0x3fffff0, v2
	v_readlane_b32 s16, v247, 9
	v_readlane_b32 s17, v247, 10
	v_readlane_b32 s18, v247, 11
	v_readlane_b32 s19, v247, 12
	v_readlane_b32 s20, v247, 13
	v_readlane_b32 s21, v247, 14
	v_and_b32_e32 v7, 63, v3
	v_sub_u32_e32 v2, v1, v2
	v_lshlrev_b32_e32 v1, 6, v5
	v_readlane_b32 s68, v247, 17
	v_readlane_b32 s22, v247, 15
	v_readlane_b32 s23, v247, 16
	s_mov_b64 s[16:17], s[20:21]
	v_or_b32_e32 v4, v1, v7
	s_movk_i32 s0, 0x1600
	v_lshlrev_b32_e32 v8, 5, v5
	s_movk_i32 s3, 0x7f
	v_and_b32_e32 v5, 2, v5
	v_readlane_b32 s69, v247, 18
	s_mov_b64 s[18:19], s[22:23]
	v_cmp_gt_i32_e64 s[0:1], s0, v4
	v_bfi_b32 v4, s3, v4, v8
	v_mov_b32_e32 v8, s69
	v_mov_b32_e32 v9, s19
	v_cmp_eq_u32_e32 vcc, 0, v5
	v_mov_b32_e32 v5, s68
	v_lshlrev_b32_e32 v2, 6, v2
	v_cndmask_b32_e32 v13, v8, v9, vcc
	v_mov_b32_e32 v8, s18
	v_cndmask_b32_e32 v12, v5, v8, vcc
	v_lshrrev_b32_e32 v5, 2, v3
	v_and_b32_e32 v8, 48, v5
	v_ashrrev_i32_e32 v5, 31, v4
	v_or_b32_e32 v11, v2, v8
	v_lshl_add_u64 v[4:5], v[4:5], 2, v[12:13]
	v_mov_b32_e32 v10, 0
	v_mov_b32_e32 v9, 0
	v_readlane_b32 s70, v247, 19
	v_readlane_b32 s71, v247, 20
	v_readlane_b32 s72, v247, 21
	v_readlane_b32 s73, v247, 22
	v_readlane_b32 s74, v247, 23
	v_readlane_b32 s75, v247, 24
	v_readlane_b32 s76, v247, 25
	v_readlane_b32 s77, v247, 26
	v_readlane_b32 s78, v247, 27
	v_readlane_b32 s79, v247, 28
	v_readlane_b32 s80, v247, 29
	v_readlane_b32 s81, v247, 30
	v_readlane_b32 s82, v247, 31
	v_readlane_b32 s83, v247, 32
	v_readlane_b32 s9, v247, 2
	v_readlane_b32 s10, v247, 3
	v_readlane_b32 s11, v247, 4
	v_readlane_b32 s12, v247, 5
	v_readlane_b32 s13, v247, 6
	v_readlane_b32 s14, v247, 7
	v_readlane_b32 s15, v247, 8
	s_and_saveexec_b64 s[4:5], s[0:1]
	s_cbranch_execz .LBB0_262
	s_movk_i32 s3, 0xb00
	v_mul_lo_u32 v12, v11, s3
	v_ashrrev_i32_e32 v13, 31, v12
	v_lshl_add_u64 v[12:13], v[12:13], 2, v[4:5]
	global_load_dword v9, v[12:13], off nt
.LBB0_262:
	s_or_b64 exec, exec, s[4:5]
	s_and_saveexec_b64 s[4:5], s[0:1]
	s_cbranch_execz .LBB0_264
	s_movk_i32 s3, 0xb00
	v_mul_lo_u32 v12, v11, s3
	v_ashrrev_i32_e32 v13, 31, v12
	v_lshl_add_u64 v[12:13], v[12:13], 2, v[4:5]
	v_add_co_u32_e32 v12, vcc, 0x2000, v12
	s_nop 1
	v_addc_co_u32_e32 v13, vcc, 0, v13, vcc
	global_load_dword v10, v[12:13], off offset:3072 nt

.LBB0_1487:
	s_ashr_i32 s47, s46, 31
	s_lshl_b64 s[46:47], s[46:47], 8
	v_mov_b32_e32 v144, v148
	v_mov_b32_e32 v169, v149
	s_add_u32 s46, s46, s69
	s_addc_u32 s47, s47, s72
	v_ashrrev_i32_e32 v145, 31, v144
	v_lshl_add_u64 v[146:147], s[46:47], 0, v[144:145]
	s_lshl_b32 s46, s82, 8
	s_or_b32 s46, s46, s70
	v_lshl_add_u32 v144, v169, 3, s46
	v_lshlrev_b64 v[170:171], 12, v[146:147]
	v_ashrrev_i32_e32 v145, 31, v144
	v_lshl_add_u64 v[170:171], s[8:9], 0, v[170:171]
	v_lshlrev_b64 v[144:145], 1, v[144:145]
	v_lshl_add_u64 v[174:175], v[170:171], 0, v[144:145]
	global_load_dwordx4 v[170:173], v[174:175], off nt
	v_lshlrev_b64 v[176:177], 11, v[146:147]
	v_lshl_add_u64 v[176:177], s[86:87], 0, v[176:177]
	v_lshl_add_u64 v[176:177], v[176:177], 0, v[144:145]
	s_mov_b64 s[46:47], 0x90
	s_and_b64 vcc, exec, s[6:7]
	s_mov_b64 s[6:7], -1
	s_waitcnt vmcnt(0)
	v_lshlrev_b32_e32 v178, 16, v170
	v_and_b32_e32 v179, 0xffff0000, v170
	v_lshlrev_b32_e32 v170, 16, v171
	v_and_b32_e32 v171, 0xffff0000, v171
	v_lshlrev_b32_e32 v180, 16, v172
	v_and_b32_e32 v181, 0xffff0000, v172
	v_lshlrev_b32_e32 v172, 16, v173
	v_and_b32_e32 v173, 0xffff0000, v173
	v_pk_mul_f32 v[126:127], v[126:127], v[170:171]
	v_pk_mul_f32 v[124:125], v[124:125], v[178:179]
	v_pk_mul_f32 v[170:171], v[122:123], v[172:173]
	v_pk_mul_f32 v[122:123], v[120:121], v[180:181]
	v_cvt_pk_bf16_f32 v120, v124, v125
	v_cvt_pk_bf16_f32 v121, v126, v127
	v_cvt_pk_bf16_f32 v122, v122, v123
	v_cvt_pk_bf16_f32 v123, v170, v171
	global_store_dwordx4 v[176:177], v[120:123], off
	global_load_dwordx4 v[120:123], v[174:175], off offset:256 nt
	v_lshl_add_u64 v[124:125], v[146:147], 0, 16
	v_lshlrev_b64 v[126:127], 12, v[124:125]
	v_lshl_add_u64 v[126:127], s[8:9], 0, v[126:127]
	v_lshl_add_u64 v[126:127], v[126:127], 0, v[144:145]
	s_waitcnt vmcnt(0)
	v_lshlrev_b32_e32 v170, 16, v120
	v_and_b32_e32 v171, 0xffff0000, v120
	v_lshlrev_b32_e32 v120, 16, v121
	v_and_b32_e32 v121, 0xffff0000, v121
	v_lshlrev_b32_e32 v172, 16, v122
	v_and_b32_e32 v173, 0xffff0000, v122
	v_lshlrev_b32_e32 v122, 16, v123
	v_and_b32_e32 v123, 0xffff0000, v123
	v_pk_mul_f32 v[118:119], v[118:119], v[120:121]
	v_pk_mul_f32 v[116:117], v[116:117], v[170:171]
	v_pk_mul_f32 v[120:121], v[114:115], v[122:123]
	v_pk_mul_f32 v[114:115], v[112:113], v[172:173]
	v_cvt_pk_bf16_f32 v112, v116, v117
	v_cvt_pk_bf16_f32 v113, v118, v119
	v_cvt_pk_bf16_f32 v114, v114, v115
	v_cvt_pk_bf16_f32 v115, v120, v121
	global_store_dwordx4 v[176:177], v[112:115], off offset:256
	global_load_dwordx4 v[112:115], v[126:127], off nt
	v_lshlrev_b64 v[116:117], 11, v[124:125]
	v_lshl_add_u64 v[116:117], s[86:87], 0, v[116:117]
	v_lshl_add_u64 v[116:117], v[116:117], 0, v[144:145]
	s_waitcnt vmcnt(0)
	v_lshlrev_b32_e32 v118, 16, v112
	v_and_b32_e32 v119, 0xffff0000, v112
	v_lshlrev_b32_e32 v112, 16, v113
	v_and_b32_e32 v113, 0xffff0000, v113
	v_lshlrev_b32_e32 v120, 16, v114
	v_and_b32_e32 v121, 0xffff0000, v114
	v_lshlrev_b32_e32 v114, 16, v115
	v_and_b32_e32 v115, 0xffff0000, v115
	v_pk_mul_f32 v[110:111], v[110:111], v[112:113]
	v_pk_mul_f32 v[108:109], v[108:109], v[118:119]
	v_pk_mul_f32 v[112:113], v[106:107], v[114:115]
	v_pk_mul_f32 v[106:107], v[104:105], v[120:121]
	v_cvt_pk_bf16_f32 v104, v108, v109
	v_cvt_pk_bf16_f32 v105, v110, v111
	v_cvt_pk_bf16_f32 v106, v106, v107
	v_cvt_pk_bf16_f32 v107, v112, v113
	global_store_dwordx4 v[116:117], v[104:107], off
	global_load_dwordx4 v[104:107], v[126:127], off offset:256 nt
	v_lshl_add_u64 v[108:109], v[146:147], 0, 32
	v_lshlrev_b64 v[110:111], 12, v[108:109]
	v_lshl_add_u64 v[110:111], s[8:9], 0, v[110:111]
	v_lshl_add_u64 v[110:111], v[110:111], 0, v[144:145]
	s_waitcnt vmcnt(0)
	v_lshlrev_b32_e32 v112, 16, v104
	v_and_b32_e32 v113, 0xffff0000, v104
	v_lshlrev_b32_e32 v104, 16, v105
	v_and_b32_e32 v105, 0xffff0000, v105
	v_lshlrev_b32_e32 v114, 16, v106
	v_and_b32_e32 v115, 0xffff0000, v106
	v_lshlrev_b32_e32 v106, 16, v107
	v_and_b32_e32 v107, 0xffff0000, v107
	v_pk_mul_f32 v[102:103], v[102:103], v[104:105]
	v_pk_mul_f32 v[100:101], v[100:101], v[112:113]
	v_pk_mul_f32 v[104:105], v[98:99], v[106:107]
	v_pk_mul_f32 v[98:99], v[96:97], v[114:115]
	v_cvt_pk_bf16_f32 v96, v100, v101
	v_cvt_pk_bf16_f32 v97, v102, v103
	v_cvt_pk_bf16_f32 v98, v98, v99
	v_cvt_pk_bf16_f32 v99, v104, v105
	global_store_dwordx4 v[116:117], v[96:99], off offset:256
	global_load_dwordx4 v[96:99], v[110:111], off nt
	v_lshlrev_b64 v[100:101], 11, v[108:109]
	v_lshl_add_u64 v[100:101], s[86:87], 0, v[100:101]
	v_lshl_add_u64 v[100:101], v[100:101], 0, v[144:145]
	s_waitcnt vmcnt(0)
	v_lshlrev_b32_e32 v102, 16, v96
	v_and_b32_e32 v103, 0xffff0000, v96
	v_lshlrev_b32_e32 v96, 16, v97
	v_and_b32_e32 v97, 0xffff0000, v97
	v_lshlrev_b32_e32 v104, 16, v98
	v_and_b32_e32 v105, 0xffff0000, v98
	v_lshlrev_b32_e32 v98, 16, v99
	v_and_b32_e32 v99, 0xffff0000, v99
	v_pk_mul_f32 v[94:95], v[94:95], v[96:97]
	v_pk_mul_f32 v[92:93], v[92:93], v[102:103]
	v_pk_mul_f32 v[96:97], v[90:91], v[98:99]
	v_pk_mul_f32 v[90:91], v[88:89], v[104:105]
	v_cvt_pk_bf16_f32 v88, v92, v93
	v_cvt_pk_bf16_f32 v89, v94, v95
	v_cvt_pk_bf16_f32 v90, v90, v91
	v_cvt_pk_bf16_f32 v91, v96, v97
	global_store_dwordx4 v[100:101], v[88:91], off
	global_load_dwordx4 v[88:91], v[110:111], off offset:256 nt
	v_lshl_add_u64 v[92:93], v[146:147], 0, 48
	v_lshlrev_b64 v[94:95], 12, v[92:93]
	v_lshl_add_u64 v[94:95], s[8:9], 0, v[94:95]
	v_lshl_add_u64 v[94:95], v[94:95], 0, v[144:145]
	s_waitcnt vmcnt(0)
	v_lshlrev_b32_e32 v96, 16, v88
	v_and_b32_e32 v97, 0xffff0000, v88
	v_lshlrev_b32_e32 v88, 16, v89
	v_and_b32_e32 v89, 0xffff0000, v89
	v_lshlrev_b32_e32 v98, 16, v90
	v_and_b32_e32 v99, 0xffff0000, v90
	v_lshlrev_b32_e32 v90, 16, v91
	v_and_b32_e32 v91, 0xffff0000, v91
	v_pk_mul_f32 v[86:87], v[86:87], v[88:89]
	v_pk_mul_f32 v[84:85], v[84:85], v[96:97]
	v_pk_mul_f32 v[88:89], v[82:83], v[90:91]
	v_pk_mul_f32 v[82:83], v[80:81], v[98:99]
	v_cvt_pk_bf16_f32 v80, v84, v85
	v_cvt_pk_bf16_f32 v81, v86, v87
	v_cvt_pk_bf16_f32 v82, v82, v83
	v_cvt_pk_bf16_f32 v83, v88, v89
	global_store_dwordx4 v[100:101], v[80:83], off offset:256
	global_load_dwordx4 v[80:83], v[94:95], off nt
	v_lshlrev_b64 v[84:85], 11, v[92:93]
	v_lshl_add_u64 v[84:85], s[86:87], 0, v[84:85]
	v_lshl_add_u64 v[84:85], v[84:85], 0, v[144:145]
	s_waitcnt vmcnt(0)
	v_lshlrev_b32_e32 v86, 16, v80
	v_and_b32_e32 v87, 0xffff0000, v80
	v_lshlrev_b32_e32 v80, 16, v81
	v_and_b32_e32 v81, 0xffff0000, v81
	v_lshlrev_b32_e32 v88, 16, v82
	v_and_b32_e32 v89, 0xffff0000, v82
	v_lshlrev_b32_e32 v82, 16, v83
	v_and_b32_e32 v83, 0xffff0000, v83
	v_pk_mul_f32 v[78:79], v[78:79], v[80:81]
	v_pk_mul_f32 v[76:77], v[76:77], v[86:87]
	v_pk_mul_f32 v[80:81], v[74:75], v[82:83]
	v_pk_mul_f32 v[74:75], v[72:73], v[88:89]
	v_cvt_pk_bf16_f32 v72, v76, v77
	v_cvt_pk_bf16_f32 v73, v78, v79
	v_cvt_pk_bf16_f32 v74, v74, v75
	v_cvt_pk_bf16_f32 v75, v80, v81
	global_store_dwordx4 v[84:85], v[72:75], off
	global_load_dwordx4 v[72:75], v[94:95], off offset:256 nt
	v_lshl_add_u64 v[76:77], v[146:147], 0, s[26:27]
	v_lshlrev_b64 v[78:79], 12, v[76:77]
	v_lshl_add_u64 v[78:79], s[8:9], 0, v[78:79]
	v_lshl_add_u64 v[78:79], v[78:79], 0, v[144:145]
	s_waitcnt vmcnt(0)
	v_lshlrev_b32_e32 v80, 16, v72
	v_and_b32_e32 v81, 0xffff0000, v72
	v_lshlrev_b32_e32 v72, 16, v73
	v_and_b32_e32 v73, 0xffff0000, v73
	v_lshlrev_b32_e32 v82, 16, v74
	v_and_b32_e32 v83, 0xffff0000, v74
	v_lshlrev_b32_e32 v74, 16, v75
	v_and_b32_e32 v75, 0xffff0000, v75
	v_pk_mul_f32 v[70:71], v[70:71], v[72:73]
	v_pk_mul_f32 v[68:69], v[68:69], v[80:81]
	v_pk_mul_f32 v[72:73], v[66:67], v[74:75]
	v_pk_mul_f32 v[66:67], v[64:65], v[82:83]
	v_cvt_pk_bf16_f32 v64, v68, v69
	v_cvt_pk_bf16_f32 v65, v70, v71
	v_cvt_pk_bf16_f32 v66, v66, v67
	v_cvt_pk_bf16_f32 v67, v72, v73
	global_store_dwordx4 v[84:85], v[64:67], off offset:256
	global_load_dwordx4 v[64:67], v[78:79], off nt
	v_lshlrev_b64 v[68:69], 11, v[76:77]
	v_lshl_add_u64 v[68:69], s[86:87], 0, v[68:69]
	v_lshl_add_u64 v[68:69], v[68:69], 0, v[144:145]
	s_waitcnt vmcnt(0)
	v_lshlrev_b32_e32 v70, 16, v64
	v_and_b32_e32 v71, 0xffff0000, v64
	v_lshlrev_b32_e32 v64, 16, v65
	v_and_b32_e32 v65, 0xffff0000, v65
	v_lshlrev_b32_e32 v72, 16, v66
	v_and_b32_e32 v73, 0xffff0000, v66
	v_lshlrev_b32_e32 v66, 16, v67
	v_and_b32_e32 v67, 0xffff0000, v67
	v_pk_mul_f32 v[62:63], v[62:63], v[64:65]
	v_pk_mul_f32 v[60:61], v[60:61], v[70:71]
	v_pk_mul_f32 v[64:65], v[58:59], v[66:67]
	v_pk_mul_f32 v[58:59], v[56:57], v[72:73]
	v_cvt_pk_bf16_f32 v56, v60, v61
	v_cvt_pk_bf16_f32 v57, v62, v63
	v_cvt_pk_bf16_f32 v58, v58, v59
	v_cvt_pk_bf16_f32 v59, v64, v65
	global_store_dwordx4 v[68:69], v[56:59], off
	global_load_dwordx4 v[56:59], v[78:79], off offset:256 nt
	v_lshl_add_u64 v[60:61], v[146:147], 0, s[46:47]
	v_lshlrev_b64 v[62:63], 12, v[60:61]
	v_lshl_add_u64 v[62:63], s[8:9], 0, v[62:63]
	v_lshl_add_u64 v[62:63], v[62:63], 0, v[144:145]
	s_mov_b64 s[46:47], 0xa0
	s_waitcnt vmcnt(0)
	v_lshlrev_b32_e32 v64, 16, v56
	v_and_b32_e32 v65, 0xffff0000, v56
	v_lshlrev_b32_e32 v56, 16, v57
	v_and_b32_e32 v57, 0xffff0000, v57
	v_lshlrev_b32_e32 v66, 16, v58
	v_and_b32_e32 v67, 0xffff0000, v58
	v_lshlrev_b32_e32 v58, 16, v59
	v_and_b32_e32 v59, 0xffff0000, v59
	v_pk_mul_f32 v[54:55], v[54:55], v[56:57]
	v_pk_mul_f32 v[52:53], v[52:53], v[64:65]
	v_pk_mul_f32 v[56:57], v[50:51], v[58:59]
	v_pk_mul_f32 v[50:51], v[48:49], v[66:67]
	v_cvt_pk_bf16_f32 v48, v52, v53
	v_cvt_pk_bf16_f32 v49, v54, v55
	v_cvt_pk_bf16_f32 v50, v50, v51
	v_cvt_pk_bf16_f32 v51, v56, v57
	global_store_dwordx4 v[68:69], v[48:51], off offset:256
	global_load_dwordx4 v[48:51], v[62:63], off nt
	v_lshlrev_b64 v[52:53], 11, v[60:61]
	v_lshl_add_u64 v[52:53], s[86:87], 0, v[52:53]
	v_lshl_add_u64 v[52:53], v[52:53], 0, v[144:145]
	s_waitcnt vmcnt(0)
	v_lshlrev_b32_e32 v54, 16, v48
	v_and_b32_e32 v55, 0xffff0000, v48
	v_lshlrev_b32_e32 v48, 16, v49
	v_and_b32_e32 v49, 0xffff0000, v49
	v_lshlrev_b32_e32 v56, 16, v50
	v_and_b32_e32 v57, 0xffff0000, v50
	v_lshlrev_b32_e32 v50, 16, v51
	v_and_b32_e32 v51, 0xffff0000, v51
	v_pk_mul_f32 v[46:47], v[46:47], v[48:49]
	v_pk_mul_f32 v[44:45], v[44:45], v[54:55]
	v_pk_mul_f32 v[48:49], v[42:43], v[50:51]
	v_pk_mul_f32 v[42:43], v[40:41], v[56:57]
	v_cvt_pk_bf16_f32 v40, v44, v45
	v_cvt_pk_bf16_f32 v41, v46, v47
	v_cvt_pk_bf16_f32 v42, v42, v43
	v_cvt_pk_bf16_f32 v43, v48, v49
	global_store_dwordx4 v[52:53], v[40:43], off
	global_load_dwordx4 v[40:43], v[62:63], off offset:256 nt
	v_lshl_add_u64 v[44:45], v[146:147], 0, s[46:47]
	v_lshlrev_b64 v[46:47], 12, v[44:45]
	v_lshl_add_u64 v[46:47], s[8:9], 0, v[46:47]
	v_lshl_add_u64 v[46:47], v[46:47], 0, v[144:145]
	s_mov_b64 s[46:47], 0xb0
	s_waitcnt vmcnt(0)
	v_lshlrev_b32_e32 v48, 16, v40
	v_and_b32_e32 v49, 0xffff0000, v40
	v_lshlrev_b32_e32 v40, 16, v41
	v_and_b32_e32 v41, 0xffff0000, v41
	v_lshlrev_b32_e32 v50, 16, v42
	v_and_b32_e32 v51, 0xffff0000, v42
	v_lshlrev_b32_e32 v42, 16, v43
	v_and_b32_e32 v43, 0xffff0000, v43
	v_pk_mul_f32 v[38:39], v[38:39], v[40:41]
	v_pk_mul_f32 v[36:37], v[36:37], v[48:49]
	v_pk_mul_f32 v[40:41], v[34:35], v[42:43]
	v_pk_mul_f32 v[34:35], v[32:33], v[50:51]
	v_cvt_pk_bf16_f32 v32, v36, v37
	v_cvt_pk_bf16_f32 v33, v38, v39
	v_cvt_pk_bf16_f32 v34, v34, v35
	v_cvt_pk_bf16_f32 v35, v40, v41
	global_store_dwordx4 v[52:53], v[32:35], off offset:256
	global_load_dwordx4 v[32:35], v[46:47], off nt
	v_lshlrev_b64 v[36:37], 11, v[44:45]
	v_lshl_add_u64 v[36:37], s[86:87], 0, v[36:37]
	v_lshl_add_u64 v[36:37], v[36:37], 0, v[144:145]
	s_waitcnt vmcnt(0)
	v_lshlrev_b32_e32 v38, 16, v32
	v_and_b32_e32 v39, 0xffff0000, v32
	v_lshlrev_b32_e32 v32, 16, v33
	v_and_b32_e32 v33, 0xffff0000, v33
	v_lshlrev_b32_e32 v40, 16, v34
	v_and_b32_e32 v41, 0xffff0000, v34
	v_lshlrev_b32_e32 v34, 16, v35
	v_and_b32_e32 v35, 0xffff0000, v35
	v_pk_mul_f32 v[30:31], v[30:31], v[32:33]
	v_pk_mul_f32 v[28:29], v[28:29], v[38:39]
	v_pk_mul_f32 v[32:33], v[26:27], v[34:35]
	v_pk_mul_f32 v[26:27], v[24:25], v[40:41]
	v_cvt_pk_bf16_f32 v24, v28, v29
	v_cvt_pk_bf16_f32 v25, v30, v31
	v_cvt_pk_bf16_f32 v26, v26, v27
	v_cvt_pk_bf16_f32 v27, v32, v33
	global_store_dwordx4 v[36:37], v[24:27], off
	global_load_dwordx4 v[24:27], v[46:47], off offset:256 nt
	v_lshl_add_u64 v[28:29], v[146:147], 0, s[46:47]
	v_lshlrev_b64 v[30:31], 12, v[28:29]
	v_lshl_add_u64 v[30:31], s[8:9], 0, v[30:31]
	v_lshl_add_u64 v[30:31], v[30:31], 0, v[144:145]
	s_waitcnt vmcnt(0)
	v_lshlrev_b32_e32 v32, 16, v24
	v_and_b32_e32 v33, 0xffff0000, v24
	v_lshlrev_b32_e32 v24, 16, v25
	v_and_b32_e32 v25, 0xffff0000, v25
	v_lshlrev_b32_e32 v34, 16, v26
	v_and_b32_e32 v35, 0xffff0000, v26
	v_lshlrev_b32_e32 v26, 16, v27
	v_and_b32_e32 v27, 0xffff0000, v27
	v_pk_mul_f32 v[22:23], v[22:23], v[24:25]
	v_pk_mul_f32 v[20:21], v[20:21], v[32:33]
	v_pk_mul_f32 v[24:25], v[18:19], v[26:27]
	v_pk_mul_f32 v[18:19], v[16:17], v[34:35]
	v_cvt_pk_bf16_f32 v16, v20, v21
	v_cvt_pk_bf16_f32 v17, v22, v23
	v_cvt_pk_bf16_f32 v18, v18, v19
	v_cvt_pk_bf16_f32 v19, v24, v25
	global_store_dwordx4 v[36:37], v[16:19], off offset:256
	global_load_dwordx4 v[16:19], v[30:31], off nt
	v_lshlrev_b64 v[20:21], 11, v[28:29]
	v_lshl_add_u64 v[20:21], s[86:87], 0, v[20:21]
	v_lshl_add_u64 v[20:21], v[20:21], 0, v[144:145]
	s_waitcnt vmcnt(0)
	v_lshlrev_b32_e32 v22, 16, v16
	v_and_b32_e32 v23, 0xffff0000, v16
	v_lshlrev_b32_e32 v16, 16, v17
	v_and_b32_e32 v17, 0xffff0000, v17
	v_lshlrev_b32_e32 v24, 16, v18
	v_and_b32_e32 v25, 0xffff0000, v18
	v_lshlrev_b32_e32 v18, 16, v19
	v_and_b32_e32 v19, 0xffff0000, v19
	v_pk_mul_f32 v[14:15], v[14:15], v[16:17]
	v_pk_mul_f32 v[12:13], v[12:13], v[22:23]
	v_pk_mul_f32 v[16:17], v[10:11], v[18:19]
	v_pk_mul_f32 v[10:11], v[8:9], v[24:25]
	v_cvt_pk_bf16_f32 v8, v12, v13
	v_cvt_pk_bf16_f32 v9, v14, v15
	v_cvt_pk_bf16_f32 v10, v10, v11
	v_cvt_pk_bf16_f32 v11, v16, v17
	global_store_dwordx4 v[20:21], v[8:11], off
	global_load_dwordx4 v[8:11], v[30:31], off offset:256 nt
	s_waitcnt vmcnt(0)
	v_lshlrev_b32_e32 v12, 16, v8
	v_and_b32_e32 v13, 0xffff0000, v8
	v_lshlrev_b32_e32 v8, 16, v9
	v_and_b32_e32 v9, 0xffff0000, v9
	v_lshlrev_b32_e32 v14, 16, v10
	v_and_b32_e32 v15, 0xffff0000, v10
	v_lshlrev_b32_e32 v10, 16, v11
	v_and_b32_e32 v11, 0xffff0000, v11
	v_pk_mul_f32 v[6:7], v[6:7], v[8:9]
	v_pk_mul_f32 v[4:5], v[4:5], v[12:13]
	v_pk_mul_f32 v[8:9], v[2:3], v[10:11]
	v_pk_mul_f32 v[2:3], v[0:1], v[14:15]
	v_cvt_pk_bf16_f32 v0, v4, v5
	v_cvt_pk_bf16_f32 v1, v6, v7
	v_cvt_pk_bf16_f32 v2, v2, v3
	v_cvt_pk_bf16_f32 v3, v8, v9
	global_store_dwordx4 v[20:21], v[0:3], off offset:256
	s_cbranch_vccnz .LBB0_1471
	s_andn2_b64 vcc, exec, s[24:25]
	s_cbranch_vccnz .LBB0_1470
	s_barrier
	s_branch .LBB0_1470

.LBB0_1516:
	s_ashr_i32 s47, s46, 31
	s_lshl_b64 s[46:47], s[46:47], 8
	v_mov_b32_e32 v144, v148
	v_mov_b32_e32 v169, v149
	s_add_u32 s46, s46, s88
	s_addc_u32 s47, s47, s69
	v_ashrrev_i32_e32 v145, 31, v144
	v_lshl_add_u64 v[146:147], s[46:47], 0, v[144:145]
	s_lshl_b32 s46, s77, 8
	s_or_b32 s46, s46, s89
	v_lshl_add_u32 v144, v169, 3, s46
	v_lshlrev_b64 v[170:171], 12, v[146:147]
	v_ashrrev_i32_e32 v145, 31, v144
	v_lshl_add_u64 v[170:171], s[8:9], 0, v[170:171]
	v_lshlrev_b64 v[144:145], 1, v[144:145]
	v_lshlrev_b64 v[174:175], 11, v[146:147]
	v_lshl_add_u64 v[182:183], v[170:171], 0, v[144:145]
	v_lshl_add_u64 v[174:175], s[86:87], 0, v[174:175]
	global_load_dwordx4 v[170:173], v[182:183], off offset:2048 nt
	v_lshl_add_u64 v[184:185], v[174:175], 0, v[144:145]
	global_load_dwordx4 v[174:177], v[184:185], off nt
	global_load_dwordx4 v[178:181], v[184:185], off offset:256 nt
	s_mov_b64 s[46:47], 0x90
	s_and_b64 vcc, exec, s[6:7]
	s_mov_b64 s[6:7], -1
	s_waitcnt vmcnt(0)
	v_lshlrev_b32_e32 v186, 16, v170
	v_and_b32_e32 v187, 0xffff0000, v170
	v_lshlrev_b32_e32 v170, 16, v171
	v_and_b32_e32 v171, 0xffff0000, v171
	v_lshlrev_b32_e32 v188, 16, v172
	v_and_b32_e32 v189, 0xffff0000, v172
	v_lshlrev_b32_e32 v172, 16, v173
	v_and_b32_e32 v173, 0xffff0000, v173
	v_lshlrev_b32_e32 v190, 16, v174
	v_and_b32_e32 v191, 0xffff0000, v174
	v_lshlrev_b32_e32 v174, 16, v175
	v_and_b32_e32 v175, 0xffff0000, v175
	v_lshlrev_b32_e32 v192, 16, v176
	v_and_b32_e32 v193, 0xffff0000, v176
	v_lshlrev_b32_e32 v176, 16, v177
	v_and_b32_e32 v177, 0xffff0000, v177
	v_pk_fma_f32 v[126:127], v[126:127], v[170:171], v[174:175]
	v_pk_fma_f32 v[124:125], v[124:125], v[186:187], v[190:191]
	v_pk_fma_f32 v[170:171], v[122:123], v[172:173], v[176:177]
	v_pk_fma_f32 v[122:123], v[120:121], v[188:189], v[192:193]
	v_cvt_pk_bf16_f32 v120, v124, v125
	v_cvt_pk_bf16_f32 v121, v126, v127
	v_cvt_pk_bf16_f32 v122, v122, v123
	v_cvt_pk_bf16_f32 v123, v170, v171
	global_store_dwordx4 v[184:185], v[120:123], off
	global_load_dwordx4 v[120:123], v[182:183], off offset:2304 nt
	v_lshl_add_u64 v[124:125], v[146:147], 0, 16
	v_lshlrev_b64 v[126:127], 12, v[124:125]
	v_lshlrev_b64 v[124:125], 11, v[124:125]
	v_lshlrev_b32_e32 v174, 16, v178
	v_and_b32_e32 v175, 0xffff0000, v178
	v_lshlrev_b32_e32 v176, 16, v179
	v_and_b32_e32 v177, 0xffff0000, v179
	v_lshlrev_b32_e32 v178, 16, v180
	v_and_b32_e32 v179, 0xffff0000, v180
	v_lshlrev_b32_e32 v180, 16, v181
	v_and_b32_e32 v181, 0xffff0000, v181
	v_lshl_add_u64 v[124:125], s[86:87], 0, v[124:125]
	v_lshl_add_u64 v[126:127], s[8:9], 0, v[126:127]
	v_lshl_add_u64 v[172:173], v[124:125], 0, v[144:145]
	v_lshl_add_u64 v[170:171], v[126:127], 0, v[144:145]
	global_load_dwordx4 v[124:127], v[172:173], off nt
	s_waitcnt vmcnt(0)
	v_lshlrev_b32_e32 v182, 16, v120
	v_and_b32_e32 v183, 0xffff0000, v120
	v_lshlrev_b32_e32 v120, 16, v121
	v_and_b32_e32 v121, 0xffff0000, v121
	v_lshlrev_b32_e32 v186, 16, v122
	v_and_b32_e32 v187, 0xffff0000, v122
	v_lshlrev_b32_e32 v122, 16, v123
	v_and_b32_e32 v123, 0xffff0000, v123
	v_pk_fma_f32 v[118:119], v[118:119], v[120:121], v[176:177]
	v_pk_fma_f32 v[116:117], v[116:117], v[182:183], v[174:175]
	v_pk_fma_f32 v[120:121], v[114:115], v[122:123], v[180:181]
	v_pk_fma_f32 v[114:115], v[112:113], v[186:187], v[178:179]
	v_cvt_pk_bf16_f32 v112, v116, v117
	v_cvt_pk_bf16_f32 v113, v118, v119
	v_cvt_pk_bf16_f32 v114, v114, v115
	v_cvt_pk_bf16_f32 v115, v120, v121
	global_store_dwordx4 v[184:185], v[112:115], off offset:256
	global_load_dwordx4 v[112:115], v[170:171], off offset:2048 nt
	s_nop 0
	global_load_dwordx4 v[116:119], v[172:173], off offset:256 nt
	v_lshlrev_b32_e32 v120, 16, v124
	v_and_b32_e32 v121, 0xffff0000, v124
	v_lshlrev_b32_e32 v122, 16, v125
	v_and_b32_e32 v123, 0xffff0000, v125
	v_lshlrev_b32_e32 v124, 16, v126
	v_and_b32_e32 v125, 0xffff0000, v126
	v_lshlrev_b32_e32 v126, 16, v127
	v_and_b32_e32 v127, 0xffff0000, v127
	s_waitcnt vmcnt(0)
	v_lshlrev_b32_e32 v174, 16, v112
	v_and_b32_e32 v175, 0xffff0000, v112
	v_lshlrev_b32_e32 v112, 16, v113
	v_and_b32_e32 v113, 0xffff0000, v113
	v_lshlrev_b32_e32 v176, 16, v114
	v_and_b32_e32 v177, 0xffff0000, v114
	v_lshlrev_b32_e32 v114, 16, v115
	v_and_b32_e32 v115, 0xffff0000, v115
	v_pk_fma_f32 v[110:111], v[110:111], v[112:113], v[122:123]
	v_pk_fma_f32 v[108:109], v[108:109], v[174:175], v[120:121]
	v_pk_fma_f32 v[112:113], v[106:107], v[114:115], v[126:127]
	v_pk_fma_f32 v[106:107], v[104:105], v[176:177], v[124:125]
	v_cvt_pk_bf16_f32 v104, v108, v109
	v_cvt_pk_bf16_f32 v105, v110, v111
	v_cvt_pk_bf16_f32 v106, v106, v107
	v_cvt_pk_bf16_f32 v107, v112, v113
	global_store_dwordx4 v[172:173], v[104:107], off
	global_load_dwordx4 v[104:107], v[170:171], off offset:2304 nt
	v_lshl_add_u64 v[108:109], v[146:147], 0, 32
	v_lshlrev_b64 v[110:111], 12, v[108:109]
	v_lshlrev_b64 v[108:109], 11, v[108:109]
	v_lshlrev_b32_e32 v120, 16, v116
	v_and_b32_e32 v121, 0xffff0000, v116
	v_lshlrev_b32_e32 v116, 16, v117
	v_and_b32_e32 v117, 0xffff0000, v117
	v_lshlrev_b32_e32 v122, 16, v118
	v_and_b32_e32 v123, 0xffff0000, v118
	v_lshlrev_b32_e32 v118, 16, v119
	v_and_b32_e32 v119, 0xffff0000, v119
	v_lshl_add_u64 v[108:109], s[86:87], 0, v[108:109]
	v_lshl_add_u64 v[110:111], s[8:9], 0, v[110:111]
	v_lshl_add_u64 v[114:115], v[108:109], 0, v[144:145]
	v_lshl_add_u64 v[112:113], v[110:111], 0, v[144:145]
	global_load_dwordx4 v[108:111], v[114:115], off nt
	s_waitcnt vmcnt(0)
	v_lshlrev_b32_e32 v124, 16, v104
	v_and_b32_e32 v125, 0xffff0000, v104
	v_lshlrev_b32_e32 v104, 16, v105
	v_and_b32_e32 v105, 0xffff0000, v105
	v_lshlrev_b32_e32 v126, 16, v106
	v_and_b32_e32 v127, 0xffff0000, v106
	v_lshlrev_b32_e32 v106, 16, v107
	v_and_b32_e32 v107, 0xffff0000, v107
	v_pk_fma_f32 v[102:103], v[102:103], v[104:105], v[116:117]
	v_pk_fma_f32 v[100:101], v[100:101], v[124:125], v[120:121]
	v_pk_fma_f32 v[104:105], v[98:99], v[106:107], v[118:119]
	v_pk_fma_f32 v[98:99], v[96:97], v[126:127], v[122:123]
	v_cvt_pk_bf16_f32 v96, v100, v101
	v_cvt_pk_bf16_f32 v97, v102, v103
	v_cvt_pk_bf16_f32 v98, v98, v99
	v_cvt_pk_bf16_f32 v99, v104, v105
	global_store_dwordx4 v[172:173], v[96:99], off offset:256
	global_load_dwordx4 v[96:99], v[112:113], off offset:2048 nt
	s_nop 0
	global_load_dwordx4 v[100:103], v[114:115], off offset:256 nt
	v_lshlrev_b32_e32 v104, 16, v108
	v_and_b32_e32 v105, 0xffff0000, v108
	v_lshlrev_b32_e32 v106, 16, v109
	v_and_b32_e32 v107, 0xffff0000, v109
	v_lshlrev_b32_e32 v108, 16, v110
	v_and_b32_e32 v109, 0xffff0000, v110
	v_lshlrev_b32_e32 v110, 16, v111
	v_and_b32_e32 v111, 0xffff0000, v111
	s_waitcnt vmcnt(0)
	v_lshlrev_b32_e32 v116, 16, v96
	v_and_b32_e32 v117, 0xffff0000, v96
	v_lshlrev_b32_e32 v96, 16, v97
	v_and_b32_e32 v97, 0xffff0000, v97
	v_lshlrev_b32_e32 v118, 16, v98
	v_and_b32_e32 v119, 0xffff0000, v98
	v_lshlrev_b32_e32 v98, 16, v99
	v_and_b32_e32 v99, 0xffff0000, v99
	v_pk_fma_f32 v[94:95], v[94:95], v[96:97], v[106:107]
	v_pk_fma_f32 v[92:93], v[92:93], v[116:117], v[104:105]
	v_pk_fma_f32 v[96:97], v[90:91], v[98:99], v[110:111]
	v_pk_fma_f32 v[90:91], v[88:89], v[118:119], v[108:109]
	v_cvt_pk_bf16_f32 v88, v92, v93
	v_cvt_pk_bf16_f32 v89, v94, v95
	v_cvt_pk_bf16_f32 v90, v90, v91
	v_cvt_pk_bf16_f32 v91, v96, v97
	global_store_dwordx4 v[114:115], v[88:91], off
	global_load_dwordx4 v[88:91], v[112:113], off offset:2304 nt
	v_lshl_add_u64 v[92:93], v[146:147], 0, 48
	v_lshlrev_b64 v[94:95], 12, v[92:93]
	v_lshlrev_b64 v[92:93], 11, v[92:93]
	v_lshlrev_b32_e32 v104, 16, v100
	v_and_b32_e32 v105, 0xffff0000, v100
	v_lshlrev_b32_e32 v100, 16, v101
	v_and_b32_e32 v101, 0xffff0000, v101
	v_lshlrev_b32_e32 v106, 16, v102
	v_and_b32_e32 v107, 0xffff0000, v102
	v_lshlrev_b32_e32 v102, 16, v103
	v_and_b32_e32 v103, 0xffff0000, v103
	v_lshl_add_u64 v[92:93], s[86:87], 0, v[92:93]
	v_lshl_add_u64 v[94:95], s[8:9], 0, v[94:95]
	v_lshl_add_u64 v[98:99], v[92:93], 0, v[144:145]
	v_lshl_add_u64 v[96:97], v[94:95], 0, v[144:145]
	global_load_dwordx4 v[92:95], v[98:99], off nt
	s_waitcnt vmcnt(0)
	v_lshlrev_b32_e32 v108, 16, v88
	v_and_b32_e32 v109, 0xffff0000, v88
	v_lshlrev_b32_e32 v88, 16, v89
	v_and_b32_e32 v89, 0xffff0000, v89
	v_lshlrev_b32_e32 v110, 16, v90
	v_and_b32_e32 v111, 0xffff0000, v90
	v_lshlrev_b32_e32 v90, 16, v91
	v_and_b32_e32 v91, 0xffff0000, v91
	v_pk_fma_f32 v[86:87], v[86:87], v[88:89], v[100:101]
	v_pk_fma_f32 v[84:85], v[84:85], v[108:109], v[104:105]
	v_pk_fma_f32 v[88:89], v[82:83], v[90:91], v[102:103]
	v_pk_fma_f32 v[82:83], v[80:81], v[110:111], v[106:107]
	v_cvt_pk_bf16_f32 v80, v84, v85
	v_cvt_pk_bf16_f32 v81, v86, v87
	v_cvt_pk_bf16_f32 v82, v82, v83
	v_cvt_pk_bf16_f32 v83, v88, v89
	global_store_dwordx4 v[114:115], v[80:83], off offset:256
	global_load_dwordx4 v[80:83], v[96:97], off offset:2048 nt
	s_nop 0
	global_load_dwordx4 v[84:87], v[98:99], off offset:256 nt
	v_lshlrev_b32_e32 v88, 16, v92
	v_and_b32_e32 v89, 0xffff0000, v92
	v_lshlrev_b32_e32 v90, 16, v93
	v_and_b32_e32 v91, 0xffff0000, v93
	v_lshlrev_b32_e32 v92, 16, v94
	v_and_b32_e32 v93, 0xffff0000, v94
	v_lshlrev_b32_e32 v94, 16, v95
	v_and_b32_e32 v95, 0xffff0000, v95
	s_waitcnt vmcnt(0)
	v_lshlrev_b32_e32 v100, 16, v80
	v_and_b32_e32 v101, 0xffff0000, v80
	v_lshlrev_b32_e32 v80, 16, v81
	v_and_b32_e32 v81, 0xffff0000, v81
	v_lshlrev_b32_e32 v102, 16, v82
	v_and_b32_e32 v103, 0xffff0000, v82
	v_lshlrev_b32_e32 v82, 16, v83
	v_and_b32_e32 v83, 0xffff0000, v83
	v_pk_fma_f32 v[78:79], v[78:79], v[80:81], v[90:91]
	v_pk_fma_f32 v[76:77], v[76:77], v[100:101], v[88:89]
	v_pk_fma_f32 v[80:81], v[74:75], v[82:83], v[94:95]
	v_pk_fma_f32 v[74:75], v[72:73], v[102:103], v[92:93]
	v_cvt_pk_bf16_f32 v72, v76, v77
	v_cvt_pk_bf16_f32 v73, v78, v79
	v_cvt_pk_bf16_f32 v74, v74, v75
	v_cvt_pk_bf16_f32 v75, v80, v81
	global_store_dwordx4 v[98:99], v[72:75], off
	global_load_dwordx4 v[72:75], v[96:97], off offset:2304 nt
	v_lshl_add_u64 v[76:77], v[146:147], 0, s[24:25]
	v_lshlrev_b64 v[78:79], 12, v[76:77]
	v_lshlrev_b64 v[76:77], 11, v[76:77]
	v_lshlrev_b32_e32 v88, 16, v84
	v_and_b32_e32 v89, 0xffff0000, v84
	v_lshlrev_b32_e32 v84, 16, v85
	v_and_b32_e32 v85, 0xffff0000, v85
	v_lshlrev_b32_e32 v90, 16, v86
	v_and_b32_e32 v91, 0xffff0000, v86
	v_lshlrev_b32_e32 v86, 16, v87
	v_and_b32_e32 v87, 0xffff0000, v87
	v_lshl_add_u64 v[76:77], s[86:87], 0, v[76:77]
	v_lshl_add_u64 v[78:79], s[8:9], 0, v[78:79]
	v_lshl_add_u64 v[82:83], v[76:77], 0, v[144:145]
	v_lshl_add_u64 v[80:81], v[78:79], 0, v[144:145]
	global_load_dwordx4 v[76:79], v[82:83], off nt
	s_waitcnt vmcnt(0)
	v_lshlrev_b32_e32 v92, 16, v72
	v_and_b32_e32 v93, 0xffff0000, v72
	v_lshlrev_b32_e32 v72, 16, v73
	v_and_b32_e32 v73, 0xffff0000, v73
	v_lshlrev_b32_e32 v94, 16, v74
	v_and_b32_e32 v95, 0xffff0000, v74
	v_lshlrev_b32_e32 v74, 16, v75
	v_and_b32_e32 v75, 0xffff0000, v75
	v_pk_fma_f32 v[70:71], v[70:71], v[72:73], v[84:85]
	v_pk_fma_f32 v[68:69], v[68:69], v[92:93], v[88:89]
	v_pk_fma_f32 v[72:73], v[66:67], v[74:75], v[86:87]
	v_pk_fma_f32 v[66:67], v[64:65], v[94:95], v[90:91]
	v_cvt_pk_bf16_f32 v64, v68, v69
	v_cvt_pk_bf16_f32 v65, v70, v71
	v_cvt_pk_bf16_f32 v66, v66, v67
	v_cvt_pk_bf16_f32 v67, v72, v73
	global_store_dwordx4 v[98:99], v[64:67], off offset:256
	global_load_dwordx4 v[64:67], v[80:81], off offset:2048 nt
	s_nop 0
	global_load_dwordx4 v[68:71], v[82:83], off offset:256 nt
	v_lshlrev_b32_e32 v72, 16, v76
	v_and_b32_e32 v73, 0xffff0000, v76
	v_lshlrev_b32_e32 v74, 16, v77
	v_and_b32_e32 v75, 0xffff0000, v77
	v_lshlrev_b32_e32 v76, 16, v78
	v_and_b32_e32 v77, 0xffff0000, v78
	v_lshlrev_b32_e32 v78, 16, v79
	v_and_b32_e32 v79, 0xffff0000, v79
	s_waitcnt vmcnt(0)
	v_lshlrev_b32_e32 v84, 16, v64
	v_and_b32_e32 v85, 0xffff0000, v64
	v_lshlrev_b32_e32 v64, 16, v65
	v_and_b32_e32 v65, 0xffff0000, v65
	v_lshlrev_b32_e32 v86, 16, v66
	v_and_b32_e32 v87, 0xffff0000, v66
	v_lshlrev_b32_e32 v66, 16, v67
	v_and_b32_e32 v67, 0xffff0000, v67
	v_pk_fma_f32 v[62:63], v[62:63], v[64:65], v[74:75]
	v_pk_fma_f32 v[60:61], v[60:61], v[84:85], v[72:73]
	v_pk_fma_f32 v[64:65], v[58:59], v[66:67], v[78:79]
	v_pk_fma_f32 v[58:59], v[56:57], v[86:87], v[76:77]
	v_cvt_pk_bf16_f32 v56, v60, v61
	v_cvt_pk_bf16_f32 v57, v62, v63
	v_cvt_pk_bf16_f32 v58, v58, v59
	v_cvt_pk_bf16_f32 v59, v64, v65
	global_store_dwordx4 v[82:83], v[56:59], off
	global_load_dwordx4 v[56:59], v[80:81], off offset:2304 nt
	v_lshl_add_u64 v[60:61], v[146:147], 0, s[46:47]
	v_lshlrev_b64 v[62:63], 12, v[60:61]
	v_lshlrev_b64 v[60:61], 11, v[60:61]
	v_lshlrev_b32_e32 v72, 16, v68
	v_and_b32_e32 v73, 0xffff0000, v68
	v_lshlrev_b32_e32 v68, 16, v69
	v_and_b32_e32 v69, 0xffff0000, v69
	v_lshlrev_b32_e32 v74, 16, v70
	v_and_b32_e32 v75, 0xffff0000, v70
	v_lshlrev_b32_e32 v70, 16, v71
	v_and_b32_e32 v71, 0xffff0000, v71
	v_lshl_add_u64 v[60:61], s[86:87], 0, v[60:61]
	v_lshl_add_u64 v[62:63], s[8:9], 0, v[62:63]
	v_lshl_add_u64 v[66:67], v[60:61], 0, v[144:145]
	v_lshl_add_u64 v[64:65], v[62:63], 0, v[144:145]
	global_load_dwordx4 v[60:63], v[66:67], off nt
	s_mov_b64 s[46:47], 0xa0
	s_waitcnt vmcnt(0)
	v_lshlrev_b32_e32 v76, 16, v56
	v_and_b32_e32 v77, 0xffff0000, v56
	v_lshlrev_b32_e32 v56, 16, v57
	v_and_b32_e32 v57, 0xffff0000, v57
	v_lshlrev_b32_e32 v78, 16, v58
	v_and_b32_e32 v79, 0xffff0000, v58
	v_lshlrev_b32_e32 v58, 16, v59
	v_and_b32_e32 v59, 0xffff0000, v59
	v_pk_fma_f32 v[54:55], v[54:55], v[56:57], v[68:69]
	v_pk_fma_f32 v[52:53], v[52:53], v[76:77], v[72:73]
	v_pk_fma_f32 v[56:57], v[50:51], v[58:59], v[70:71]
	v_pk_fma_f32 v[50:51], v[48:49], v[78:79], v[74:75]
	v_cvt_pk_bf16_f32 v48, v52, v53
	v_cvt_pk_bf16_f32 v49, v54, v55
	v_cvt_pk_bf16_f32 v50, v50, v51
	v_cvt_pk_bf16_f32 v51, v56, v57
	global_store_dwordx4 v[82:83], v[48:51], off offset:256
	global_load_dwordx4 v[48:51], v[64:65], off offset:2048 nt
	s_nop 0
	global_load_dwordx4 v[52:55], v[66:67], off offset:256 nt
	v_lshlrev_b32_e32 v56, 16, v60
	v_and_b32_e32 v57, 0xffff0000, v60
	v_lshlrev_b32_e32 v58, 16, v61
	v_and_b32_e32 v59, 0xffff0000, v61
	v_lshlrev_b32_e32 v60, 16, v62
	v_and_b32_e32 v61, 0xffff0000, v62
	v_lshlrev_b32_e32 v62, 16, v63
	v_and_b32_e32 v63, 0xffff0000, v63
	s_waitcnt vmcnt(0)
	v_lshlrev_b32_e32 v68, 16, v48
	v_and_b32_e32 v69, 0xffff0000, v48
	v_lshlrev_b32_e32 v48, 16, v49
	v_and_b32_e32 v49, 0xffff0000, v49
	v_lshlrev_b32_e32 v70, 16, v50
	v_and_b32_e32 v71, 0xffff0000, v50
	v_lshlrev_b32_e32 v50, 16, v51
	v_and_b32_e32 v51, 0xffff0000, v51
	v_pk_fma_f32 v[46:47], v[46:47], v[48:49], v[58:59]
	v_pk_fma_f32 v[44:45], v[44:45], v[68:69], v[56:57]
	v_pk_fma_f32 v[48:49], v[42:43], v[50:51], v[62:63]
	v_pk_fma_f32 v[42:43], v[40:41], v[70:71], v[60:61]
	v_cvt_pk_bf16_f32 v40, v44, v45
	v_cvt_pk_bf16_f32 v41, v46, v47
	v_cvt_pk_bf16_f32 v42, v42, v43
	v_cvt_pk_bf16_f32 v43, v48, v49
	global_store_dwordx4 v[66:67], v[40:43], off
	global_load_dwordx4 v[40:43], v[64:65], off offset:2304 nt
	v_lshl_add_u64 v[44:45], v[146:147], 0, s[46:47]
	v_lshlrev_b64 v[46:47], 12, v[44:45]
	v_lshlrev_b64 v[44:45], 11, v[44:45]
	v_lshlrev_b32_e32 v56, 16, v52
	v_and_b32_e32 v57, 0xffff0000, v52
	v_lshlrev_b32_e32 v52, 16, v53
	v_and_b32_e32 v53, 0xffff0000, v53
	v_lshlrev_b32_e32 v58, 16, v54
	v_and_b32_e32 v59, 0xffff0000, v54
	v_lshlrev_b32_e32 v54, 16, v55
	v_and_b32_e32 v55, 0xffff0000, v55
	v_lshl_add_u64 v[44:45], s[86:87], 0, v[44:45]
	v_lshl_add_u64 v[46:47], s[8:9], 0, v[46:47]
	v_lshl_add_u64 v[50:51], v[44:45], 0, v[144:145]
	v_lshl_add_u64 v[48:49], v[46:47], 0, v[144:145]
	global_load_dwordx4 v[44:47], v[50:51], off nt
	s_waitcnt vmcnt(0)
	v_lshlrev_b32_e32 v60, 16, v40
	v_and_b32_e32 v61, 0xffff0000, v40
	v_lshlrev_b32_e32 v40, 16, v41
	v_and_b32_e32 v41, 0xffff0000, v41
	v_lshlrev_b32_e32 v62, 16, v42
	v_and_b32_e32 v63, 0xffff0000, v42
	v_lshlrev_b32_e32 v42, 16, v43
	v_and_b32_e32 v43, 0xffff0000, v43
	v_pk_fma_f32 v[38:39], v[38:39], v[40:41], v[52:53]
	v_pk_fma_f32 v[36:37], v[36:37], v[60:61], v[56:57]
	v_pk_fma_f32 v[40:41], v[34:35], v[42:43], v[54:55]
	v_pk_fma_f32 v[34:35], v[32:33], v[62:63], v[58:59]
	v_cvt_pk_bf16_f32 v32, v36, v37
	v_cvt_pk_bf16_f32 v33, v38, v39
	v_cvt_pk_bf16_f32 v34, v34, v35
	v_cvt_pk_bf16_f32 v35, v40, v41
	global_store_dwordx4 v[66:67], v[32:35], off offset:256
	global_load_dwordx4 v[32:35], v[48:49], off offset:2048 nt
	s_nop 0
	global_load_dwordx4 v[36:39], v[50:51], off offset:256 nt
	v_lshlrev_b32_e32 v40, 16, v44
	v_and_b32_e32 v41, 0xffff0000, v44
	v_lshlrev_b32_e32 v42, 16, v45
	v_and_b32_e32 v43, 0xffff0000, v45
	v_lshlrev_b32_e32 v44, 16, v46
	v_and_b32_e32 v45, 0xffff0000, v46
	v_lshlrev_b32_e32 v46, 16, v47
	v_and_b32_e32 v47, 0xffff0000, v47
	s_waitcnt vmcnt(0)
	v_lshlrev_b32_e32 v52, 16, v32
	v_and_b32_e32 v53, 0xffff0000, v32
	v_lshlrev_b32_e32 v32, 16, v33
	v_and_b32_e32 v33, 0xffff0000, v33
	v_lshlrev_b32_e32 v54, 16, v34
	v_and_b32_e32 v55, 0xffff0000, v34
	v_lshlrev_b32_e32 v34, 16, v35
	v_and_b32_e32 v35, 0xffff0000, v35
	v_pk_fma_f32 v[30:31], v[30:31], v[32:33], v[42:43]
	v_pk_fma_f32 v[28:29], v[28:29], v[52:53], v[40:41]
	v_pk_fma_f32 v[32:33], v[26:27], v[34:35], v[46:47]
	v_pk_fma_f32 v[26:27], v[24:25], v[54:55], v[44:45]
	v_cvt_pk_bf16_f32 v24, v28, v29
	v_cvt_pk_bf16_f32 v25, v30, v31
	v_cvt_pk_bf16_f32 v26, v26, v27
	v_cvt_pk_bf16_f32 v27, v32, v33
	global_store_dwordx4 v[50:51], v[24:27], off
	global_load_dwordx4 v[24:27], v[48:49], off offset:2304 nt
	v_lshl_add_u64 v[28:29], v[146:147], 0, s[36:37]
	v_lshlrev_b64 v[30:31], 12, v[28:29]
	v_lshlrev_b64 v[28:29], 11, v[28:29]
	v_lshlrev_b32_e32 v40, 16, v36
	v_and_b32_e32 v41, 0xffff0000, v36
	v_lshlrev_b32_e32 v36, 16, v37
	v_and_b32_e32 v37, 0xffff0000, v37
	v_lshlrev_b32_e32 v42, 16, v38
	v_and_b32_e32 v43, 0xffff0000, v38
	v_lshlrev_b32_e32 v38, 16, v39
	v_and_b32_e32 v39, 0xffff0000, v39
	v_lshl_add_u64 v[28:29], s[86:87], 0, v[28:29]
	v_lshl_add_u64 v[30:31], s[8:9], 0, v[30:31]
	v_lshl_add_u64 v[34:35], v[28:29], 0, v[144:145]
	v_lshl_add_u64 v[32:33], v[30:31], 0, v[144:145]
	global_load_dwordx4 v[28:31], v[34:35], off nt
	s_waitcnt vmcnt(0)
	v_lshlrev_b32_e32 v44, 16, v24
	v_and_b32_e32 v45, 0xffff0000, v24
	v_lshlrev_b32_e32 v24, 16, v25
	v_and_b32_e32 v25, 0xffff0000, v25
	v_lshlrev_b32_e32 v46, 16, v26
	v_and_b32_e32 v47, 0xffff0000, v26
	v_lshlrev_b32_e32 v26, 16, v27
	v_and_b32_e32 v27, 0xffff0000, v27
	v_pk_fma_f32 v[22:23], v[22:23], v[24:25], v[36:37]
	v_pk_fma_f32 v[20:21], v[20:21], v[44:45], v[40:41]
	v_pk_fma_f32 v[24:25], v[18:19], v[26:27], v[38:39]
	v_pk_fma_f32 v[18:19], v[16:17], v[46:47], v[42:43]
	v_cvt_pk_bf16_f32 v16, v20, v21
	v_cvt_pk_bf16_f32 v17, v22, v23
	v_cvt_pk_bf16_f32 v18, v18, v19
	v_cvt_pk_bf16_f32 v19, v24, v25
	global_store_dwordx4 v[50:51], v[16:19], off offset:256
	global_load_dwordx4 v[16:19], v[32:33], off offset:2048 nt
	s_nop 0
	global_load_dwordx4 v[20:23], v[34:35], off offset:256 nt
	v_lshlrev_b32_e32 v24, 16, v28
	v_and_b32_e32 v25, 0xffff0000, v28
	v_lshlrev_b32_e32 v26, 16, v29
	v_and_b32_e32 v27, 0xffff0000, v29
	v_lshlrev_b32_e32 v28, 16, v30
	v_and_b32_e32 v29, 0xffff0000, v30
	v_lshlrev_b32_e32 v30, 16, v31
	v_and_b32_e32 v31, 0xffff0000, v31
	s_waitcnt vmcnt(0)
	v_lshlrev_b32_e32 v36, 16, v16
	v_and_b32_e32 v37, 0xffff0000, v16
	v_lshlrev_b32_e32 v16, 16, v17
	v_and_b32_e32 v17, 0xffff0000, v17
	v_lshlrev_b32_e32 v38, 16, v18
	v_and_b32_e32 v39, 0xffff0000, v18
	v_lshlrev_b32_e32 v18, 16, v19
	v_and_b32_e32 v19, 0xffff0000, v19
	v_pk_fma_f32 v[14:15], v[14:15], v[16:17], v[26:27]
	v_pk_fma_f32 v[12:13], v[12:13], v[36:37], v[24:25]
	v_pk_fma_f32 v[16:17], v[10:11], v[18:19], v[30:31]
	v_pk_fma_f32 v[10:11], v[8:9], v[38:39], v[28:29]
	v_cvt_pk_bf16_f32 v8, v12, v13
	v_cvt_pk_bf16_f32 v9, v14, v15
	v_cvt_pk_bf16_f32 v10, v10, v11
	v_cvt_pk_bf16_f32 v11, v16, v17
	global_store_dwordx4 v[34:35], v[8:11], off
	global_load_dwordx4 v[8:11], v[32:33], off offset:2304 nt
	v_lshlrev_b32_e32 v12, 16, v20
	v_and_b32_e32 v13, 0xffff0000, v20
	v_lshlrev_b32_e32 v14, 16, v21
	v_and_b32_e32 v15, 0xffff0000, v21
	v_lshlrev_b32_e32 v16, 16, v22
	v_and_b32_e32 v17, 0xffff0000, v22
	v_lshlrev_b32_e32 v18, 16, v23
	v_and_b32_e32 v19, 0xffff0000, v23
	s_waitcnt vmcnt(0)
	v_lshlrev_b32_e32 v20, 16, v8
	v_and_b32_e32 v21, 0xffff0000, v8
	v_lshlrev_b32_e32 v8, 16, v9
	v_and_b32_e32 v9, 0xffff0000, v9
	v_lshlrev_b32_e32 v22, 16, v10
	v_and_b32_e32 v23, 0xffff0000, v10
	v_lshlrev_b32_e32 v10, 16, v11
	v_and_b32_e32 v11, 0xffff0000, v11
	v_pk_fma_f32 v[6:7], v[6:7], v[8:9], v[14:15]
	v_pk_fma_f32 v[4:5], v[4:5], v[20:21], v[12:13]
	v_pk_fma_f32 v[8:9], v[2:3], v[10:11], v[18:19]
	v_pk_fma_f32 v[2:3], v[0:1], v[22:23], v[16:17]
	v_cvt_pk_bf16_f32 v0, v4, v5
	v_cvt_pk_bf16_f32 v1, v6, v7
	v_cvt_pk_bf16_f32 v2, v2, v3
	v_cvt_pk_bf16_f32 v3, v8, v9
	global_store_dwordx4 v[34:35], v[0:3], off offset:256
	s_cbranch_vccnz .LBB0_1500
	s_andn2_b64 vcc, exec, s[18:19]
	s_cbranch_vccnz .LBB0_1499
	s_barrier
	s_branch .LBB0_1499
